# store-only GEMM K-loops: first two vmcnt waits after an epilogue relaxed to vmcnt(24) (protected loads precede the 16 stores), flag in v244 lane 63
# baseline (speedup 1.0000x reference)
; template <class Epi, class Sched, bool ALIGN_EPI = false, bool SP2 = false>
; __device__ __forceinline__ void gemm_phase(PG8_LAS unsigned char* lds, const Gemm g, const Sched& S, const Epi& E, const int wave0) {
;     int tid_ = wave0 * 64 + xb_lane_pg8();
;     const int tid = tid_, wid = __builtin_amdgcn_readfirstlane(tid >> 6), lane = tid & 63, wr = wid >> 2, wc = wid & 3, fr = lane & 15, fq = lane >> 4;
;     const int K = g.K, nt = K / BK;
;     unsigned voffA[2], voffB[2];
; #pragma unroll
;     for (int i = 0; i < 2; ++i) { int R, C; stage_rc(tid * 16 + i * 8192, R, C); const int Rb = Epi::PERM ? ((R & ~31) + perm32(R & 31)) : R;
;         voffA[i] = (unsigned)(R * g.lda + C) * 2u; voffB[i] = (unsigned)(Rb * g.ldb + C) * 2u; }
;     const size_t kstep = (size_t)(BK * 2);
;     const size_t hstepA = (size_t)HALF * g.lda * 2, hstepB = (size_t)HALF * g.ldb * 2;
;     const size_t tstepA = 2 * hstepA, tstepB = 2 * hstepB;
;     const unsigned ldsw = (unsigned)wid * 1024u;
;     const int aoff = lds_byte(wr * 64 + fr, fq * 8), boff = lds_byte(wc * 32 + fr, fq * 8);
;     ...
;     Unit cur, nxt; int ui = 0;
;     if (!S.next(0, cur)) return;
;     f32x4 acc[2][2][4][2];
; #pragma unroll
;     for (int a = 0; a < 2; ++a)
; #pragma unroll
;         for (int b = 0; b < 2; ++b)
; #pragma unroll
;             for (int m = 0; m < 4; ++m)
; #pragma unroll
;                 for (int n = 0; n < 2; ++n) acc[a][b][m][n] = (f32x4){0.f, 0.f, 0.f, 0.f};
;     bf16x8 At[4][2], B0[2][2], B1[2][2];
;     const char* cA = (const char*)g.A + (size_t)cur.z * g.zsA + (size_t)cur.pm * tstepA + (size_t)cur.k0 * 2; const char* cB = (const char*)g.Bt + (size_t)cur.z * g.zsB + (size_t)cur.pn * tstepB + (size_t)cur.k0 * 2;
;     S.a_ready(cur);
;     if constexpr (SP2) {
;         PG8_STAGE(PG8_SB(0, 0), cB, voffB); PG8_STAGE(PG8_SB(0, 1), cB + hstepB, voffB); PG8_STAGE(PG8_SA(0, 0), cA, voffA); PG8_STAGE(PG8_SA(0, 1), cA + hstepA, voffA);
;         if (wr == 1) PG8_BAR;
;         PG8_WAIT_V(2); PG8_BAR;
;         PG8_STAGE(PG8_SB(1, 0), cB + kstep, voffB); PG8_STAGE(PG8_SA(1, 0), cA + kstep, voffA); PG8_STAGE(PG8_SB(1, 1), cB + hstepB + kstep, voffB);
;         PG8_WAIT_V(6); PG8_BAR;
;     } else {
;         PG8_STAGE(PG8_SB(0, 0), cB, voffB); PG8_STAGE(PG8_SA(0, 0), cA, voffA); PG8_STAGE(PG8_SB(0, 1), cB + hstepB, voffB); PG8_STAGE(PG8_SA(0, 1), cA + hstepA, voffA);
.LBB0_306:
	v_lshl_add_u64 v[8:9], s[16:17], 0, v[64:65]
	v_mov_b32_e32 v131, v65
	v_readlane_b32 s12, v245, 8
	s_lshl_b32 s2, s2, 5
	v_lshl_add_u64 v[10:11], s[16:17], 0, v[130:131]
	v_mov_b32_e32 v135, v65
	v_readlane_b32 s13, v245, 9
	s_and_b32 s8, s2, 0x60
	s_add_i32 m0, s23, 0x18000
	v_lshl_add_u64 v[8:9], v[8:9], 0, s[36:37]
	v_lshl_add_u64 v[12:13], s[12:13], 0, v[134:135]
	v_mov_b32_e32 v133, v65
	s_lshl_b32 s6, s1, 13
	s_lshl_b32 s7, s8, 7
	s_waitcnt vmcnt(2)
	s_barrier
	global_load_lds_dwordx4 v[8:9], off
	v_lshl_add_u64 v[8:9], v[10:11], 0, s[36:37]
	s_add_i32 m0, s23, 0x1a000
	s_add_i32 s27, s23, 0x8000
	s_add_i32 s28, s23, 0xa000
	v_lshl_add_u64 v[14:15], s[12:13], 0, v[132:133]
	global_load_lds_dwordx4 v[8:9], off
	v_lshl_add_u64 v[8:9], v[12:13], 0, s[36:37]
	s_mov_b32 m0, s27
	s_add_u32 s2, s16, 0x80080
	global_load_lds_dwordx4 v[8:9], off
	v_lshl_add_u64 v[8:9], v[14:15], 0, s[36:37]
	s_mov_b32 m0, s28
	s_addc_u32 s3, s17, 0
	global_load_lds_dwordx4 v[8:9], off
	s_add_i32 m0, s23, 0x1c000
	v_lshl_add_u64 v[8:9], s[2:3], 0, v[64:65]
	global_load_lds_dwordx4 v[8:9], off
	v_lshl_add_u64 v[8:9], s[2:3], 0, v[130:131]
	s_add_i32 m0, s23, 0x1e000
	v_and_b32_e32 v7, 15, v0
	global_load_lds_dwordx4 v[8:9], off
	v_lshrrev_b32_e32 v8, 1, v0
	v_and_b32_e32 v8, 24, v8
	v_lshlrev_b32_e32 v9, 1, v8
	v_lshlrev_b32_e32 v0, 2, v0
	v_lshl_or_b32 v140, s1, 6, v7
	v_lshl_or_b32 v7, v7, 6, v9
	v_and_b32_e32 v0, 32, v0
	v_bitop3_b32 v9, v7, s6, v0 bitop3:0xde
	v_bitop3_b32 v141, v7, s7, v0 bitop3:0xde
	v_lshlrev_b32_e32 v0, 15, v5
	v_and_b32_e32 v0, 0xffff0000, v0
	v_lshl_add_u32 v0, v4, 12, v0
	v_and_b32_e32 v4, 1, v5
	v_lshl_or_b32 v0, v4, 6, v0
	v_lshl_add_u32 v136, v6, 1, v0
	v_lshlrev_b32_e32 v0, 15, v1
	v_and_b32_e32 v0, 0xffff0000, v0
	v_writelane_b32 v244, 0, 63
	s_waitcnt vmcnt(6)
	s_cmpk_lt_u32 s0, 0x100
	v_lshl_add_u32 v0, v2, 12, v0
	v_and_b32_e32 v1, 1, v1
	v_readlane_b32 s0, v246, 63
	v_lshl_or_b32 v0, v1, 6, v0
	v_readlane_b32 s1, v245, 0
	s_cselect_b64 s[6:7], -1, 0
	v_or_b32_e32 v142, s8, v8
	v_mov_b32_e32 v137, v65
	v_lshl_add_u32 v138, v3, 1, v0
	v_mov_b32_e32 v139, v65
	s_mov_b32 s29, 0
	v_add_u32_e32 v143, 0, v9
	v_readlane_b32 s30, v245, 3
	s_mov_b32 s31, s0
	s_mov_b64 s[0:1], s[12:13]
	s_barrier
	s_branch .LBB0_309

;     __host__ __device__ bool next(int i, Unit& u) const { return tile((long)i * G + c, u); }
;     __host__ __device__ bool next(int i, Unit& u) const { if (!tile((long)(i / NZ) * G + c, u)) return false; u.z = i % NZ; return true; }
; #define PG8_STAGE(bufoff, gbase, voff) do { _Pragma("unroll") for (int _i = 0; _i < 2; ++_i) \
;         __builtin_amdgcn_global_load_lds((const unsigned*)((const char*)(gbase) + (voff)[_i]), (PG8_LAS unsigned*)(lds + (bufoff) + ldsw + _i * 8192), 16, 0, 0); } while (0)
; #define PG8_LDA(dst, b, h) do { _Pragma("unroll") for (int m = 0; m < 4; ++m) _Pragma("unroll") for (int k = 0; k < 2; ++k) dst[m][k] = *(const PG8_LAS bf16x8*)(lds + PG8_SA(b, h) + aoff + m * 2048 + k * 1024); } while (0)
; #define PG8_LDB(dst, b, h) do { _Pragma("unroll") for (int n = 0; n < 2; ++n) _Pragma("unroll") for (int k = 0; k < 2; ++k) dst[n][k] = *(const PG8_LAS bf16x8*)(lds + PG8_SB(b, h) + boff + n * 2048 + k * 1024); } while (0)
; #define PG8_SCHED __builtin_amdgcn_sched_barrier(0)
; template <class Epi, class Sched, bool ALIGN_EPI = false, bool SP2 = false>
; __device__ __forceinline__ void gemm_phase(PG8_LAS unsigned char* lds, const Gemm g, const Sched& S, const Epi& E, const int wave0) {
;     ...
;         const bool has_next = S.next(ui + 1, nxt);
;         const char* nA = has_next ? (const char*)g.A + (size_t)nxt.z * g.zsA + (size_t)nxt.pm * tstepA + (size_t)nxt.k0 * 2 : cA; const char* nB = has_next ? (const char*)g.Bt + (size_t)nxt.z * g.zsB + (size_t)nxt.pn * tstepB + (size_t)nxt.k0 * 2 : cB;
;         for (int t = 0; t < nt; t += 2) {
;             const bool last = (t == nt - 2);
;             const char* a1 = cA + (size_t)(t + 1) * kstep;
;             const char* a2 = last ? nA : cA + (size_t)(t + 2) * kstep; const char* b2 = last ? nB : cB + (size_t)(t + 2) * kstep;
;             const char* a3 = a2 + kstep; const char* b3 = b2 + kstep;
;             if (last && has_next) S.a_ready(nxt);
;             if constexpr (SP2) {
;             PG8_LDB(B0, 0, 0); PG8_LDB(B1, 0, 1); PG8_SCHED; PG8_LDA(At, 0, 0); PG8_STAGE(PG8_SA(1, 1), a1 + hstepA, voffA);
;     ...
;         for (int a = 0; a < 2; ++a)
; #pragma unroll
;             for (int b = 0; b < 2; ++b)
; #pragma unroll
;                 for (int m = 0; m < 4; ++m)
; #pragma unroll
;                     for (int n = 0; n < 2; ++n) acc[a][b][m][n] = (f32x4){0.f, 0.f, 0.f, 0.f};
.LBB0_315:
	s_ashr_i32 s11, s10, 31
	s_lshl_b64 s[12:13], s[10:11], 20
	v_readlane_b32 s14, v245, 1
	v_readlane_b32 s15, v245, 2
	s_add_u32 s12, s14, s12
	s_addc_u32 s13, s15, s13
	s_and_b64 s[14:15], s[2:3], exec
	s_cselect_b32 s11, s13, s1
	s_cselect_b32 s33, s12, s0
	s_ashr_i32 s9, s8, 31
	s_lshl_b64 s[14:15], s[8:9], 20
	s_add_u32 s14, s20, s14
	s_addc_u32 s15, s21, s15
	s_and_b64 s[18:19], s[2:3], exec
	s_cselect_b32 s9, s15, s17
	s_cselect_b32 s34, s14, s16
	s_add_u32 s0, s0, 0x80080
	s_addc_u32 s1, s1, 0
	s_add_u32 s35, s16, 0x100
	v_mov_b32_e32 v0, 0
	s_addc_u32 s36, s17, 0
	s_mov_b32 s37, -2
	v_mov_b32_e32 v1, v0
	v_mov_b64_e32 v[2:3], 0
	v_mov_b64_e32 v[4:5], 0
	v_mov_b64_e32 v[6:7], 0
	v_mov_b64_e32 v[8:9], 0
	v_mov_b64_e32 v[10:11], 0
	v_mov_b64_e32 v[12:13], 0
	v_mov_b64_e32 v[14:15], 0
	v_mov_b64_e32 v[24:25], 0
	v_mov_b64_e32 v[26:27], 0
	v_mov_b64_e32 v[28:29], 0
	v_mov_b64_e32 v[30:31], 0
	v_mov_b64_e32 v[40:41], 0
	v_mov_b64_e32 v[42:43], 0
	v_mov_b64_e32 v[44:45], 0
	v_mov_b64_e32 v[46:47], 0
	v_mov_b64_e32 v[16:17], 0
	v_mov_b64_e32 v[18:19], 0
	v_mov_b64_e32 v[20:21], 0
	v_mov_b64_e32 v[22:23], 0
	v_mov_b64_e32 v[32:33], 0
	v_mov_b64_e32 v[34:35], 0
	v_mov_b64_e32 v[36:37], 0
	v_mov_b64_e32 v[38:39], 0
	v_mov_b64_e32 v[48:49], 0
	v_mov_b64_e32 v[50:51], 0
	v_mov_b64_e32 v[52:53], 0
	v_mov_b64_e32 v[54:55], 0
	v_mov_b64_e32 v[56:57], 0
	v_mov_b64_e32 v[58:59], 0
	v_mov_b64_e32 v[60:61], 0
	v_mov_b64_e32 v[62:63], 0
	v_mov_b64_e32 v[66:67], 0
	v_mov_b64_e32 v[68:69], 0
	v_mov_b64_e32 v[70:71], 0
	v_mov_b64_e32 v[72:73], 0
	v_mov_b64_e32 v[74:75], 0
	v_mov_b64_e32 v[76:77], 0
	v_mov_b64_e32 v[78:79], 0
	v_mov_b64_e32 v[80:81], 0
	v_mov_b64_e32 v[90:91], 0
	v_mov_b64_e32 v[92:93], 0
	v_mov_b64_e32 v[94:95], 0
	v_mov_b64_e32 v[96:97], 0
	v_mov_b64_e32 v[106:107], 0
	v_mov_b64_e32 v[108:109], 0
	v_mov_b64_e32 v[110:111], 0
	v_mov_b64_e32 v[112:113], 0
	v_mov_b64_e32 v[82:83], 0
	v_mov_b64_e32 v[84:85], 0
	v_mov_b64_e32 v[86:87], 0
	v_mov_b64_e32 v[88:89], 0
	v_mov_b64_e32 v[98:99], 0
	v_mov_b64_e32 v[100:101], 0
	v_mov_b64_e32 v[102:103], 0
	v_mov_b64_e32 v[104:105], 0
	v_mov_b64_e32 v[114:115], 0
	v_mov_b64_e32 v[116:117], 0
	v_mov_b64_e32 v[118:119], 0
	v_mov_b64_e32 v[120:121], 0
	v_mov_b64_e32 v[122:123], 0
	v_mov_b64_e32 v[124:125], 0
	v_mov_b64_e32 v[126:127], 0
	v_mov_b64_e32 v[128:129], 0
	s_mov_b64 s[42:43], 0x80
	v_add_u32_e32 v252, 0x10000, v141
	v_add_u32_e32 v253, 0x14000, v141
	v_add_u32_e32 v254, 0x18000, v141
	v_add_u32_e32 v255, 0x1c000, v141
	v_readlane_b32 s42, v244, 63
	v_writelane_b32 v244, 0, 63
.LBB0_316:
	s_add_u32 s16, s0, 0xfff80080
	s_addc_u32 s17, s1, -1
	s_add_i32 s38, 0, 0x10000
	s_cmp_eq_u32 s37, 28
	s_cselect_b32 s19, s11, s17
	s_cselect_b32 s18, s33, s16
	s_cselect_b32 s17, s9, s36
	s_cselect_b32 s16, s34, s35
	s_add_i32 s40, 0, 0x14000
	ds_read_b128 v[144:147], v252
	ds_read_b128 v[148:151], v252 offset:1024
	ds_read_b128 v[152:155], v252 offset:2048
	ds_read_b128 v[156:159], v252 offset:3072
	ds_read_b128 v[178:181], v253
	ds_read_b128 v[182:185], v253 offset:1024
	ds_read_b128 v[186:189], v253 offset:2048
	ds_read_b128 v[190:193], v253 offset:3072
	s_add_i32 m0, s23, 0xc000
	ds_read_b128 v[194:197], v143
	ds_read_b128 v[208:211], v143 offset:1024
	ds_read_b128 v[212:215], v143 offset:2048
	ds_read_b128 v[216:219], v143 offset:3072
	ds_read_b128 v[220:223], v143 offset:4096
	ds_read_b128 v[224:227], v143 offset:5120
	ds_read_b128 v[228:231], v143 offset:6144
	ds_read_b128 v[232:235], v143 offset:7168
	global_load_lds_dwordx4 v136, s[0:1]
	s_add_i32 m0, s23, 0xe000
	s_nop 0
	global_load_lds_dwordx4 v138, s[0:1]
	s_cmp_eq_u32 s42, 1
	s_cbranch_scc0 .Ldf0_0n
	s_waitcnt vmcnt(24)
	s_branch .Ldf0_0d
; #define PG8_STAGE(bufoff, gbase, voff) do { _Pragma("unroll") for (int _i = 0; _i < 2; ++_i) \
;         __builtin_amdgcn_global_load_lds((const unsigned*)((const char*)(gbase) + (voff)[_i]), (PG8_LAS unsigned*)(lds + (bufoff) + ldsw + _i * 8192), 16, 0, 0); } while (0)
; #define PG8_LDA(dst, b, h) do { _Pragma("unroll") for (int m = 0; m < 4; ++m) _Pragma("unroll") for (int k = 0; k < 2; ++k) dst[m][k] = *(const PG8_LAS bf16x8*)(lds + PG8_SA(b, h) + aoff + m * 2048 + k * 1024); } while (0)
; #define PG8_MMA(ai, bj, At, Bt) do { __builtin_amdgcn_s_setprio(1); _Pragma("unroll") for (int m = 0; m < 4; ++m) _Pragma("unroll") for (int n = 0; n < 2; ++n) _Pragma("unroll") for (int k = 0; k < 2; ++k) \
;         acc[ai][bj][m][n] = __builtin_amdgcn_mfma_f32_16x16x32_bf16(Bt[n][k], At[m][k], acc[ai][bj][m][n], 0, 0, 0); __builtin_amdgcn_s_setprio(0); } while (0)
; #define PG8_WAIT_V(n) asm volatile("s_waitcnt vmcnt(" #n ")" ::: "memory")
; #define PG8_WAIT_L(n) asm volatile("s_waitcnt lgkmcnt(" #n ")" ::: "memory")
; #define PG8_BAR __builtin_amdgcn_s_barrier()
; #define PG8_SCHED __builtin_amdgcn_sched_barrier(0)
; template <class Epi, class Sched, bool ALIGN_EPI = false, bool SP2 = false>
; __device__ __forceinline__ void gemm_phase(PG8_LAS unsigned char* lds, const Gemm g, const Sched& S, const Epi& E, const int wave0) {
;     ...
;             PG8_WAIT_V(8); PG8_WAIT_L(0); PG8_BAR; PG8_MMA(0, 0, At, B0); PG8_MMA(0, 1, At, B1); PG8_BAR; PG8_SCHED;
;             PG8_LDA(At, 0, 1); PG8_STAGE(PG8_SB(0, 0), b2, voffB); PG8_STAGE(PG8_SB(0, 1), b2 + hstepB, voffB); PG8_STAGE(PG8_SA(0, 0), a2, voffA);
;             PG8_WAIT_V(8); PG8_WAIT_L(0); PG8_BAR; PG8_MMA(1, 0, At, B0); PG8_MMA(1, 1, At, B1); PG8_BAR; PG8_SCHED;
.Ldf0_0n:
	s_waitcnt vmcnt(8)
.Ldf0_0d:
	s_waitcnt lgkmcnt(0)
	s_barrier
	s_setprio 1
	s_waitcnt lgkmcnt(0)
	v_mfma_f32_16x16x32_bf16 v[126:129], v[144:147], v[194:197], v[126:129]
	v_mfma_f32_16x16x32_bf16 v[122:125], v[152:155], v[194:197], v[122:125]
	v_mfma_f32_16x16x32_bf16 v[118:121], v[144:147], v[212:215], v[118:121]
	v_mfma_f32_16x16x32_bf16 v[114:117], v[152:155], v[212:215], v[114:117]
	v_mfma_f32_16x16x32_bf16 v[102:105], v[144:147], v[220:223], v[102:105]
	v_mfma_f32_16x16x32_bf16 v[98:101], v[152:155], v[220:223], v[98:101]
	v_mfma_f32_16x16x32_bf16 v[86:89], v[144:147], v[228:231], v[86:89]
	v_mfma_f32_16x16x32_bf16 v[82:85], v[152:155], v[228:231], v[82:85]
	v_mfma_f32_16x16x32_bf16 v[126:129], v[148:151], v[208:211], v[126:129]
	v_mfma_f32_16x16x32_bf16 v[122:125], v[156:159], v[208:211], v[122:125]
	v_mfma_f32_16x16x32_bf16 v[118:121], v[148:151], v[216:219], v[118:121]
	v_mfma_f32_16x16x32_bf16 v[114:117], v[156:159], v[216:219], v[114:117]
	v_mfma_f32_16x16x32_bf16 v[102:105], v[148:151], v[224:227], v[102:105]
	v_mfma_f32_16x16x32_bf16 v[98:101], v[156:159], v[224:227], v[98:101]
	v_mfma_f32_16x16x32_bf16 v[86:89], v[148:151], v[232:235], v[86:89]
	v_mfma_f32_16x16x32_bf16 v[82:85], v[156:159], v[232:235], v[82:85]
	s_setprio 0
	s_setprio 1
	v_mfma_f32_16x16x32_bf16 v[110:113], v[178:181], v[194:197], v[110:113]
	v_mfma_f32_16x16x32_bf16 v[106:109], v[186:189], v[194:197], v[106:109]
	v_mfma_f32_16x16x32_bf16 v[94:97], v[178:181], v[212:215], v[94:97]
	v_mfma_f32_16x16x32_bf16 v[90:93], v[186:189], v[212:215], v[90:93]
	v_mfma_f32_16x16x32_bf16 v[78:81], v[178:181], v[220:223], v[78:81]
	v_mfma_f32_16x16x32_bf16 v[74:77], v[186:189], v[220:223], v[74:77]
	v_mfma_f32_16x16x32_bf16 v[70:73], v[178:181], v[228:231], v[70:73]
	v_mfma_f32_16x16x32_bf16 v[66:69], v[186:189], v[228:231], v[66:69]
	v_mfma_f32_16x16x32_bf16 v[110:113], v[182:185], v[208:211], v[110:113]
	v_mfma_f32_16x16x32_bf16 v[106:109], v[190:193], v[208:211], v[106:109]
	v_mfma_f32_16x16x32_bf16 v[94:97], v[182:185], v[216:219], v[94:97]
	v_mfma_f32_16x16x32_bf16 v[90:93], v[190:193], v[216:219], v[90:93]
	v_mfma_f32_16x16x32_bf16 v[78:81], v[182:185], v[224:227], v[78:81]
	v_mfma_f32_16x16x32_bf16 v[74:77], v[190:193], v[224:227], v[74:77]
	v_mfma_f32_16x16x32_bf16 v[70:73], v[182:185], v[232:235], v[70:73]
	v_mfma_f32_16x16x32_bf16 v[66:69], v[190:193], v[232:235], v[66:69]
	s_setprio 0
	s_barrier
	s_add_i32 s38, s38, s22
	s_mov_b32 m0, s38
	ds_read_b128 v[194:197], v143 offset:16384
	ds_read_b128 v[208:211], v143 offset:17408
	ds_read_b128 v[212:215], v143 offset:18432
	ds_read_b128 v[216:219], v143 offset:19456
	ds_read_b128 v[220:223], v143 offset:20480
	ds_read_b128 v[224:227], v143 offset:21504
	ds_read_b128 v[228:231], v143 offset:22528
	ds_read_b128 v[232:235], v143 offset:23552
	global_load_lds_dwordx4 v64, s[16:17]
	s_add_i32 m0, s38, 0x2000
	s_add_u32 s38, s16, 0x80000
	s_addc_u32 s39, s17, 0
	s_add_i32 s40, s40, s22
	global_load_lds_dwordx4 v130, s[16:17]
	s_mov_b32 m0, s40
	s_mov_b64 s[100:101], s[18:19]
	global_load_lds_dwordx4 v64, s[38:39]
	s_add_i32 m0, s40, 0x2000
	s_nop 0
	global_load_lds_dwordx4 v130, s[38:39]
	s_mov_b32 m0, s23
	s_nop 0
	global_load_lds_dwordx4 v134, s[18:19]
	s_mov_b32 m0, s24
	s_nop 0
	global_load_lds_dwordx4 v132, s[18:19]
	s_cmp_eq_u32 s42, 1
	s_cbranch_scc0 .Ldf0_1n
	s_waitcnt vmcnt(24)
	s_mov_b32 s42, 0
	s_branch .Ldf0_1d

; #define PG8_STAGE(bufoff, gbase, voff) do { _Pragma("unroll") for (int _i = 0; _i < 2; ++_i) \
;         __builtin_amdgcn_global_load_lds((const unsigned*)((const char*)(gbase) + (voff)[_i]), (PG8_LAS unsigned*)(lds + (bufoff) + ldsw + _i * 8192), 16, 0, 0); } while (0)
; #define PG8_LDA(dst, b, h) do { _Pragma("unroll") for (int m = 0; m < 4; ++m) _Pragma("unroll") for (int k = 0; k < 2; ++k) dst[m][k] = *(const PG8_LAS bf16x8*)(lds + PG8_SA(b, h) + aoff + m * 2048 + k * 1024); } while (0)
; #define PG8_LDB(dst, b, h) do { _Pragma("unroll") for (int n = 0; n < 2; ++n) _Pragma("unroll") for (int k = 0; k < 2; ++k) dst[n][k] = *(const PG8_LAS bf16x8*)(lds + PG8_SB(b, h) + boff + n * 2048 + k * 1024); } while (0)
; #define PG8_MMA(ai, bj, At, Bt) do { __builtin_amdgcn_s_setprio(1); _Pragma("unroll") for (int m = 0; m < 4; ++m) _Pragma("unroll") for (int n = 0; n < 2; ++n) _Pragma("unroll") for (int k = 0; k < 2; ++k) \
;         acc[ai][bj][m][n] = __builtin_amdgcn_mfma_f32_16x16x32_bf16(Bt[n][k], At[m][k], acc[ai][bj][m][n], 0, 0, 0); __builtin_amdgcn_s_setprio(0); } while (0)
; #define PG8_WAIT_V(n) asm volatile("s_waitcnt vmcnt(" #n ")" ::: "memory")
; #define PG8_WAIT_L(n) asm volatile("s_waitcnt lgkmcnt(" #n ")" ::: "memory")
; #define PG8_BAR __builtin_amdgcn_s_barrier()
; #define PG8_SCHED __builtin_amdgcn_sched_barrier(0)
; template <class Epi, class Sched, bool ALIGN_EPI = false, bool SP2 = false>
; __device__ __forceinline__ void gemm_phase(PG8_LAS unsigned char* lds, const Gemm g, const Sched& S, const Epi& E, const int wave0) {
;     ...
;             PG8_WAIT_V(8); PG8_WAIT_L(0); PG8_BAR; PG8_MMA(1, 0, At, B0); PG8_MMA(1, 1, At, B1); PG8_BAR; PG8_SCHED;
;             PG8_LDB(B0, 1, 0); PG8_LDB(B1, 1, 1); PG8_SCHED; PG8_LDA(At, 1, 0); PG8_STAGE(PG8_SA(0, 1), a2 + hstepA, voffA);
;             PG8_WAIT_V(8); PG8_WAIT_L(0); PG8_BAR; PG8_MMA(0, 0, At, B0); PG8_MMA(0, 1, At, B1); PG8_BAR; PG8_SCHED;
.Ldf0_1d:
	s_waitcnt lgkmcnt(0)
	s_barrier
	s_setprio 1
	s_waitcnt lgkmcnt(0)
	v_mfma_f32_16x16x32_bf16 v[60:63], v[144:147], v[194:197], v[60:63]
	v_mfma_f32_16x16x32_bf16 v[56:59], v[152:155], v[194:197], v[56:59]
	v_mfma_f32_16x16x32_bf16 v[52:55], v[144:147], v[212:215], v[52:55]
	v_mfma_f32_16x16x32_bf16 v[48:51], v[152:155], v[212:215], v[48:51]
	v_mfma_f32_16x16x32_bf16 v[36:39], v[144:147], v[220:223], v[36:39]
	v_mfma_f32_16x16x32_bf16 v[32:35], v[152:155], v[220:223], v[32:35]
	v_mfma_f32_16x16x32_bf16 v[20:23], v[144:147], v[228:231], v[20:23]
	v_mfma_f32_16x16x32_bf16 v[16:19], v[152:155], v[228:231], v[16:19]
	v_mfma_f32_16x16x32_bf16 v[60:63], v[148:151], v[208:211], v[60:63]
	v_mfma_f32_16x16x32_bf16 v[56:59], v[156:159], v[208:211], v[56:59]
	v_mfma_f32_16x16x32_bf16 v[52:55], v[148:151], v[216:219], v[52:55]
	v_mfma_f32_16x16x32_bf16 v[48:51], v[156:159], v[216:219], v[48:51]
	v_mfma_f32_16x16x32_bf16 v[36:39], v[148:151], v[224:227], v[36:39]
	v_mfma_f32_16x16x32_bf16 v[32:35], v[156:159], v[224:227], v[32:35]
	v_mfma_f32_16x16x32_bf16 v[20:23], v[148:151], v[232:235], v[20:23]
	v_mfma_f32_16x16x32_bf16 v[16:19], v[156:159], v[232:235], v[16:19]
	s_setprio 0
	s_setprio 1
	v_mfma_f32_16x16x32_bf16 v[44:47], v[178:181], v[194:197], v[44:47]
	v_mfma_f32_16x16x32_bf16 v[40:43], v[186:189], v[194:197], v[40:43]
	v_mfma_f32_16x16x32_bf16 v[28:31], v[178:181], v[212:215], v[28:31]
	v_mfma_f32_16x16x32_bf16 v[24:27], v[186:189], v[212:215], v[24:27]
	v_mfma_f32_16x16x32_bf16 v[12:15], v[178:181], v[220:223], v[12:15]
	v_mfma_f32_16x16x32_bf16 v[8:11], v[186:189], v[220:223], v[8:11]
	v_mfma_f32_16x16x32_bf16 v[4:7], v[178:181], v[228:231], v[4:7]
	v_mfma_f32_16x16x32_bf16 v[0:3], v[186:189], v[228:231], v[0:3]
	v_mfma_f32_16x16x32_bf16 v[44:47], v[182:185], v[208:211], v[44:47]
	v_mfma_f32_16x16x32_bf16 v[40:43], v[190:193], v[208:211], v[40:43]
	v_mfma_f32_16x16x32_bf16 v[28:31], v[182:185], v[216:219], v[28:31]
	v_mfma_f32_16x16x32_bf16 v[24:27], v[190:193], v[216:219], v[24:27]
	v_mfma_f32_16x16x32_bf16 v[12:15], v[182:185], v[224:227], v[12:15]
	v_mfma_f32_16x16x32_bf16 v[8:11], v[190:193], v[224:227], v[8:11]
	v_mfma_f32_16x16x32_bf16 v[4:7], v[182:185], v[232:235], v[4:7]
	v_mfma_f32_16x16x32_bf16 v[0:3], v[190:193], v[232:235], v[0:3]
	s_setprio 0
	s_barrier
	s_add_i32 s38, 0, 0x18000
	s_add_i32 s39, 0, 0x1c000
	ds_read_b128 v[144:147], v254
	ds_read_b128 v[148:151], v254 offset:1024
	ds_read_b128 v[152:155], v254 offset:2048
	ds_read_b128 v[156:159], v254 offset:3072
	ds_read_b128 v[178:181], v255
	ds_read_b128 v[182:185], v255 offset:1024
	ds_read_b128 v[186:189], v255 offset:2048
	ds_read_b128 v[190:193], v255 offset:3072
	s_add_u32 s18, s18, 0x80000
	s_addc_u32 s19, s19, 0
	s_mov_b32 m0, s25
	ds_read_b128 v[194:197], v143 offset:32768
	ds_read_b128 v[208:211], v143 offset:33792
	ds_read_b128 v[212:215], v143 offset:34816
	ds_read_b128 v[216:219], v143 offset:35840
	ds_read_b128 v[220:223], v143 offset:36864
	ds_read_b128 v[224:227], v143 offset:37888
	ds_read_b128 v[228:231], v143 offset:38912
	ds_read_b128 v[232:235], v143 offset:39936
	global_load_lds_dwordx4 v134, s[18:19]
	s_mov_b32 m0, s26
	s_nop 0
	global_load_lds_dwordx4 v132, s[18:19]
	s_waitcnt vmcnt(8)
	s_waitcnt lgkmcnt(0)
	s_barrier
	s_setprio 1
	s_waitcnt lgkmcnt(0)
	v_mfma_f32_16x16x32_bf16 v[126:129], v[144:147], v[194:197], v[126:129]
	v_mfma_f32_16x16x32_bf16 v[122:125], v[152:155], v[194:197], v[122:125]
	v_mfma_f32_16x16x32_bf16 v[118:121], v[144:147], v[212:215], v[118:121]
	v_mfma_f32_16x16x32_bf16 v[114:117], v[152:155], v[212:215], v[114:117]
	v_mfma_f32_16x16x32_bf16 v[102:105], v[144:147], v[220:223], v[102:105]
	v_mfma_f32_16x16x32_bf16 v[98:101], v[152:155], v[220:223], v[98:101]
	v_mfma_f32_16x16x32_bf16 v[86:89], v[144:147], v[228:231], v[86:89]
	v_mfma_f32_16x16x32_bf16 v[82:85], v[152:155], v[228:231], v[82:85]
	v_mfma_f32_16x16x32_bf16 v[126:129], v[148:151], v[208:211], v[126:129]
	v_mfma_f32_16x16x32_bf16 v[122:125], v[156:159], v[208:211], v[122:125]
	v_mfma_f32_16x16x32_bf16 v[118:121], v[148:151], v[216:219], v[118:121]
	v_mfma_f32_16x16x32_bf16 v[114:117], v[156:159], v[216:219], v[114:117]
	v_mfma_f32_16x16x32_bf16 v[102:105], v[148:151], v[224:227], v[102:105]
	v_mfma_f32_16x16x32_bf16 v[98:101], v[156:159], v[224:227], v[98:101]
	v_mfma_f32_16x16x32_bf16 v[86:89], v[148:151], v[232:235], v[86:89]
	v_mfma_f32_16x16x32_bf16 v[82:85], v[156:159], v[232:235], v[82:85]
	s_setprio 0
	s_setprio 1
	v_mfma_f32_16x16x32_bf16 v[110:113], v[178:181], v[194:197], v[110:113]
	v_mfma_f32_16x16x32_bf16 v[106:109], v[186:189], v[194:197], v[106:109]
	v_mfma_f32_16x16x32_bf16 v[94:97], v[178:181], v[212:215], v[94:97]
	v_mfma_f32_16x16x32_bf16 v[90:93], v[186:189], v[212:215], v[90:93]
	v_mfma_f32_16x16x32_bf16 v[78:81], v[178:181], v[220:223], v[78:81]
	v_mfma_f32_16x16x32_bf16 v[74:77], v[186:189], v[220:223], v[74:77]
	v_mfma_f32_16x16x32_bf16 v[70:73], v[178:181], v[228:231], v[70:73]
	v_mfma_f32_16x16x32_bf16 v[66:69], v[186:189], v[228:231], v[66:69]
	v_mfma_f32_16x16x32_bf16 v[110:113], v[182:185], v[208:211], v[110:113]
	v_mfma_f32_16x16x32_bf16 v[106:109], v[190:193], v[208:211], v[106:109]
	v_mfma_f32_16x16x32_bf16 v[94:97], v[182:185], v[216:219], v[94:97]
	v_mfma_f32_16x16x32_bf16 v[90:93], v[190:193], v[216:219], v[90:93]
	v_mfma_f32_16x16x32_bf16 v[78:81], v[182:185], v[224:227], v[78:81]
	v_mfma_f32_16x16x32_bf16 v[74:77], v[190:193], v[224:227], v[74:77]
	v_mfma_f32_16x16x32_bf16 v[70:73], v[182:185], v[232:235], v[70:73]
	v_mfma_f32_16x16x32_bf16 v[66:69], v[190:193], v[232:235], v[66:69]
	s_setprio 0
	s_barrier
; #define PG8_STAGE(bufoff, gbase, voff) do { _Pragma("unroll") for (int _i = 0; _i < 2; ++_i) \
;         __builtin_amdgcn_global_load_lds((const unsigned*)((const char*)(gbase) + (voff)[_i]), (PG8_LAS unsigned*)(lds + (bufoff) + ldsw + _i * 8192), 16, 0, 0); } while (0)
; #define PG8_LDA(dst, b, h) do { _Pragma("unroll") for (int m = 0; m < 4; ++m) _Pragma("unroll") for (int k = 0; k < 2; ++k) dst[m][k] = *(const PG8_LAS bf16x8*)(lds + PG8_SA(b, h) + aoff + m * 2048 + k * 1024); } while (0)
; #define PG8_MMA(ai, bj, At, Bt) do { __builtin_amdgcn_s_setprio(1); _Pragma("unroll") for (int m = 0; m < 4; ++m) _Pragma("unroll") for (int n = 0; n < 2; ++n) _Pragma("unroll") for (int k = 0; k < 2; ++k) \
;         acc[ai][bj][m][n] = __builtin_amdgcn_mfma_f32_16x16x32_bf16(Bt[n][k], At[m][k], acc[ai][bj][m][n], 0, 0, 0); __builtin_amdgcn_s_setprio(0); } while (0)
; #define PG8_WAIT_V(n) asm volatile("s_waitcnt vmcnt(" #n ")" ::: "memory")
; #define PG8_WAIT_L(n) asm volatile("s_waitcnt lgkmcnt(" #n ")" ::: "memory")
; #define PG8_BAR __builtin_amdgcn_s_barrier()
; #define PG8_SCHED __builtin_amdgcn_sched_barrier(0)
; template <class Epi, class Sched, bool ALIGN_EPI = false, bool SP2 = false>
; __device__ __forceinline__ void gemm_phase(PG8_LAS unsigned char* lds, const Gemm g, const Sched& S, const Epi& E, const int wave0) {
;     ...
;             PG8_WAIT_V(8); PG8_WAIT_L(0); PG8_BAR; PG8_MMA(0, 0, At, B0); PG8_MMA(0, 1, At, B1); PG8_BAR; PG8_SCHED;
;             PG8_LDA(At, 1, 1); PG8_STAGE(PG8_SB(1, 0), b3, voffB); PG8_STAGE(PG8_SB(1, 1), b3 + hstepB, voffB); PG8_STAGE(PG8_SA(1, 0), a3, voffA);
;             PG8_WAIT_V(8); PG8_WAIT_L(0); PG8_BAR; PG8_MMA(1, 0, At, B0); PG8_MMA(1, 1, At, B1); PG8_BAR; PG8_SCHED;
	s_add_i32 s18, s38, s22
	s_add_u32 s42, s16, 0x80
	s_addc_u32 s43, s17, 0
	s_mov_b32 m0, s18
	ds_read_b128 v[194:197], v143 offset:49152
	ds_read_b128 v[208:211], v143 offset:50176
	ds_read_b128 v[212:215], v143 offset:51200
	ds_read_b128 v[216:219], v143 offset:52224
	ds_read_b128 v[220:223], v143 offset:53248
	ds_read_b128 v[224:227], v143 offset:54272
	ds_read_b128 v[228:231], v143 offset:55296
	ds_read_b128 v[232:235], v143 offset:56320
	global_load_lds_dwordx4 v64, s[42:43]
	s_add_i32 m0, s18, 0x2000
	s_add_u32 s16, s16, 0x80080
	s_addc_u32 s17, s17, 0
	s_add_i32 s18, s39, s22
	global_load_lds_dwordx4 v130, s[42:43]
	s_mov_b32 m0, s18
	s_nop 0
	global_load_lds_dwordx4 v64, s[16:17]
	s_add_i32 m0, s18, 0x2000
	s_nop 0
	global_load_lds_dwordx4 v130, s[16:17]
	s_add_u32 s100, s100, 0x80
	s_addc_u32 s101, s101, 0
	s_mov_b32 m0, s27
	s_nop 0
	global_load_lds_dwordx4 v134, s[100:101]
	s_mov_b32 m0, s28
	s_nop 0
	global_load_lds_dwordx4 v132, s[100:101]
	s_waitcnt vmcnt(8)
	s_waitcnt lgkmcnt(0)
	s_barrier
	s_setprio 1
	s_waitcnt lgkmcnt(0)
	v_mfma_f32_16x16x32_bf16 v[60:63], v[144:147], v[194:197], v[60:63]
	v_mfma_f32_16x16x32_bf16 v[56:59], v[152:155], v[194:197], v[56:59]
	v_mfma_f32_16x16x32_bf16 v[52:55], v[144:147], v[212:215], v[52:55]
	v_mfma_f32_16x16x32_bf16 v[48:51], v[152:155], v[212:215], v[48:51]
	v_mfma_f32_16x16x32_bf16 v[36:39], v[144:147], v[220:223], v[36:39]
	v_mfma_f32_16x16x32_bf16 v[32:35], v[152:155], v[220:223], v[32:35]
	v_mfma_f32_16x16x32_bf16 v[20:23], v[144:147], v[228:231], v[20:23]
	v_mfma_f32_16x16x32_bf16 v[16:19], v[152:155], v[228:231], v[16:19]
	v_mfma_f32_16x16x32_bf16 v[60:63], v[148:151], v[208:211], v[60:63]
	v_mfma_f32_16x16x32_bf16 v[56:59], v[156:159], v[208:211], v[56:59]
	v_mfma_f32_16x16x32_bf16 v[52:55], v[148:151], v[216:219], v[52:55]
	v_mfma_f32_16x16x32_bf16 v[48:51], v[156:159], v[216:219], v[48:51]
	v_mfma_f32_16x16x32_bf16 v[36:39], v[148:151], v[224:227], v[36:39]
	v_mfma_f32_16x16x32_bf16 v[32:35], v[156:159], v[224:227], v[32:35]
	v_mfma_f32_16x16x32_bf16 v[20:23], v[148:151], v[232:235], v[20:23]
	v_mfma_f32_16x16x32_bf16 v[16:19], v[156:159], v[232:235], v[16:19]
	s_setprio 0
	s_setprio 1
	v_mfma_f32_16x16x32_bf16 v[44:47], v[178:181], v[194:197], v[44:47]
	v_mfma_f32_16x16x32_bf16 v[40:43], v[186:189], v[194:197], v[40:43]
	v_mfma_f32_16x16x32_bf16 v[28:31], v[178:181], v[212:215], v[28:31]
	v_mfma_f32_16x16x32_bf16 v[24:27], v[186:189], v[212:215], v[24:27]
	v_mfma_f32_16x16x32_bf16 v[12:15], v[178:181], v[220:223], v[12:15]
	v_mfma_f32_16x16x32_bf16 v[8:11], v[186:189], v[220:223], v[8:11]
	v_mfma_f32_16x16x32_bf16 v[4:7], v[178:181], v[228:231], v[4:7]
	v_mfma_f32_16x16x32_bf16 v[0:3], v[186:189], v[228:231], v[0:3]
	v_mfma_f32_16x16x32_bf16 v[44:47], v[182:185], v[208:211], v[44:47]
	v_mfma_f32_16x16x32_bf16 v[40:43], v[190:193], v[208:211], v[40:43]
	v_mfma_f32_16x16x32_bf16 v[28:31], v[182:185], v[216:219], v[28:31]
	v_mfma_f32_16x16x32_bf16 v[24:27], v[190:193], v[216:219], v[24:27]
	v_mfma_f32_16x16x32_bf16 v[12:15], v[182:185], v[224:227], v[12:15]
	v_mfma_f32_16x16x32_bf16 v[8:11], v[190:193], v[224:227], v[8:11]
	v_mfma_f32_16x16x32_bf16 v[4:7], v[182:185], v[232:235], v[4:7]
	v_mfma_f32_16x16x32_bf16 v[0:3], v[190:193], v[232:235], v[0:3]
	s_setprio 0
	s_barrier
	s_add_i32 s37, s37, 2
	s_add_u32 s0, s0, 0x100
	s_addc_u32 s1, s1, 0
	s_add_u32 s35, s35, 0x100
	s_addc_u32 s36, s36, 0
	s_cmp_gt_u32 s37, 29
	s_cbranch_scc0 .LBB0_316
	s_mov_b64 s[42:43], 0x80
	s_and_b64 vcc, exec, s[6:7]
	s_mov_b64 s[34:35], 0x45000
	s_cbranch_vccz .LBB0_319
	s_barrier
; __device__ __forceinline__ unsigned cvt_pk_bf16(float lo, float hi) { const f32x2_t v = {lo, hi}; const bf16x2_t b = __builtin_convertvector(v, bf16x2_t); return __builtin_bit_cast(unsigned, b); }
;     __device__ __forceinline__ void operator()(const f32x4 (&acc)[2][2][4][2], const Unit& u, int wr, int wc, int fr, int fq) const {
;         const int row0 = u.pm * BM + wr * 64 + fr; const int col0 = u.pn * BM + wc * 32 + 8 * fq;
; #pragma unroll
;         for (int ai = 0; ai < 2; ++ai)
; #pragma unroll
;             for (int m = 0; m < 4; ++m) { bf16_t* rowp = O + (size_t)u.zo * zsO + (size_t)(row0 + ai * HALF + m * 16) * ldc + col0;
; #pragma unroll
;                 for (int bj = 0; bj < 2; ++bj) { f32x4 v0 = acc[ai][bj][m][0], v1 = acc[ai][bj][m][1];
;                     if (ACT == 2) {
; #pragma unroll
;                         for (int j = 0; j < 4; ++j) { const float a = fmaxf(v0[j], 0.f), b = fmaxf(v1[j], 0.f); v0[j] = a * a; v1[j] = b * b; } }
;                     u32x4 w; w.x = cvt_pk_bf16(v0[0], v0[1]); w.y = cvt_pk_bf16(v0[2], v0[3]); w.z = cvt_pk_bf16(v1[0], v1[1]); w.w = cvt_pk_bf16(v1[2], v1[3]);
;                     *(u32x4*)(rowp + bj * HALF) = w; } }
;     }
.LBB0_319:
	v_lshl_or_b32 v144, s30, 8, v142
	v_lshl_add_u32 v150, s31, 8, v140
	v_ashrrev_i32_e32 v145, 31, v144
	v_mov_b64_e32 v[146:147], s[84:85]
	v_cvt_pk_bf16_f32 v70, v70, v71
	v_cvt_pk_bf16_f32 v71, v72, v73
	v_cvt_pk_bf16_f32 v72, v66, v67
	v_add_u32_e32 v66, 0x80, v150
	v_mad_i64_i32 v[148:149], s[0:1], v150, s91, v[146:147]
	v_lshlrev_b64 v[144:145], 1, v[144:145]
	v_cvt_pk_bf16_f32 v110, v110, v111
	v_cvt_pk_bf16_f32 v111, v112, v113
	v_cvt_pk_bf16_f32 v112, v106, v107
	v_or_b32_e32 v106, 16, v150
	v_mad_i64_i32 v[66:67], s[0:1], v66, s91, v[146:147]
	v_cvt_pk_bf16_f32 v44, v44, v45
	v_cvt_pk_bf16_f32 v45, v46, v47
	v_cvt_pk_bf16_f32 v46, v40, v41
	v_add_u32_e32 v40, 0x90, v150
	v_lshl_add_u64 v[148:149], v[148:149], 0, v[144:145]
	v_cvt_pk_bf16_f32 v113, v108, v109
	v_mad_i64_i32 v[106:107], s[0:1], v106, s91, v[146:147]
	v_cvt_pk_bf16_f32 v94, v94, v95
	v_cvt_pk_bf16_f32 v95, v96, v97
	v_cvt_pk_bf16_f32 v96, v90, v91
	v_or_b32_e32 v90, 32, v150
	v_lshl_add_u64 v[66:67], v[66:67], 0, v[144:145]
	v_cvt_pk_bf16_f32 v47, v42, v43
	v_mad_i64_i32 v[40:41], s[0:1], v40, s91, v[146:147]
	v_cvt_pk_bf16_f32 v28, v28, v29
	v_cvt_pk_bf16_f32 v29, v30, v31
	v_cvt_pk_bf16_f32 v30, v24, v25
	v_add_u32_e32 v24, 0xa0, v150
	global_store_dwordx4 v[148:149], v[110:113], off offset:256
	v_cvt_pk_bf16_f32 v97, v92, v93
	v_mad_i64_i32 v[90:91], s[0:1], v90, s91, v[146:147]
	v_lshl_add_u64 v[110:111], v[106:107], 0, v[144:145]
	v_cvt_pk_bf16_f32 v78, v78, v79
	v_cvt_pk_bf16_f32 v79, v80, v81
	v_cvt_pk_bf16_f32 v80, v74, v75
	v_or_b32_e32 v74, 48, v150
	global_store_dwordx4 v[66:67], v[44:47], off offset:256
	v_cvt_pk_bf16_f32 v31, v26, v27
	v_mad_i64_i32 v[24:25], s[0:1], v24, s91, v[146:147]
	v_lshl_add_u64 v[44:45], v[40:41], 0, v[144:145]
	v_cvt_pk_bf16_f32 v12, v12, v13
	v_cvt_pk_bf16_f32 v13, v14, v15
	v_cvt_pk_bf16_f32 v14, v8, v9
	v_add_u32_e32 v8, 0xb0, v150
	global_store_dwordx4 v[110:111], v[94:97], off offset:256
	v_cvt_pk_bf16_f32 v81, v76, v77
	v_mad_i64_i32 v[74:75], s[0:1], v74, s91, v[146:147]
	v_lshl_add_u64 v[94:95], v[90:91], 0, v[144:145]
	global_store_dwordx4 v[44:45], v[28:31], off offset:256
	v_cvt_pk_bf16_f32 v15, v10, v11
	v_mad_i64_i32 v[8:9], s[0:1], v8, s91, v[146:147]
	v_lshl_add_u64 v[28:29], v[24:25], 0, v[144:145]
	v_cvt_pk_bf16_f32 v126, v126, v127
	v_cvt_pk_bf16_f32 v127, v128, v129
	v_cvt_pk_bf16_f32 v128, v122, v123
	v_cvt_pk_bf16_f32 v129, v124, v125
	v_cvt_pk_bf16_f32 v106, v118, v119
	v_cvt_pk_bf16_f32 v107, v120, v121
	v_cvt_pk_bf16_f32 v108, v114, v115
	v_cvt_pk_bf16_f32 v109, v116, v117
	v_cvt_pk_bf16_f32 v90, v102, v103
	v_cvt_pk_bf16_f32 v91, v104, v105
	v_cvt_pk_bf16_f32 v92, v98, v99
	v_cvt_pk_bf16_f32 v93, v100, v101
	global_store_dwordx4 v[94:95], v[78:81], off offset:256
	v_cvt_pk_bf16_f32 v76, v82, v83
	v_cvt_pk_bf16_f32 v77, v84, v85
	v_lshl_add_u64 v[78:79], v[74:75], 0, v[144:145]
	v_cvt_pk_bf16_f32 v74, v86, v87
	v_cvt_pk_bf16_f32 v75, v88, v89
	v_cvt_pk_bf16_f32 v73, v68, v69
	v_cvt_pk_bf16_f32 v60, v60, v61
	v_cvt_pk_bf16_f32 v61, v62, v63
	v_cvt_pk_bf16_f32 v62, v56, v57
	v_cvt_pk_bf16_f32 v63, v58, v59
	v_cvt_pk_bf16_f32 v40, v52, v53
	v_cvt_pk_bf16_f32 v41, v54, v55
	v_cvt_pk_bf16_f32 v42, v48, v49
	v_cvt_pk_bf16_f32 v43, v50, v51
	v_cvt_pk_bf16_f32 v24, v36, v37
	v_cvt_pk_bf16_f32 v25, v38, v39
	v_cvt_pk_bf16_f32 v26, v32, v33
	v_cvt_pk_bf16_f32 v27, v34, v35
	global_store_dwordx4 v[28:29], v[12:15], off offset:256
	v_cvt_pk_bf16_f32 v10, v16, v17
	v_cvt_pk_bf16_f32 v11, v18, v19
	v_lshl_add_u64 v[12:13], v[8:9], 0, v[144:145]
	v_cvt_pk_bf16_f32 v8, v20, v21
	v_cvt_pk_bf16_f32 v9, v22, v23
	v_cvt_pk_bf16_f32 v4, v4, v5
	v_cvt_pk_bf16_f32 v5, v6, v7
	v_cvt_pk_bf16_f32 v6, v0, v1
	v_cvt_pk_bf16_f32 v7, v2, v3
	s_andn2_b64 vcc, exec, s[2:3]
	s_mov_b64 s[0:1], -1
	s_mov_b64 s[36:37], 0x80
	global_store_dwordx4 v[148:149], v[126:129], off
	global_store_dwordx4 v[110:111], v[106:109], off
	global_store_dwordx4 v[94:95], v[90:93], off
	global_store_dwordx4 v[78:79], v[74:77], off
	global_store_dwordx4 v[78:79], v[70:73], off offset:256
	global_store_dwordx4 v[66:67], v[60:63], off
	global_store_dwordx4 v[44:45], v[40:43], off
	global_store_dwordx4 v[28:29], v[24:27], off
	global_store_dwordx4 v[12:13], v[8:11], off
	global_store_dwordx4 v[12:13], v[4:7], off offset:256
	v_writelane_b32 v244, 1, 63
	s_cbranch_vccnz .LBB0_308
	s_andn2_b64 vcc, exec, s[4:5]
	s_cbranch_vccnz .LBB0_307
	s_barrier
	s_branch .LBB0_307

; template <class Epi, class Sched, bool ALIGN_EPI = false, bool SP2 = false>
; __device__ __forceinline__ void gemm_phase(PG8_LAS unsigned char* lds, const Gemm g, const Sched& S, const Epi& E, const int wave0) {
;     int tid_ = wave0 * 64 + xb_lane_pg8();
;     const int tid = tid_, wid = __builtin_amdgcn_readfirstlane(tid >> 6), lane = tid & 63, wr = wid >> 2, wc = wid & 3, fr = lane & 15, fq = lane >> 4;
;     const int K = g.K, nt = K / BK;
;     unsigned voffA[2], voffB[2];
; #pragma unroll
;     for (int i = 0; i < 2; ++i) { int R, C; stage_rc(tid * 16 + i * 8192, R, C); const int Rb = Epi::PERM ? ((R & ~31) + perm32(R & 31)) : R;
;         voffA[i] = (unsigned)(R * g.lda + C) * 2u; voffB[i] = (unsigned)(Rb * g.ldb + C) * 2u; }
;     const size_t kstep = (size_t)(BK * 2);
;     const size_t hstepA = (size_t)HALF * g.lda * 2, hstepB = (size_t)HALF * g.ldb * 2;
;     const size_t tstepA = 2 * hstepA, tstepB = 2 * hstepB;
;     const unsigned ldsw = (unsigned)wid * 1024u;
;     const int aoff = lds_byte(wr * 64 + fr, fq * 8), boff = lds_byte(wc * 32 + fr, fq * 8);
;     ...
;     Unit cur, nxt; int ui = 0;
;     if (!S.next(0, cur)) return;
;     f32x4 acc[2][2][4][2];
; #pragma unroll
;     for (int a = 0; a < 2; ++a)
; #pragma unroll
;         for (int b = 0; b < 2; ++b)
; #pragma unroll
;             for (int m = 0; m < 4; ++m)
; #pragma unroll
;                 for (int n = 0; n < 2; ++n) acc[a][b][m][n] = (f32x4){0.f, 0.f, 0.f, 0.f};
;     bf16x8 At[4][2], B0[2][2], B1[2][2];
;     const char* cA = (const char*)g.A + (size_t)cur.z * g.zsA + (size_t)cur.pm * tstepA + (size_t)cur.k0 * 2; const char* cB = (const char*)g.Bt + (size_t)cur.z * g.zsB + (size_t)cur.pn * tstepB + (size_t)cur.k0 * 2;
;     S.a_ready(cur);
;     if constexpr (SP2) {
;         PG8_STAGE(PG8_SB(0, 0), cB, voffB); PG8_STAGE(PG8_SB(0, 1), cB + hstepB, voffB); PG8_STAGE(PG8_SA(0, 0), cA, voffA); PG8_STAGE(PG8_SA(0, 1), cA + hstepA, voffA);
;         if (wr == 1) PG8_BAR;
;         PG8_WAIT_V(2); PG8_BAR;
;         PG8_STAGE(PG8_SB(1, 0), cB + kstep, voffB); PG8_STAGE(PG8_SA(1, 0), cA + kstep, voffA); PG8_STAGE(PG8_SB(1, 1), cB + hstepB + kstep, voffB);
;         PG8_WAIT_V(6); PG8_BAR;
;     } else {
;         PG8_STAGE(PG8_SB(0, 0), cB, voffB); PG8_STAGE(PG8_SA(0, 0), cA, voffA); PG8_STAGE(PG8_SB(0, 1), cB + hstepB, voffB); PG8_STAGE(PG8_SA(0, 1), cA + hstepA, voffA);
.LBB0_1331:
	v_lshrrev_b32_e32 v16, 1, v6
	v_and_b32_e32 v16, 24, v16
	v_and_b32_e32 v7, 15, v6
	v_lshlrev_b32_e32 v17, 1, v16
	v_lshlrev_b32_e32 v6, 2, v6
	s_lshl_b32 s1, s1, 5
	v_lshl_or_b32 v140, s2, 6, v7
	v_lshl_or_b32 v7, v7, 6, v17
	s_lshl_b32 s2, s2, 13
	v_and_b32_e32 v6, 32, v6
	s_and_b32 s1, s1, 0x60
	v_lshl_add_u64 v[8:9], s[16:17], 0, v[64:65]
	v_mov_b32_e32 v131, v65
	v_readlane_b32 s12, v246, 35
	v_bitop3_b32 v17, v7, s2, v6 bitop3:0xde
	s_lshl_b32 s2, s1, 7
	v_lshl_add_u64 v[10:11], s[16:17], 0, v[130:131]
	v_mov_b32_e32 v135, v65
	v_readlane_b32 s13, v246, 36
	v_bitop3_b32 v141, v7, s2, v6 bitop3:0xde
	s_add_i32 m0, s23, 0x18000
	v_lshl_add_u64 v[6:7], v[8:9], 0, s[36:37]
	v_lshl_add_u64 v[12:13], s[12:13], 0, v[134:135]
	v_mov_b32_e32 v133, v65
	s_waitcnt vmcnt(2)
	s_barrier
	global_load_lds_dwordx4 v[6:7], off
	v_lshl_add_u64 v[6:7], v[10:11], 0, s[36:37]
	s_add_i32 m0, s23, 0x1a000
	s_add_i32 s27, s23, 0x8000
	s_add_i32 s28, s23, 0xa000
	v_lshl_add_u64 v[14:15], s[12:13], 0, v[132:133]
	global_load_lds_dwordx4 v[6:7], off
	v_lshl_add_u64 v[6:7], v[12:13], 0, s[36:37]
	s_mov_b32 m0, s27
	s_add_u32 s2, s16, 0x80080
	global_load_lds_dwordx4 v[6:7], off
	v_lshl_add_u64 v[6:7], v[14:15], 0, s[36:37]
	s_mov_b32 m0, s28
	s_addc_u32 s3, s17, 0
	global_load_lds_dwordx4 v[6:7], off
	s_add_i32 m0, s23, 0x1c000
	v_lshl_add_u64 v[6:7], s[2:3], 0, v[64:65]
	global_load_lds_dwordx4 v[6:7], off
	v_lshl_add_u64 v[6:7], s[2:3], 0, v[130:131]
	s_add_i32 m0, s23, 0x1e000
	s_cmpk_lt_u32 s0, 0x100
	global_load_lds_dwordx4 v[6:7], off
	v_lshlrev_b32_e32 v6, 15, v4
	v_and_b32_e32 v6, 0xffff0000, v6
	v_lshl_add_u32 v3, v3, 12, v6
	v_and_b32_e32 v4, 1, v4
	v_lshl_or_b32 v3, v4, 6, v3
	v_lshl_add_u32 v136, v5, 1, v3
	v_lshlrev_b32_e32 v3, 15, v0
	v_and_b32_e32 v3, 0xffff0000, v3
	v_writelane_b32 v244, 0, 63
	s_waitcnt vmcnt(6)
	v_or_b32_e32 v142, s1, v16
	v_lshl_add_u32 v1, v1, 12, v3
	v_and_b32_e32 v0, 1, v0
	v_readlane_b32 s0, v246, 53
	v_lshl_or_b32 v0, v0, 6, v1
	v_readlane_b32 s1, v246, 54
	s_cselect_b64 s[6:7], -1, 0
	v_mov_b32_e32 v137, v65
	v_lshl_add_u32 v138, v2, 1, v0
	v_mov_b32_e32 v139, v65
	s_mov_b32 s29, 0
	v_add_u32_e32 v143, 0, v17
	v_readlane_b32 s30, v246, 30
	s_mov_b32 s31, s0
	s_mov_b64 s[0:1], s[12:13]
	s_barrier
	s_branch .LBB0_1334

;     __host__ __device__ bool next(int i, Unit& u) const { return tile((long)i * G + c, u); }
;     __host__ __device__ bool next(int i, Unit& u) const { if (!tile((long)(i / NZ) * G + c, u)) return false; u.z = i % NZ; return true; }
; #define PG8_STAGE(bufoff, gbase, voff) do { _Pragma("unroll") for (int _i = 0; _i < 2; ++_i) \
;         __builtin_amdgcn_global_load_lds((const unsigned*)((const char*)(gbase) + (voff)[_i]), (PG8_LAS unsigned*)(lds + (bufoff) + ldsw + _i * 8192), 16, 0, 0); } while (0)
; #define PG8_LDA(dst, b, h) do { _Pragma("unroll") for (int m = 0; m < 4; ++m) _Pragma("unroll") for (int k = 0; k < 2; ++k) dst[m][k] = *(const PG8_LAS bf16x8*)(lds + PG8_SA(b, h) + aoff + m * 2048 + k * 1024); } while (0)
; #define PG8_LDB(dst, b, h) do { _Pragma("unroll") for (int n = 0; n < 2; ++n) _Pragma("unroll") for (int k = 0; k < 2; ++k) dst[n][k] = *(const PG8_LAS bf16x8*)(lds + PG8_SB(b, h) + boff + n * 2048 + k * 1024); } while (0)
; #define PG8_SCHED __builtin_amdgcn_sched_barrier(0)
; template <class Epi, class Sched, bool ALIGN_EPI = false, bool SP2 = false>
; __device__ __forceinline__ void gemm_phase(PG8_LAS unsigned char* lds, const Gemm g, const Sched& S, const Epi& E, const int wave0) {
;     ...
;         const bool has_next = S.next(ui + 1, nxt);
;         const char* nA = has_next ? (const char*)g.A + (size_t)nxt.z * g.zsA + (size_t)nxt.pm * tstepA + (size_t)nxt.k0 * 2 : cA; const char* nB = has_next ? (const char*)g.Bt + (size_t)nxt.z * g.zsB + (size_t)nxt.pn * tstepB + (size_t)nxt.k0 * 2 : cB;
;         for (int t = 0; t < nt; t += 2) {
;             const bool last = (t == nt - 2);
;             const char* a1 = cA + (size_t)(t + 1) * kstep;
;             const char* a2 = last ? nA : cA + (size_t)(t + 2) * kstep; const char* b2 = last ? nB : cB + (size_t)(t + 2) * kstep;
;             const char* a3 = a2 + kstep; const char* b3 = b2 + kstep;
;             if (last && has_next) S.a_ready(nxt);
;             if constexpr (SP2) {
;             PG8_LDB(B0, 0, 0); PG8_LDB(B1, 0, 1); PG8_SCHED; PG8_LDA(At, 0, 0); PG8_STAGE(PG8_SA(1, 1), a1 + hstepA, voffA);
;     ...
;         for (int a = 0; a < 2; ++a)
; #pragma unroll
;             for (int b = 0; b < 2; ++b)
; #pragma unroll
;                 for (int m = 0; m < 4; ++m)
; #pragma unroll
;                     for (int n = 0; n < 2; ++n) acc[a][b][m][n] = (f32x4){0.f, 0.f, 0.f, 0.f};
.LBB0_1340:
	s_ashr_i32 s11, s10, 31
	s_lshl_b64 s[12:13], s[10:11], 20
	v_readlane_b32 s14, v246, 33
	v_readlane_b32 s15, v246, 34
	s_add_u32 s12, s14, s12
	s_addc_u32 s13, s15, s13
	s_and_b64 s[14:15], s[2:3], exec
	s_cselect_b32 s11, s13, s1
	s_cselect_b32 s33, s12, s0
	s_ashr_i32 s9, s8, 31
	s_lshl_b64 s[14:15], s[8:9], 20
	s_add_u32 s14, s20, s14
	s_addc_u32 s15, s21, s15
	s_and_b64 s[18:19], s[2:3], exec
	s_cselect_b32 s9, s15, s17
	s_cselect_b32 s34, s14, s16
	s_add_u32 s0, s0, 0x80080
	s_addc_u32 s1, s1, 0
	s_add_u32 s35, s16, 0x100
	v_mov_b32_e32 v0, 0
	s_addc_u32 s36, s17, 0
	s_mov_b32 s37, -2
	v_mov_b32_e32 v1, v0
	v_mov_b64_e32 v[2:3], 0
	v_mov_b64_e32 v[4:5], 0
	v_mov_b64_e32 v[6:7], 0
	v_mov_b64_e32 v[8:9], 0
	v_mov_b64_e32 v[10:11], 0
	v_mov_b64_e32 v[12:13], 0
	v_mov_b64_e32 v[14:15], 0
	v_mov_b64_e32 v[24:25], 0
	v_mov_b64_e32 v[26:27], 0
	v_mov_b64_e32 v[28:29], 0
	v_mov_b64_e32 v[30:31], 0
	v_mov_b64_e32 v[40:41], 0
	v_mov_b64_e32 v[42:43], 0
	v_mov_b64_e32 v[44:45], 0
	v_mov_b64_e32 v[46:47], 0
	v_mov_b64_e32 v[16:17], 0
	v_mov_b64_e32 v[18:19], 0
	v_mov_b64_e32 v[20:21], 0
	v_mov_b64_e32 v[22:23], 0
	v_mov_b64_e32 v[32:33], 0
	v_mov_b64_e32 v[34:35], 0
	v_mov_b64_e32 v[36:37], 0
	v_mov_b64_e32 v[38:39], 0
	v_mov_b64_e32 v[48:49], 0
	v_mov_b64_e32 v[50:51], 0
	v_mov_b64_e32 v[52:53], 0
	v_mov_b64_e32 v[54:55], 0
	v_mov_b64_e32 v[56:57], 0
	v_mov_b64_e32 v[58:59], 0
	v_mov_b64_e32 v[60:61], 0
	v_mov_b64_e32 v[62:63], 0
	v_mov_b64_e32 v[66:67], 0
	v_mov_b64_e32 v[68:69], 0
	v_mov_b64_e32 v[70:71], 0
	v_mov_b64_e32 v[72:73], 0
	v_mov_b64_e32 v[74:75], 0
	v_mov_b64_e32 v[76:77], 0
	v_mov_b64_e32 v[78:79], 0
	v_mov_b64_e32 v[80:81], 0
	v_mov_b64_e32 v[90:91], 0
	v_mov_b64_e32 v[92:93], 0
	v_mov_b64_e32 v[94:95], 0
	v_mov_b64_e32 v[96:97], 0
	v_mov_b64_e32 v[106:107], 0
	v_mov_b64_e32 v[108:109], 0
	v_mov_b64_e32 v[110:111], 0
	v_mov_b64_e32 v[112:113], 0
	v_mov_b64_e32 v[82:83], 0
	v_mov_b64_e32 v[84:85], 0
	v_mov_b64_e32 v[86:87], 0
	v_mov_b64_e32 v[88:89], 0
	v_mov_b64_e32 v[98:99], 0
	v_mov_b64_e32 v[100:101], 0
	v_mov_b64_e32 v[102:103], 0
	v_mov_b64_e32 v[104:105], 0
	v_mov_b64_e32 v[114:115], 0
	v_mov_b64_e32 v[116:117], 0
	v_mov_b64_e32 v[118:119], 0
	v_mov_b64_e32 v[120:121], 0
	v_mov_b64_e32 v[122:123], 0
	v_mov_b64_e32 v[124:125], 0
	v_mov_b64_e32 v[126:127], 0
	v_mov_b64_e32 v[128:129], 0
	s_mov_b64 s[44:45], 0x80
	v_add_u32_e32 v252, 0x10000, v141
	v_add_u32_e32 v253, 0x14000, v141
	v_add_u32_e32 v254, 0x18000, v141
	v_add_u32_e32 v255, 0x1c000, v141
	v_readlane_b32 s44, v244, 63
	v_writelane_b32 v244, 0, 63
.LBB0_1341:
	s_add_u32 s16, s0, 0xfff80080
	s_addc_u32 s17, s1, -1
	s_add_i32 s40, 0, 0x10000
	s_cmp_eq_u32 s37, 28
	s_cselect_b32 s19, s11, s17
	s_cselect_b32 s18, s33, s16
	s_cselect_b32 s17, s9, s36
	s_cselect_b32 s16, s34, s35
	s_add_i32 s42, 0, 0x14000
	ds_read_b128 v[144:147], v252
	ds_read_b128 v[148:151], v252 offset:1024
	ds_read_b128 v[152:155], v252 offset:2048
	ds_read_b128 v[156:159], v252 offset:3072
	ds_read_b128 v[178:181], v253
	ds_read_b128 v[182:185], v253 offset:1024
	ds_read_b128 v[186:189], v253 offset:2048
	ds_read_b128 v[190:193], v253 offset:3072
	s_add_i32 m0, s23, 0xc000
	ds_read_b128 v[194:197], v143
	ds_read_b128 v[208:211], v143 offset:1024
	ds_read_b128 v[212:215], v143 offset:2048
	ds_read_b128 v[216:219], v143 offset:3072
	ds_read_b128 v[220:223], v143 offset:4096
	ds_read_b128 v[224:227], v143 offset:5120
	ds_read_b128 v[228:231], v143 offset:6144
	ds_read_b128 v[232:235], v143 offset:7168
	global_load_lds_dwordx4 v136, s[0:1]
	s_add_i32 m0, s23, 0xe000
	s_nop 0
	global_load_lds_dwordx4 v138, s[0:1]
	s_cmp_eq_u32 s44, 1
	s_cbranch_scc0 .Ldf1_0n
	s_waitcnt vmcnt(24)
	s_branch .Ldf1_0d

; #define PG8_STAGE(bufoff, gbase, voff) do { _Pragma("unroll") for (int _i = 0; _i < 2; ++_i) \
;         __builtin_amdgcn_global_load_lds((const unsigned*)((const char*)(gbase) + (voff)[_i]), (PG8_LAS unsigned*)(lds + (bufoff) + ldsw + _i * 8192), 16, 0, 0); } while (0)
; #define PG8_LDA(dst, b, h) do { _Pragma("unroll") for (int m = 0; m < 4; ++m) _Pragma("unroll") for (int k = 0; k < 2; ++k) dst[m][k] = *(const PG8_LAS bf16x8*)(lds + PG8_SA(b, h) + aoff + m * 2048 + k * 1024); } while (0)
; #define PG8_MMA(ai, bj, At, Bt) do { __builtin_amdgcn_s_setprio(1); _Pragma("unroll") for (int m = 0; m < 4; ++m) _Pragma("unroll") for (int n = 0; n < 2; ++n) _Pragma("unroll") for (int k = 0; k < 2; ++k) \
;         acc[ai][bj][m][n] = __builtin_amdgcn_mfma_f32_16x16x32_bf16(Bt[n][k], At[m][k], acc[ai][bj][m][n], 0, 0, 0); __builtin_amdgcn_s_setprio(0); } while (0)
; #define PG8_WAIT_V(n) asm volatile("s_waitcnt vmcnt(" #n ")" ::: "memory")
; #define PG8_WAIT_L(n) asm volatile("s_waitcnt lgkmcnt(" #n ")" ::: "memory")
; #define PG8_BAR __builtin_amdgcn_s_barrier()
; #define PG8_SCHED __builtin_amdgcn_sched_barrier(0)
; template <class Epi, class Sched, bool ALIGN_EPI = false, bool SP2 = false>
; __device__ __forceinline__ void gemm_phase(PG8_LAS unsigned char* lds, const Gemm g, const Sched& S, const Epi& E, const int wave0) {
;     ...
;             PG8_WAIT_V(8); PG8_WAIT_L(0); PG8_BAR; PG8_MMA(0, 0, At, B0); PG8_MMA(0, 1, At, B1); PG8_BAR; PG8_SCHED;
;             PG8_LDA(At, 0, 1); PG8_STAGE(PG8_SB(0, 0), b2, voffB); PG8_STAGE(PG8_SB(0, 1), b2 + hstepB, voffB); PG8_STAGE(PG8_SA(0, 0), a2, voffA);
;             PG8_WAIT_V(8); PG8_WAIT_L(0); PG8_BAR; PG8_MMA(1, 0, At, B0); PG8_MMA(1, 1, At, B1); PG8_BAR; PG8_SCHED;
.Ldf1_0d:
	s_waitcnt lgkmcnt(0)
	s_barrier
	s_setprio 1
	s_waitcnt lgkmcnt(0)
	v_mfma_f32_16x16x32_bf16 v[126:129], v[144:147], v[194:197], v[126:129]
	v_mfma_f32_16x16x32_bf16 v[122:125], v[152:155], v[194:197], v[122:125]
	v_mfma_f32_16x16x32_bf16 v[118:121], v[144:147], v[212:215], v[118:121]
	v_mfma_f32_16x16x32_bf16 v[114:117], v[152:155], v[212:215], v[114:117]
	v_mfma_f32_16x16x32_bf16 v[102:105], v[144:147], v[220:223], v[102:105]
	v_mfma_f32_16x16x32_bf16 v[98:101], v[152:155], v[220:223], v[98:101]
	v_mfma_f32_16x16x32_bf16 v[86:89], v[144:147], v[228:231], v[86:89]
	v_mfma_f32_16x16x32_bf16 v[82:85], v[152:155], v[228:231], v[82:85]
	v_mfma_f32_16x16x32_bf16 v[126:129], v[148:151], v[208:211], v[126:129]
	v_mfma_f32_16x16x32_bf16 v[122:125], v[156:159], v[208:211], v[122:125]
	v_mfma_f32_16x16x32_bf16 v[118:121], v[148:151], v[216:219], v[118:121]
	v_mfma_f32_16x16x32_bf16 v[114:117], v[156:159], v[216:219], v[114:117]
	v_mfma_f32_16x16x32_bf16 v[102:105], v[148:151], v[224:227], v[102:105]
	v_mfma_f32_16x16x32_bf16 v[98:101], v[156:159], v[224:227], v[98:101]
	v_mfma_f32_16x16x32_bf16 v[86:89], v[148:151], v[232:235], v[86:89]
	v_mfma_f32_16x16x32_bf16 v[82:85], v[156:159], v[232:235], v[82:85]
	s_setprio 0
	s_setprio 1
	v_mfma_f32_16x16x32_bf16 v[110:113], v[178:181], v[194:197], v[110:113]
	v_mfma_f32_16x16x32_bf16 v[106:109], v[186:189], v[194:197], v[106:109]
	v_mfma_f32_16x16x32_bf16 v[94:97], v[178:181], v[212:215], v[94:97]
	v_mfma_f32_16x16x32_bf16 v[90:93], v[186:189], v[212:215], v[90:93]
	v_mfma_f32_16x16x32_bf16 v[78:81], v[178:181], v[220:223], v[78:81]
	v_mfma_f32_16x16x32_bf16 v[74:77], v[186:189], v[220:223], v[74:77]
	v_mfma_f32_16x16x32_bf16 v[70:73], v[178:181], v[228:231], v[70:73]
	v_mfma_f32_16x16x32_bf16 v[66:69], v[186:189], v[228:231], v[66:69]
	v_mfma_f32_16x16x32_bf16 v[110:113], v[182:185], v[208:211], v[110:113]
	v_mfma_f32_16x16x32_bf16 v[106:109], v[190:193], v[208:211], v[106:109]
	v_mfma_f32_16x16x32_bf16 v[94:97], v[182:185], v[216:219], v[94:97]
	v_mfma_f32_16x16x32_bf16 v[90:93], v[190:193], v[216:219], v[90:93]
	v_mfma_f32_16x16x32_bf16 v[78:81], v[182:185], v[224:227], v[78:81]
	v_mfma_f32_16x16x32_bf16 v[74:77], v[190:193], v[224:227], v[74:77]
	v_mfma_f32_16x16x32_bf16 v[70:73], v[182:185], v[232:235], v[70:73]
	v_mfma_f32_16x16x32_bf16 v[66:69], v[190:193], v[232:235], v[66:69]
	s_setprio 0
	s_barrier
	s_add_i32 s40, s40, s22
	s_mov_b32 m0, s40
	ds_read_b128 v[194:197], v143 offset:16384
	ds_read_b128 v[208:211], v143 offset:17408
	ds_read_b128 v[212:215], v143 offset:18432
	ds_read_b128 v[216:219], v143 offset:19456
	ds_read_b128 v[220:223], v143 offset:20480
	ds_read_b128 v[224:227], v143 offset:21504
	ds_read_b128 v[228:231], v143 offset:22528
	ds_read_b128 v[232:235], v143 offset:23552
	global_load_lds_dwordx4 v64, s[16:17]
	s_add_i32 m0, s40, 0x2000
	s_add_u32 s40, s16, 0x80000
	s_addc_u32 s41, s17, 0
	s_add_i32 s42, s42, s22
	global_load_lds_dwordx4 v130, s[16:17]
	s_mov_b32 m0, s42
	s_mov_b64 s[100:101], s[18:19]
	global_load_lds_dwordx4 v64, s[40:41]
	s_add_i32 m0, s42, 0x2000
	s_nop 0
	global_load_lds_dwordx4 v130, s[40:41]
	s_mov_b32 m0, s23
	s_nop 0
	global_load_lds_dwordx4 v134, s[18:19]
	s_mov_b32 m0, s24
	s_nop 0
	global_load_lds_dwordx4 v132, s[18:19]
	s_cmp_eq_u32 s44, 1
	s_cbranch_scc0 .Ldf1_1n
	s_waitcnt vmcnt(24)
	s_mov_b32 s44, 0
	s_branch .Ldf1_1d

; #define PG8_STAGE(bufoff, gbase, voff) do { _Pragma("unroll") for (int _i = 0; _i < 2; ++_i) \
;         __builtin_amdgcn_global_load_lds((const unsigned*)((const char*)(gbase) + (voff)[_i]), (PG8_LAS unsigned*)(lds + (bufoff) + ldsw + _i * 8192), 16, 0, 0); } while (0)
; #define PG8_LDA(dst, b, h) do { _Pragma("unroll") for (int m = 0; m < 4; ++m) _Pragma("unroll") for (int k = 0; k < 2; ++k) dst[m][k] = *(const PG8_LAS bf16x8*)(lds + PG8_SA(b, h) + aoff + m * 2048 + k * 1024); } while (0)
; #define PG8_LDB(dst, b, h) do { _Pragma("unroll") for (int n = 0; n < 2; ++n) _Pragma("unroll") for (int k = 0; k < 2; ++k) dst[n][k] = *(const PG8_LAS bf16x8*)(lds + PG8_SB(b, h) + boff + n * 2048 + k * 1024); } while (0)
; #define PG8_MMA(ai, bj, At, Bt) do { __builtin_amdgcn_s_setprio(1); _Pragma("unroll") for (int m = 0; m < 4; ++m) _Pragma("unroll") for (int n = 0; n < 2; ++n) _Pragma("unroll") for (int k = 0; k < 2; ++k) \
;         acc[ai][bj][m][n] = __builtin_amdgcn_mfma_f32_16x16x32_bf16(Bt[n][k], At[m][k], acc[ai][bj][m][n], 0, 0, 0); __builtin_amdgcn_s_setprio(0); } while (0)
; #define PG8_WAIT_V(n) asm volatile("s_waitcnt vmcnt(" #n ")" ::: "memory")
; #define PG8_WAIT_L(n) asm volatile("s_waitcnt lgkmcnt(" #n ")" ::: "memory")
; #define PG8_BAR __builtin_amdgcn_s_barrier()
; #define PG8_SCHED __builtin_amdgcn_sched_barrier(0)
; template <class Epi, class Sched, bool ALIGN_EPI = false, bool SP2 = false>
; __device__ __forceinline__ void gemm_phase(PG8_LAS unsigned char* lds, const Gemm g, const Sched& S, const Epi& E, const int wave0) {
;     ...
;             PG8_WAIT_V(8); PG8_WAIT_L(0); PG8_BAR; PG8_MMA(1, 0, At, B0); PG8_MMA(1, 1, At, B1); PG8_BAR; PG8_SCHED;
;             PG8_LDB(B0, 1, 0); PG8_LDB(B1, 1, 1); PG8_SCHED; PG8_LDA(At, 1, 0); PG8_STAGE(PG8_SA(0, 1), a2 + hstepA, voffA);
;             PG8_WAIT_V(8); PG8_WAIT_L(0); PG8_BAR; PG8_MMA(0, 0, At, B0); PG8_MMA(0, 1, At, B1); PG8_BAR; PG8_SCHED;
.Ldf1_1d:
	s_waitcnt lgkmcnt(0)
	s_barrier
	s_setprio 1
	s_waitcnt lgkmcnt(0)
	v_mfma_f32_16x16x32_bf16 v[60:63], v[144:147], v[194:197], v[60:63]
	v_mfma_f32_16x16x32_bf16 v[56:59], v[152:155], v[194:197], v[56:59]
	v_mfma_f32_16x16x32_bf16 v[52:55], v[144:147], v[212:215], v[52:55]
	v_mfma_f32_16x16x32_bf16 v[48:51], v[152:155], v[212:215], v[48:51]
	v_mfma_f32_16x16x32_bf16 v[36:39], v[144:147], v[220:223], v[36:39]
	v_mfma_f32_16x16x32_bf16 v[32:35], v[152:155], v[220:223], v[32:35]
	v_mfma_f32_16x16x32_bf16 v[20:23], v[144:147], v[228:231], v[20:23]
	v_mfma_f32_16x16x32_bf16 v[16:19], v[152:155], v[228:231], v[16:19]
	v_mfma_f32_16x16x32_bf16 v[60:63], v[148:151], v[208:211], v[60:63]
	v_mfma_f32_16x16x32_bf16 v[56:59], v[156:159], v[208:211], v[56:59]
	v_mfma_f32_16x16x32_bf16 v[52:55], v[148:151], v[216:219], v[52:55]
	v_mfma_f32_16x16x32_bf16 v[48:51], v[156:159], v[216:219], v[48:51]
	v_mfma_f32_16x16x32_bf16 v[36:39], v[148:151], v[224:227], v[36:39]
	v_mfma_f32_16x16x32_bf16 v[32:35], v[156:159], v[224:227], v[32:35]
	v_mfma_f32_16x16x32_bf16 v[20:23], v[148:151], v[232:235], v[20:23]
	v_mfma_f32_16x16x32_bf16 v[16:19], v[156:159], v[232:235], v[16:19]
	s_setprio 0
	s_setprio 1
	v_mfma_f32_16x16x32_bf16 v[44:47], v[178:181], v[194:197], v[44:47]
	v_mfma_f32_16x16x32_bf16 v[40:43], v[186:189], v[194:197], v[40:43]
	v_mfma_f32_16x16x32_bf16 v[28:31], v[178:181], v[212:215], v[28:31]
	v_mfma_f32_16x16x32_bf16 v[24:27], v[186:189], v[212:215], v[24:27]
	v_mfma_f32_16x16x32_bf16 v[12:15], v[178:181], v[220:223], v[12:15]
	v_mfma_f32_16x16x32_bf16 v[8:11], v[186:189], v[220:223], v[8:11]
	v_mfma_f32_16x16x32_bf16 v[4:7], v[178:181], v[228:231], v[4:7]
	v_mfma_f32_16x16x32_bf16 v[0:3], v[186:189], v[228:231], v[0:3]
	v_mfma_f32_16x16x32_bf16 v[44:47], v[182:185], v[208:211], v[44:47]
	v_mfma_f32_16x16x32_bf16 v[40:43], v[190:193], v[208:211], v[40:43]
	v_mfma_f32_16x16x32_bf16 v[28:31], v[182:185], v[216:219], v[28:31]
	v_mfma_f32_16x16x32_bf16 v[24:27], v[190:193], v[216:219], v[24:27]
	v_mfma_f32_16x16x32_bf16 v[12:15], v[182:185], v[224:227], v[12:15]
	v_mfma_f32_16x16x32_bf16 v[8:11], v[190:193], v[224:227], v[8:11]
	v_mfma_f32_16x16x32_bf16 v[4:7], v[182:185], v[232:235], v[4:7]
	v_mfma_f32_16x16x32_bf16 v[0:3], v[190:193], v[232:235], v[0:3]
	s_setprio 0
	s_barrier
	s_add_i32 s40, 0, 0x18000
	s_add_i32 s41, 0, 0x1c000
	ds_read_b128 v[144:147], v254
	ds_read_b128 v[148:151], v254 offset:1024
	ds_read_b128 v[152:155], v254 offset:2048
	ds_read_b128 v[156:159], v254 offset:3072
	ds_read_b128 v[178:181], v255
	ds_read_b128 v[182:185], v255 offset:1024
	ds_read_b128 v[186:189], v255 offset:2048
	ds_read_b128 v[190:193], v255 offset:3072
	s_add_u32 s18, s18, 0x80000
	s_addc_u32 s19, s19, 0
	s_mov_b32 m0, s25
	ds_read_b128 v[194:197], v143 offset:32768
	ds_read_b128 v[208:211], v143 offset:33792
	ds_read_b128 v[212:215], v143 offset:34816
	ds_read_b128 v[216:219], v143 offset:35840
	ds_read_b128 v[220:223], v143 offset:36864
	ds_read_b128 v[224:227], v143 offset:37888
	ds_read_b128 v[228:231], v143 offset:38912
	ds_read_b128 v[232:235], v143 offset:39936
	global_load_lds_dwordx4 v134, s[18:19]
	s_mov_b32 m0, s26
	s_nop 0
	global_load_lds_dwordx4 v132, s[18:19]
	s_waitcnt vmcnt(8)
	s_waitcnt lgkmcnt(0)
	s_barrier
	s_setprio 1
	s_waitcnt lgkmcnt(0)
	v_mfma_f32_16x16x32_bf16 v[126:129], v[144:147], v[194:197], v[126:129]
	v_mfma_f32_16x16x32_bf16 v[122:125], v[152:155], v[194:197], v[122:125]
	v_mfma_f32_16x16x32_bf16 v[118:121], v[144:147], v[212:215], v[118:121]
	v_mfma_f32_16x16x32_bf16 v[114:117], v[152:155], v[212:215], v[114:117]
	v_mfma_f32_16x16x32_bf16 v[102:105], v[144:147], v[220:223], v[102:105]
	v_mfma_f32_16x16x32_bf16 v[98:101], v[152:155], v[220:223], v[98:101]
	v_mfma_f32_16x16x32_bf16 v[86:89], v[144:147], v[228:231], v[86:89]
	v_mfma_f32_16x16x32_bf16 v[82:85], v[152:155], v[228:231], v[82:85]
	v_mfma_f32_16x16x32_bf16 v[126:129], v[148:151], v[208:211], v[126:129]
	v_mfma_f32_16x16x32_bf16 v[122:125], v[156:159], v[208:211], v[122:125]
	v_mfma_f32_16x16x32_bf16 v[118:121], v[148:151], v[216:219], v[118:121]
	v_mfma_f32_16x16x32_bf16 v[114:117], v[156:159], v[216:219], v[114:117]
	v_mfma_f32_16x16x32_bf16 v[102:105], v[148:151], v[224:227], v[102:105]
	v_mfma_f32_16x16x32_bf16 v[98:101], v[156:159], v[224:227], v[98:101]
	v_mfma_f32_16x16x32_bf16 v[86:89], v[148:151], v[232:235], v[86:89]
	v_mfma_f32_16x16x32_bf16 v[82:85], v[156:159], v[232:235], v[82:85]
	s_setprio 0
	s_setprio 1
	v_mfma_f32_16x16x32_bf16 v[110:113], v[178:181], v[194:197], v[110:113]
	v_mfma_f32_16x16x32_bf16 v[106:109], v[186:189], v[194:197], v[106:109]
	v_mfma_f32_16x16x32_bf16 v[94:97], v[178:181], v[212:215], v[94:97]
	v_mfma_f32_16x16x32_bf16 v[90:93], v[186:189], v[212:215], v[90:93]
	v_mfma_f32_16x16x32_bf16 v[78:81], v[178:181], v[220:223], v[78:81]
	v_mfma_f32_16x16x32_bf16 v[74:77], v[186:189], v[220:223], v[74:77]
	v_mfma_f32_16x16x32_bf16 v[70:73], v[178:181], v[228:231], v[70:73]
	v_mfma_f32_16x16x32_bf16 v[66:69], v[186:189], v[228:231], v[66:69]
	v_mfma_f32_16x16x32_bf16 v[110:113], v[182:185], v[208:211], v[110:113]
	v_mfma_f32_16x16x32_bf16 v[106:109], v[190:193], v[208:211], v[106:109]
	v_mfma_f32_16x16x32_bf16 v[94:97], v[182:185], v[216:219], v[94:97]
	v_mfma_f32_16x16x32_bf16 v[90:93], v[190:193], v[216:219], v[90:93]
	v_mfma_f32_16x16x32_bf16 v[78:81], v[182:185], v[224:227], v[78:81]
	v_mfma_f32_16x16x32_bf16 v[74:77], v[190:193], v[224:227], v[74:77]
	v_mfma_f32_16x16x32_bf16 v[70:73], v[182:185], v[232:235], v[70:73]
	v_mfma_f32_16x16x32_bf16 v[66:69], v[190:193], v[232:235], v[66:69]
	s_setprio 0
	s_barrier
; #define PG8_STAGE(bufoff, gbase, voff) do { _Pragma("unroll") for (int _i = 0; _i < 2; ++_i) \
;         __builtin_amdgcn_global_load_lds((const unsigned*)((const char*)(gbase) + (voff)[_i]), (PG8_LAS unsigned*)(lds + (bufoff) + ldsw + _i * 8192), 16, 0, 0); } while (0)
; #define PG8_LDA(dst, b, h) do { _Pragma("unroll") for (int m = 0; m < 4; ++m) _Pragma("unroll") for (int k = 0; k < 2; ++k) dst[m][k] = *(const PG8_LAS bf16x8*)(lds + PG8_SA(b, h) + aoff + m * 2048 + k * 1024); } while (0)
; #define PG8_MMA(ai, bj, At, Bt) do { __builtin_amdgcn_s_setprio(1); _Pragma("unroll") for (int m = 0; m < 4; ++m) _Pragma("unroll") for (int n = 0; n < 2; ++n) _Pragma("unroll") for (int k = 0; k < 2; ++k) \
;         acc[ai][bj][m][n] = __builtin_amdgcn_mfma_f32_16x16x32_bf16(Bt[n][k], At[m][k], acc[ai][bj][m][n], 0, 0, 0); __builtin_amdgcn_s_setprio(0); } while (0)
; #define PG8_WAIT_V(n) asm volatile("s_waitcnt vmcnt(" #n ")" ::: "memory")
; #define PG8_WAIT_L(n) asm volatile("s_waitcnt lgkmcnt(" #n ")" ::: "memory")
; #define PG8_BAR __builtin_amdgcn_s_barrier()
; #define PG8_SCHED __builtin_amdgcn_sched_barrier(0)
; template <class Epi, class Sched, bool ALIGN_EPI = false, bool SP2 = false>
; __device__ __forceinline__ void gemm_phase(PG8_LAS unsigned char* lds, const Gemm g, const Sched& S, const Epi& E, const int wave0) {
;     ...
;             PG8_WAIT_V(8); PG8_WAIT_L(0); PG8_BAR; PG8_MMA(0, 0, At, B0); PG8_MMA(0, 1, At, B1); PG8_BAR; PG8_SCHED;
;             PG8_LDA(At, 1, 1); PG8_STAGE(PG8_SB(1, 0), b3, voffB); PG8_STAGE(PG8_SB(1, 1), b3 + hstepB, voffB); PG8_STAGE(PG8_SA(1, 0), a3, voffA);
;             PG8_WAIT_V(8); PG8_WAIT_L(0); PG8_BAR; PG8_MMA(1, 0, At, B0); PG8_MMA(1, 1, At, B1); PG8_BAR; PG8_SCHED;
	s_add_i32 s18, s40, s22
	s_add_u32 s44, s16, 0x80
	s_addc_u32 s45, s17, 0
	s_mov_b32 m0, s18
	ds_read_b128 v[194:197], v143 offset:49152
	ds_read_b128 v[208:211], v143 offset:50176
	ds_read_b128 v[212:215], v143 offset:51200
	ds_read_b128 v[216:219], v143 offset:52224
	ds_read_b128 v[220:223], v143 offset:53248
	ds_read_b128 v[224:227], v143 offset:54272
	ds_read_b128 v[228:231], v143 offset:55296
	ds_read_b128 v[232:235], v143 offset:56320
	global_load_lds_dwordx4 v64, s[44:45]
	s_add_i32 m0, s18, 0x2000
	s_add_u32 s16, s16, 0x80080
	s_addc_u32 s17, s17, 0
	s_add_i32 s18, s41, s22
	global_load_lds_dwordx4 v130, s[44:45]
	s_mov_b32 m0, s18
	s_nop 0
	global_load_lds_dwordx4 v64, s[16:17]
	s_add_i32 m0, s18, 0x2000
	s_nop 0
	global_load_lds_dwordx4 v130, s[16:17]
	s_add_u32 s100, s100, 0x80
	s_addc_u32 s101, s101, 0
	s_mov_b32 m0, s27
	s_nop 0
	global_load_lds_dwordx4 v134, s[100:101]
	s_mov_b32 m0, s28
	s_nop 0
	global_load_lds_dwordx4 v132, s[100:101]
	s_waitcnt vmcnt(8)
	s_waitcnt lgkmcnt(0)
	s_barrier
	s_setprio 1
	s_waitcnt lgkmcnt(0)
	v_mfma_f32_16x16x32_bf16 v[60:63], v[144:147], v[194:197], v[60:63]
	v_mfma_f32_16x16x32_bf16 v[56:59], v[152:155], v[194:197], v[56:59]
	v_mfma_f32_16x16x32_bf16 v[52:55], v[144:147], v[212:215], v[52:55]
	v_mfma_f32_16x16x32_bf16 v[48:51], v[152:155], v[212:215], v[48:51]
	v_mfma_f32_16x16x32_bf16 v[36:39], v[144:147], v[220:223], v[36:39]
	v_mfma_f32_16x16x32_bf16 v[32:35], v[152:155], v[220:223], v[32:35]
	v_mfma_f32_16x16x32_bf16 v[20:23], v[144:147], v[228:231], v[20:23]
	v_mfma_f32_16x16x32_bf16 v[16:19], v[152:155], v[228:231], v[16:19]
	v_mfma_f32_16x16x32_bf16 v[60:63], v[148:151], v[208:211], v[60:63]
	v_mfma_f32_16x16x32_bf16 v[56:59], v[156:159], v[208:211], v[56:59]
	v_mfma_f32_16x16x32_bf16 v[52:55], v[148:151], v[216:219], v[52:55]
	v_mfma_f32_16x16x32_bf16 v[48:51], v[156:159], v[216:219], v[48:51]
	v_mfma_f32_16x16x32_bf16 v[36:39], v[148:151], v[224:227], v[36:39]
	v_mfma_f32_16x16x32_bf16 v[32:35], v[156:159], v[224:227], v[32:35]
	v_mfma_f32_16x16x32_bf16 v[20:23], v[148:151], v[232:235], v[20:23]
	v_mfma_f32_16x16x32_bf16 v[16:19], v[156:159], v[232:235], v[16:19]
	s_setprio 0
	s_setprio 1
	v_mfma_f32_16x16x32_bf16 v[44:47], v[178:181], v[194:197], v[44:47]
	v_mfma_f32_16x16x32_bf16 v[40:43], v[186:189], v[194:197], v[40:43]
	v_mfma_f32_16x16x32_bf16 v[28:31], v[178:181], v[212:215], v[28:31]
	v_mfma_f32_16x16x32_bf16 v[24:27], v[186:189], v[212:215], v[24:27]
	v_mfma_f32_16x16x32_bf16 v[12:15], v[178:181], v[220:223], v[12:15]
	v_mfma_f32_16x16x32_bf16 v[8:11], v[186:189], v[220:223], v[8:11]
	v_mfma_f32_16x16x32_bf16 v[4:7], v[178:181], v[228:231], v[4:7]
	v_mfma_f32_16x16x32_bf16 v[0:3], v[186:189], v[228:231], v[0:3]
	v_mfma_f32_16x16x32_bf16 v[44:47], v[182:185], v[208:211], v[44:47]
	v_mfma_f32_16x16x32_bf16 v[40:43], v[190:193], v[208:211], v[40:43]
	v_mfma_f32_16x16x32_bf16 v[28:31], v[182:185], v[216:219], v[28:31]
	v_mfma_f32_16x16x32_bf16 v[24:27], v[190:193], v[216:219], v[24:27]
	v_mfma_f32_16x16x32_bf16 v[12:15], v[182:185], v[224:227], v[12:15]
	v_mfma_f32_16x16x32_bf16 v[8:11], v[190:193], v[224:227], v[8:11]
	v_mfma_f32_16x16x32_bf16 v[4:7], v[182:185], v[232:235], v[4:7]
	v_mfma_f32_16x16x32_bf16 v[0:3], v[190:193], v[232:235], v[0:3]
	s_setprio 0
	s_barrier
	s_add_i32 s37, s37, 2
	s_add_u32 s0, s0, 0x100
	s_addc_u32 s1, s1, 0
	s_add_u32 s35, s35, 0x100
	s_addc_u32 s36, s36, 0
	s_cmp_gt_u32 s37, 29
	s_cbranch_scc0 .LBB0_1341
	s_mov_b64 s[44:45], 0x80
	s_and_b64 vcc, exec, s[6:7]
	s_mov_b64 s[34:35], 0x45000
	s_cbranch_vccz .LBB0_1344
	s_barrier
; __device__ __forceinline__ unsigned cvt_pk_bf16(float lo, float hi) { const f32x2_t v = {lo, hi}; const bf16x2_t b = __builtin_convertvector(v, bf16x2_t); return __builtin_bit_cast(unsigned, b); }
;     __device__ __forceinline__ void operator()(const f32x4 (&acc)[2][2][4][2], const Unit& u, int wr, int wc, int fr, int fq) const {
;         const int row0 = u.pm * BM + wr * 64 + fr; const int col0 = u.pn * BM + wc * 32 + 8 * fq;
; #pragma unroll
;         for (int ai = 0; ai < 2; ++ai)
; #pragma unroll
;             for (int m = 0; m < 4; ++m) { bf16_t* rowp = O + (size_t)u.zo * zsO + (size_t)(row0 + ai * HALF + m * 16) * ldc + col0;
; #pragma unroll
;                 for (int bj = 0; bj < 2; ++bj) { f32x4 v0 = acc[ai][bj][m][0], v1 = acc[ai][bj][m][1];
;                     if (ACT == 2) {
; #pragma unroll
;                         for (int j = 0; j < 4; ++j) { const float a = fmaxf(v0[j], 0.f), b = fmaxf(v1[j], 0.f); v0[j] = a * a; v1[j] = b * b; } }
;                     u32x4 w; w.x = cvt_pk_bf16(v0[0], v0[1]); w.y = cvt_pk_bf16(v0[2], v0[3]); w.z = cvt_pk_bf16(v1[0], v1[1]); w.w = cvt_pk_bf16(v1[2], v1[3]);
;                     *(u32x4*)(rowp + bj * HALF) = w; } }
;     }
.LBB0_1344:
	v_lshl_add_u32 v146, s31, 8, v140
	v_lshl_or_b32 v144, s30, 8, v142
	v_ashrrev_i32_e32 v147, 31, v146
	v_readlane_b32 s0, v247, 44
	v_cvt_pk_bf16_f32 v110, v110, v111
	v_cvt_pk_bf16_f32 v111, v112, v113
	v_cvt_pk_bf16_f32 v112, v106, v107
	v_or_b32_e32 v106, 16, v146
	v_cvt_pk_bf16_f32 v94, v94, v95
	v_cvt_pk_bf16_f32 v95, v96, v97
	v_cvt_pk_bf16_f32 v96, v90, v91
	v_or_b32_e32 v90, 32, v146
	v_cvt_pk_bf16_f32 v78, v78, v79
	v_cvt_pk_bf16_f32 v79, v80, v81
	v_cvt_pk_bf16_f32 v80, v74, v75
	v_or_b32_e32 v74, 48, v146
	v_ashrrev_i32_e32 v145, 31, v144
	v_lshlrev_b64 v[148:149], 12, v[146:147]
	v_readlane_b32 s1, v247, 45
	v_ashrrev_i32_e32 v107, 31, v106
	v_ashrrev_i32_e32 v91, 31, v90
	v_ashrrev_i32_e32 v75, 31, v74
	v_lshl_add_u64 v[148:149], s[0:1], 0, v[148:149]
	v_lshlrev_b64 v[144:145], 1, v[144:145]
	v_lshlrev_b64 v[106:107], 12, v[106:107]
	v_lshlrev_b64 v[90:91], 12, v[90:91]
	v_lshlrev_b64 v[74:75], 12, v[74:75]
	v_lshl_add_u64 v[148:149], v[148:149], 0, v[144:145]
	v_lshl_add_u64 v[106:107], s[0:1], 0, v[106:107]
	v_lshl_add_u64 v[90:91], s[0:1], 0, v[90:91]
	v_lshl_add_u64 v[74:75], s[0:1], 0, v[74:75]
	s_mov_b64 s[0:1], 0x80000
	v_cvt_pk_bf16_f32 v70, v70, v71
	v_cvt_pk_bf16_f32 v71, v72, v73
	v_cvt_pk_bf16_f32 v72, v66, v67
	v_lshl_add_u64 v[66:67], v[148:149], 0, s[0:1]
	s_mov_b32 s0, 0x80000
	v_cvt_pk_bf16_f32 v60, v60, v61
	v_cvt_pk_bf16_f32 v61, v62, v63
	v_cvt_pk_bf16_f32 v62, v56, v57
	v_add_co_u32_e32 v56, vcc, s0, v148
	v_cvt_pk_bf16_f32 v44, v44, v45
	v_cvt_pk_bf16_f32 v45, v46, v47
	v_cvt_pk_bf16_f32 v46, v40, v41
	v_cvt_pk_bf16_f32 v47, v42, v43
	s_mov_b64 s[0:1], 0x90000
	v_addc_co_u32_e32 v57, vcc, 0, v149, vcc
	global_store_dwordx4 v[66:67], v[44:47], off offset:256
	v_cvt_pk_bf16_f32 v28, v28, v29
	v_cvt_pk_bf16_f32 v29, v30, v31
	v_lshl_add_u64 v[44:45], v[148:149], 0, s[0:1]
	s_mov_b32 s0, 0x90000
	v_add_co_u32_e32 v46, vcc, s0, v148
	v_cvt_pk_bf16_f32 v30, v24, v25
	v_cvt_pk_bf16_f32 v31, v26, v27
	s_mov_b64 s[0:1], 0xa0000
	v_addc_co_u32_e32 v47, vcc, 0, v149, vcc
	global_store_dwordx4 v[44:45], v[28:31], off offset:256
	v_cvt_pk_bf16_f32 v12, v12, v13
	v_cvt_pk_bf16_f32 v13, v14, v15
	v_lshl_add_u64 v[28:29], v[148:149], 0, s[0:1]
	s_mov_b32 s0, 0xa0000
	v_add_co_u32_e32 v30, vcc, s0, v148
	v_cvt_pk_bf16_f32 v14, v8, v9
	v_cvt_pk_bf16_f32 v15, v10, v11
	s_mov_b64 s[0:1], 0xb0000
	v_cvt_pk_bf16_f32 v113, v108, v109
	v_addc_co_u32_e32 v31, vcc, 0, v149, vcc
	global_store_dwordx4 v[28:29], v[12:15], off offset:256
	global_store_dwordx4 v[148:149], v[110:113], off offset:256
	v_cvt_pk_bf16_f32 v97, v92, v93
	v_lshl_add_u64 v[12:13], v[148:149], 0, s[0:1]
	s_mov_b32 s0, 0xb0000
	v_lshl_add_u64 v[110:111], v[106:107], 0, v[144:145]
	v_add_co_u32_e32 v14, vcc, s0, v148
	global_store_dwordx4 v[110:111], v[94:97], off offset:256
	v_cvt_pk_bf16_f32 v81, v76, v77
	v_addc_co_u32_e32 v15, vcc, 0, v149, vcc
	v_lshl_add_u64 v[94:95], v[90:91], 0, v[144:145]
	v_cvt_pk_bf16_f32 v126, v126, v127
	v_cvt_pk_bf16_f32 v127, v128, v129
	v_cvt_pk_bf16_f32 v128, v122, v123
	v_cvt_pk_bf16_f32 v129, v124, v125
	v_cvt_pk_bf16_f32 v106, v118, v119
	v_cvt_pk_bf16_f32 v107, v120, v121
	v_cvt_pk_bf16_f32 v108, v114, v115
	v_cvt_pk_bf16_f32 v109, v116, v117
	v_cvt_pk_bf16_f32 v90, v102, v103
	v_cvt_pk_bf16_f32 v91, v104, v105
	v_cvt_pk_bf16_f32 v92, v98, v99
	v_cvt_pk_bf16_f32 v93, v100, v101
	global_store_dwordx4 v[94:95], v[78:81], off offset:256
	v_cvt_pk_bf16_f32 v76, v82, v83
	v_cvt_pk_bf16_f32 v77, v84, v85
	v_lshl_add_u64 v[78:79], v[74:75], 0, v[144:145]
	v_cvt_pk_bf16_f32 v74, v86, v87
	v_cvt_pk_bf16_f32 v75, v88, v89
	v_cvt_pk_bf16_f32 v73, v68, v69
	v_cvt_pk_bf16_f32 v63, v58, v59
	v_cvt_pk_bf16_f32 v40, v52, v53
	v_cvt_pk_bf16_f32 v41, v54, v55
	v_cvt_pk_bf16_f32 v42, v48, v49
	v_cvt_pk_bf16_f32 v43, v50, v51
	v_cvt_pk_bf16_f32 v24, v36, v37
	v_cvt_pk_bf16_f32 v25, v38, v39
	v_cvt_pk_bf16_f32 v26, v32, v33
	v_cvt_pk_bf16_f32 v27, v34, v35
	v_cvt_pk_bf16_f32 v8, v20, v21
	v_cvt_pk_bf16_f32 v9, v22, v23
	v_cvt_pk_bf16_f32 v10, v16, v17
	v_cvt_pk_bf16_f32 v11, v18, v19
	v_cvt_pk_bf16_f32 v4, v4, v5
	v_cvt_pk_bf16_f32 v5, v6, v7
	v_cvt_pk_bf16_f32 v6, v0, v1
	v_cvt_pk_bf16_f32 v7, v2, v3
	s_andn2_b64 vcc, exec, s[2:3]
	s_mov_b64 s[0:1], -1
	s_mov_b64 s[36:37], 0x80
	global_store_dwordx4 v[148:149], v[126:129], off
	global_store_dwordx4 v[110:111], v[106:109], off
	global_store_dwordx4 v[94:95], v[90:93], off
	global_store_dwordx4 v[78:79], v[74:77], off
	global_store_dwordx4 v[78:79], v[70:73], off offset:256
	global_store_dwordx4 v[56:57], v[60:63], off
	global_store_dwordx4 v[46:47], v[40:43], off
	global_store_dwordx4 v[30:31], v[24:27], off
	global_store_dwordx4 v[14:15], v[8:11], off
	global_store_dwordx4 v[12:13], v[4:7], off offset:256
	v_writelane_b32 v244, 1, 63
	s_cbranch_vccnz .LBB0_1333
	s_andn2_b64 vcc, exec, s[4:5]
	s_cbranch_vccnz .LBB0_1332
	s_barrier
	s_branch .LBB0_1332

; template <class Epi, class Sched, bool ALIGN_EPI = false, bool SP2 = false>
; __device__ __forceinline__ void gemm_phase(PG8_LAS unsigned char* lds, const Gemm g, const Sched& S, const Epi& E, const int wave0) {
;     int tid_ = wave0 * 64 + xb_lane_pg8();
;     const int tid = tid_, wid = __builtin_amdgcn_readfirstlane(tid >> 6), lane = tid & 63, wr = wid >> 2, wc = wid & 3, fr = lane & 15, fq = lane >> 4;
;     const int K = g.K, nt = K / BK;
;     unsigned voffA[2], voffB[2];
; #pragma unroll
;     for (int i = 0; i < 2; ++i) { int R, C; stage_rc(tid * 16 + i * 8192, R, C); const int Rb = Epi::PERM ? ((R & ~31) + perm32(R & 31)) : R;
;         voffA[i] = (unsigned)(R * g.lda + C) * 2u; voffB[i] = (unsigned)(Rb * g.ldb + C) * 2u; }
;     const size_t kstep = (size_t)(BK * 2);
;     const size_t hstepA = (size_t)HALF * g.lda * 2, hstepB = (size_t)HALF * g.ldb * 2;
;     const size_t tstepA = 2 * hstepA, tstepB = 2 * hstepB;
;     const unsigned ldsw = (unsigned)wid * 1024u;
;     const int aoff = lds_byte(wr * 64 + fr, fq * 8), boff = lds_byte(wc * 32 + fr, fq * 8);
;     ...
;     Unit cur, nxt; int ui = 0;
;     if (!S.next(0, cur)) return;
;     f32x4 acc[2][2][4][2];
; #pragma unroll
;     for (int a = 0; a < 2; ++a)
; #pragma unroll
;         for (int b = 0; b < 2; ++b)
; #pragma unroll
;             for (int m = 0; m < 4; ++m)
; #pragma unroll
;                 for (int n = 0; n < 2; ++n) acc[a][b][m][n] = (f32x4){0.f, 0.f, 0.f, 0.f};
;     bf16x8 At[4][2], B0[2][2], B1[2][2];
;     const char* cA = (const char*)g.A + (size_t)cur.z * g.zsA + (size_t)cur.pm * tstepA + (size_t)cur.k0 * 2; const char* cB = (const char*)g.Bt + (size_t)cur.z * g.zsB + (size_t)cur.pn * tstepB + (size_t)cur.k0 * 2;
;     S.a_ready(cur);
;     if constexpr (SP2) {
;         PG8_STAGE(PG8_SB(0, 0), cB, voffB); PG8_STAGE(PG8_SB(0, 1), cB + hstepB, voffB); PG8_STAGE(PG8_SA(0, 0), cA, voffA); PG8_STAGE(PG8_SA(0, 1), cA + hstepA, voffA);
;         if (wr == 1) PG8_BAR;
;         PG8_WAIT_V(2); PG8_BAR;
;         PG8_STAGE(PG8_SB(1, 0), cB + kstep, voffB); PG8_STAGE(PG8_SA(1, 0), cA + kstep, voffA); PG8_STAGE(PG8_SB(1, 1), cB + hstepB + kstep, voffB);
;         PG8_WAIT_V(6); PG8_BAR;
;     } else {
;         PG8_STAGE(PG8_SB(0, 0), cB, voffB); PG8_STAGE(PG8_SA(0, 0), cA, voffA); PG8_STAGE(PG8_SB(0, 1), cB + hstepB, voffB); PG8_STAGE(PG8_SA(0, 1), cA + hstepA, voffA);
.LBB0_1352:
	v_lshrrev_b32_e32 v16, 1, v6
	v_and_b32_e32 v16, 24, v16
	v_and_b32_e32 v7, 15, v6
	v_lshlrev_b32_e32 v17, 1, v16
	v_lshlrev_b32_e32 v6, 2, v6
	s_lshl_b32 s1, s1, 5
	v_lshl_or_b32 v140, s2, 6, v7
	v_lshl_or_b32 v7, v7, 6, v17
	s_lshl_b32 s2, s2, 13
	v_and_b32_e32 v6, 32, v6
	s_and_b32 s1, s1, 0x60
	v_bitop3_b32 v17, v7, s2, v6 bitop3:0xde
	s_lshl_b32 s2, s1, 7
	v_lshl_add_u64 v[8:9], s[16:17], 0, v[64:65]
	v_mov_b32_e32 v131, v65
	v_readlane_b32 s4, v247, 28
	v_bitop3_b32 v141, v7, s2, v6 bitop3:0xde
	s_add_u32 s2, s16, 0x80080
	v_lshl_add_u64 v[10:11], s[16:17], 0, v[130:131]
	v_mov_b32_e32 v135, v65
	v_readlane_b32 s5, v247, 29
	s_addc_u32 s3, s17, 0
	s_add_i32 m0, s23, 0x18000
	v_lshl_add_u64 v[6:7], v[8:9], 0, s[36:37]
	v_lshl_add_u64 v[12:13], s[4:5], 0, v[134:135]
	v_mov_b32_e32 v133, v65
	s_waitcnt vmcnt(2)
	s_barrier
	global_load_lds_dwordx4 v[6:7], off
	v_lshl_add_u64 v[6:7], v[10:11], 0, s[36:37]
	s_add_i32 m0, s23, 0x1a000
	s_add_i32 s34, s23, 0x8000
	v_lshl_add_u64 v[14:15], s[4:5], 0, v[132:133]
	global_load_lds_dwordx4 v[6:7], off
	v_lshl_add_u64 v[6:7], v[12:13], 0, s[36:37]
	s_mov_b32 m0, s34
	s_add_i32 s35, s23, 0xa000
	global_load_lds_dwordx4 v[6:7], off
	v_lshl_add_u64 v[6:7], v[14:15], 0, s[36:37]
	s_mov_b32 m0, s35
	v_or_b32_e32 v142, s1, v16
	global_load_lds_dwordx4 v[6:7], off
	s_add_i32 m0, s23, 0x1c000
	v_lshl_add_u64 v[6:7], s[2:3], 0, v[64:65]
	global_load_lds_dwordx4 v[6:7], off
	v_lshl_add_u64 v[6:7], s[2:3], 0, v[130:131]
	s_add_i32 m0, s23, 0x1e000
	s_cmpk_lt_u32 s0, 0x100
	global_load_lds_dwordx4 v[6:7], off
	v_lshlrev_b32_e32 v6, 15, v4
	v_and_b32_e32 v6, 0xffff0000, v6
	v_lshl_add_u32 v3, v3, 12, v6
	v_and_b32_e32 v4, 1, v4
	v_lshl_or_b32 v3, v4, 6, v3
	v_readlane_b32 s0, v247, 17
	v_lshl_add_u32 v136, v5, 1, v3
	v_lshlrev_b32_e32 v3, 15, v0
	s_mov_b32 s30, s0
	v_readlane_b32 s0, v247, 22
	v_and_b32_e32 v3, 0xffff0000, v3
	v_readlane_b32 s1, v247, 23
	v_writelane_b32 v244, 0, 63
	s_waitcnt vmcnt(6)
	v_lshl_add_u32 v1, v1, 12, v3
	v_and_b32_e32 v0, 1, v0
	s_mov_b32 s31, s0
	v_readlane_b32 s0, v247, 20
	v_lshl_or_b32 v0, v0, 6, v1
	v_readlane_b32 s1, v247, 21
	s_cselect_b64 s[8:9], -1, 0
	v_mov_b32_e32 v137, v65
	v_lshl_add_u32 v138, v2, 1, v0
	v_mov_b32_e32 v139, v65
	s_mov_b32 s36, 0
	v_add_u32_e32 v143, 0, v17
	s_mov_b32 s40, s0
	s_mov_b64 s[0:1], s[4:5]
	s_barrier
	s_branch .LBB0_1355

;     __host__ __device__ bool next(int i, Unit& u) const { return tile((long)i * G + c, u); }
;     __host__ __device__ bool next(int i, Unit& u) const { if (!tile((long)(i / NZ) * G + c, u)) return false; u.z = i % NZ; return true; }
; #define PG8_STAGE(bufoff, gbase, voff) do { _Pragma("unroll") for (int _i = 0; _i < 2; ++_i) \
;         __builtin_amdgcn_global_load_lds((const unsigned*)((const char*)(gbase) + (voff)[_i]), (PG8_LAS unsigned*)(lds + (bufoff) + ldsw + _i * 8192), 16, 0, 0); } while (0)
; #define PG8_LDA(dst, b, h) do { _Pragma("unroll") for (int m = 0; m < 4; ++m) _Pragma("unroll") for (int k = 0; k < 2; ++k) dst[m][k] = *(const PG8_LAS bf16x8*)(lds + PG8_SA(b, h) + aoff + m * 2048 + k * 1024); } while (0)
; #define PG8_LDB(dst, b, h) do { _Pragma("unroll") for (int n = 0; n < 2; ++n) _Pragma("unroll") for (int k = 0; k < 2; ++k) dst[n][k] = *(const PG8_LAS bf16x8*)(lds + PG8_SB(b, h) + boff + n * 2048 + k * 1024); } while (0)
; #define PG8_SCHED __builtin_amdgcn_sched_barrier(0)
; template <class Epi, class Sched, bool ALIGN_EPI = false, bool SP2 = false>
; __device__ __forceinline__ void gemm_phase(PG8_LAS unsigned char* lds, const Gemm g, const Sched& S, const Epi& E, const int wave0) {
;     ...
;         const bool has_next = S.next(ui + 1, nxt);
;         const char* nA = has_next ? (const char*)g.A + (size_t)nxt.z * g.zsA + (size_t)nxt.pm * tstepA + (size_t)nxt.k0 * 2 : cA; const char* nB = has_next ? (const char*)g.Bt + (size_t)nxt.z * g.zsB + (size_t)nxt.pn * tstepB + (size_t)nxt.k0 * 2 : cB;
;         for (int t = 0; t < nt; t += 2) {
;             const bool last = (t == nt - 2);
;             const char* a1 = cA + (size_t)(t + 1) * kstep;
;             const char* a2 = last ? nA : cA + (size_t)(t + 2) * kstep; const char* b2 = last ? nB : cB + (size_t)(t + 2) * kstep;
;             const char* a3 = a2 + kstep; const char* b3 = b2 + kstep;
;             if (last && has_next) S.a_ready(nxt);
;             if constexpr (SP2) {
;             PG8_LDB(B0, 0, 0); PG8_LDB(B1, 0, 1); PG8_SCHED; PG8_LDA(At, 0, 0); PG8_STAGE(PG8_SA(1, 1), a1 + hstepA, voffA);
;     ...
;         for (int a = 0; a < 2; ++a)
; #pragma unroll
;             for (int b = 0; b < 2; ++b)
; #pragma unroll
;                 for (int m = 0; m < 4; ++m)
; #pragma unroll
;                     for (int n = 0; n < 2; ++n) acc[a][b][m][n] = (f32x4){0.f, 0.f, 0.f, 0.f};
.LBB0_1359:
	s_ashr_i32 s27, s26, 31
	s_lshl_b64 s[28:29], s[26:27], 20
	s_add_u32 s11, s20, s28
	s_addc_u32 s13, s21, s29
	s_add_u32 s28, s11, s18
	s_addc_u32 s29, s13, s19
	s_and_b64 s[18:19], s[2:3], exec
	s_cselect_b32 s11, s29, s17
	s_cselect_b32 s13, s28, s16
	s_add_u32 s0, s0, 0x80080
	s_addc_u32 s1, s1, 0
	s_add_u32 s15, s16, 0x100
	v_mov_b32_e32 v0, 0
	s_addc_u32 s27, s17, 0
	s_mov_b32 s41, -2
	v_mov_b32_e32 v1, v0
	v_mov_b64_e32 v[2:3], 0
	v_mov_b64_e32 v[4:5], 0
	v_mov_b64_e32 v[6:7], 0
	v_mov_b64_e32 v[8:9], 0
	v_mov_b64_e32 v[10:11], 0
	v_mov_b64_e32 v[12:13], 0
	v_mov_b64_e32 v[14:15], 0
	v_mov_b64_e32 v[24:25], 0
	v_mov_b64_e32 v[26:27], 0
	v_mov_b64_e32 v[28:29], 0
	v_mov_b64_e32 v[30:31], 0
	v_mov_b64_e32 v[40:41], 0
	v_mov_b64_e32 v[42:43], 0
	v_mov_b64_e32 v[44:45], 0
	v_mov_b64_e32 v[46:47], 0
	v_mov_b64_e32 v[16:17], 0
	v_mov_b64_e32 v[18:19], 0
	v_mov_b64_e32 v[20:21], 0
	v_mov_b64_e32 v[22:23], 0
	v_mov_b64_e32 v[32:33], 0
	v_mov_b64_e32 v[34:35], 0
	v_mov_b64_e32 v[36:37], 0
	v_mov_b64_e32 v[38:39], 0
	v_mov_b64_e32 v[48:49], 0
	v_mov_b64_e32 v[50:51], 0
	v_mov_b64_e32 v[52:53], 0
	v_mov_b64_e32 v[54:55], 0
	v_mov_b64_e32 v[56:57], 0
	v_mov_b64_e32 v[58:59], 0
	v_mov_b64_e32 v[60:61], 0
	v_mov_b64_e32 v[62:63], 0
	v_mov_b64_e32 v[66:67], 0
	v_mov_b64_e32 v[68:69], 0
	v_mov_b64_e32 v[70:71], 0
	v_mov_b64_e32 v[72:73], 0
	v_mov_b64_e32 v[74:75], 0
	v_mov_b64_e32 v[76:77], 0
	v_mov_b64_e32 v[78:79], 0
	v_mov_b64_e32 v[80:81], 0
	v_mov_b64_e32 v[90:91], 0
	v_mov_b64_e32 v[92:93], 0
	v_mov_b64_e32 v[94:95], 0
	v_mov_b64_e32 v[96:97], 0
	v_mov_b64_e32 v[106:107], 0
	v_mov_b64_e32 v[108:109], 0
	v_mov_b64_e32 v[110:111], 0
	v_mov_b64_e32 v[112:113], 0
	v_mov_b64_e32 v[82:83], 0
	v_mov_b64_e32 v[84:85], 0
	v_mov_b64_e32 v[86:87], 0
	v_mov_b64_e32 v[88:89], 0
	v_mov_b64_e32 v[98:99], 0
	v_mov_b64_e32 v[100:101], 0
	v_mov_b64_e32 v[102:103], 0
	v_mov_b64_e32 v[104:105], 0
	v_mov_b64_e32 v[114:115], 0
	v_mov_b64_e32 v[116:117], 0
	v_mov_b64_e32 v[118:119], 0
	v_mov_b64_e32 v[120:121], 0
	v_mov_b64_e32 v[122:123], 0
	v_mov_b64_e32 v[124:125], 0
	v_mov_b64_e32 v[126:127], 0
	v_mov_b64_e32 v[128:129], 0
	s_mov_b64 s[46:47], 0x80
	v_add_u32_e32 v252, 0x10000, v141
	v_add_u32_e32 v253, 0x14000, v141
	v_add_u32_e32 v254, 0x18000, v141
	v_add_u32_e32 v255, 0x1c000, v141
	v_readlane_b32 s46, v244, 63
	v_writelane_b32 v244, 0, 63
.LBB0_1360:
	s_add_u32 s16, s0, 0xfff80080
	s_addc_u32 s17, s1, -1
	s_add_i32 s42, 0, 0x10000
	s_cmp_eq_u32 s41, 12
	s_cselect_b32 s19, s5, s17
	s_cselect_b32 s18, s4, s16
	s_cselect_b32 s17, s11, s27
	s_cselect_b32 s16, s13, s15
	s_add_i32 s44, 0, 0x14000
	ds_read_b128 v[144:147], v252
	ds_read_b128 v[148:151], v252 offset:1024
	ds_read_b128 v[152:155], v252 offset:2048
	ds_read_b128 v[156:159], v252 offset:3072
	ds_read_b128 v[178:181], v253
	ds_read_b128 v[182:185], v253 offset:1024
	ds_read_b128 v[186:189], v253 offset:2048
	ds_read_b128 v[190:193], v253 offset:3072
	s_add_i32 m0, s23, 0xc000
	ds_read_b128 v[194:197], v143
	ds_read_b128 v[208:211], v143 offset:1024
	ds_read_b128 v[212:215], v143 offset:2048
	ds_read_b128 v[216:219], v143 offset:3072
	ds_read_b128 v[220:223], v143 offset:4096
	ds_read_b128 v[224:227], v143 offset:5120
	ds_read_b128 v[228:231], v143 offset:6144
	ds_read_b128 v[232:235], v143 offset:7168
	global_load_lds_dwordx4 v136, s[0:1]
	s_add_i32 m0, s23, 0xe000
	s_nop 0
	global_load_lds_dwordx4 v138, s[0:1]
	s_cmp_eq_u32 s46, 1
	s_cbranch_scc0 .Ldf2_0n
	s_waitcnt vmcnt(24)
	s_branch .Ldf2_0d

; #define PG8_STAGE(bufoff, gbase, voff) do { _Pragma("unroll") for (int _i = 0; _i < 2; ++_i) \
;         __builtin_amdgcn_global_load_lds((const unsigned*)((const char*)(gbase) + (voff)[_i]), (PG8_LAS unsigned*)(lds + (bufoff) + ldsw + _i * 8192), 16, 0, 0); } while (0)
; #define PG8_LDA(dst, b, h) do { _Pragma("unroll") for (int m = 0; m < 4; ++m) _Pragma("unroll") for (int k = 0; k < 2; ++k) dst[m][k] = *(const PG8_LAS bf16x8*)(lds + PG8_SA(b, h) + aoff + m * 2048 + k * 1024); } while (0)
; #define PG8_MMA(ai, bj, At, Bt) do { __builtin_amdgcn_s_setprio(1); _Pragma("unroll") for (int m = 0; m < 4; ++m) _Pragma("unroll") for (int n = 0; n < 2; ++n) _Pragma("unroll") for (int k = 0; k < 2; ++k) \
;         acc[ai][bj][m][n] = __builtin_amdgcn_mfma_f32_16x16x32_bf16(Bt[n][k], At[m][k], acc[ai][bj][m][n], 0, 0, 0); __builtin_amdgcn_s_setprio(0); } while (0)
; #define PG8_WAIT_V(n) asm volatile("s_waitcnt vmcnt(" #n ")" ::: "memory")
; #define PG8_WAIT_L(n) asm volatile("s_waitcnt lgkmcnt(" #n ")" ::: "memory")
; #define PG8_BAR __builtin_amdgcn_s_barrier()
; #define PG8_SCHED __builtin_amdgcn_sched_barrier(0)
; template <class Epi, class Sched, bool ALIGN_EPI = false, bool SP2 = false>
; __device__ __forceinline__ void gemm_phase(PG8_LAS unsigned char* lds, const Gemm g, const Sched& S, const Epi& E, const int wave0) {
;     ...
;             PG8_WAIT_V(8); PG8_WAIT_L(0); PG8_BAR; PG8_MMA(0, 0, At, B0); PG8_MMA(0, 1, At, B1); PG8_BAR; PG8_SCHED;
;             PG8_LDA(At, 0, 1); PG8_STAGE(PG8_SB(0, 0), b2, voffB); PG8_STAGE(PG8_SB(0, 1), b2 + hstepB, voffB); PG8_STAGE(PG8_SA(0, 0), a2, voffA);
;             PG8_WAIT_V(8); PG8_WAIT_L(0); PG8_BAR; PG8_MMA(1, 0, At, B0); PG8_MMA(1, 1, At, B1); PG8_BAR; PG8_SCHED;
.Ldf2_0d:
	s_waitcnt lgkmcnt(0)
	s_barrier
	s_setprio 1
	s_waitcnt lgkmcnt(0)
	v_mfma_f32_16x16x32_bf16 v[126:129], v[144:147], v[194:197], v[126:129]
	v_mfma_f32_16x16x32_bf16 v[122:125], v[152:155], v[194:197], v[122:125]
	v_mfma_f32_16x16x32_bf16 v[118:121], v[144:147], v[212:215], v[118:121]
	v_mfma_f32_16x16x32_bf16 v[114:117], v[152:155], v[212:215], v[114:117]
	v_mfma_f32_16x16x32_bf16 v[102:105], v[144:147], v[220:223], v[102:105]
	v_mfma_f32_16x16x32_bf16 v[98:101], v[152:155], v[220:223], v[98:101]
	v_mfma_f32_16x16x32_bf16 v[86:89], v[144:147], v[228:231], v[86:89]
	v_mfma_f32_16x16x32_bf16 v[82:85], v[152:155], v[228:231], v[82:85]
	v_mfma_f32_16x16x32_bf16 v[126:129], v[148:151], v[208:211], v[126:129]
	v_mfma_f32_16x16x32_bf16 v[122:125], v[156:159], v[208:211], v[122:125]
	v_mfma_f32_16x16x32_bf16 v[118:121], v[148:151], v[216:219], v[118:121]
	v_mfma_f32_16x16x32_bf16 v[114:117], v[156:159], v[216:219], v[114:117]
	v_mfma_f32_16x16x32_bf16 v[102:105], v[148:151], v[224:227], v[102:105]
	v_mfma_f32_16x16x32_bf16 v[98:101], v[156:159], v[224:227], v[98:101]
	v_mfma_f32_16x16x32_bf16 v[86:89], v[148:151], v[232:235], v[86:89]
	v_mfma_f32_16x16x32_bf16 v[82:85], v[156:159], v[232:235], v[82:85]
	s_setprio 0
	s_setprio 1
	v_mfma_f32_16x16x32_bf16 v[110:113], v[178:181], v[194:197], v[110:113]
	v_mfma_f32_16x16x32_bf16 v[106:109], v[186:189], v[194:197], v[106:109]
	v_mfma_f32_16x16x32_bf16 v[94:97], v[178:181], v[212:215], v[94:97]
	v_mfma_f32_16x16x32_bf16 v[90:93], v[186:189], v[212:215], v[90:93]
	v_mfma_f32_16x16x32_bf16 v[78:81], v[178:181], v[220:223], v[78:81]
	v_mfma_f32_16x16x32_bf16 v[74:77], v[186:189], v[220:223], v[74:77]
	v_mfma_f32_16x16x32_bf16 v[70:73], v[178:181], v[228:231], v[70:73]
	v_mfma_f32_16x16x32_bf16 v[66:69], v[186:189], v[228:231], v[66:69]
	v_mfma_f32_16x16x32_bf16 v[110:113], v[182:185], v[208:211], v[110:113]
	v_mfma_f32_16x16x32_bf16 v[106:109], v[190:193], v[208:211], v[106:109]
	v_mfma_f32_16x16x32_bf16 v[94:97], v[182:185], v[216:219], v[94:97]
	v_mfma_f32_16x16x32_bf16 v[90:93], v[190:193], v[216:219], v[90:93]
	v_mfma_f32_16x16x32_bf16 v[78:81], v[182:185], v[224:227], v[78:81]
	v_mfma_f32_16x16x32_bf16 v[74:77], v[190:193], v[224:227], v[74:77]
	v_mfma_f32_16x16x32_bf16 v[70:73], v[182:185], v[232:235], v[70:73]
	v_mfma_f32_16x16x32_bf16 v[66:69], v[190:193], v[232:235], v[66:69]
	s_setprio 0
	s_barrier
	s_add_i32 s42, s42, s22
	s_mov_b32 m0, s42
	ds_read_b128 v[194:197], v143 offset:16384
	ds_read_b128 v[208:211], v143 offset:17408
	ds_read_b128 v[212:215], v143 offset:18432
	ds_read_b128 v[216:219], v143 offset:19456
	ds_read_b128 v[220:223], v143 offset:20480
	ds_read_b128 v[224:227], v143 offset:21504
	ds_read_b128 v[228:231], v143 offset:22528
	ds_read_b128 v[232:235], v143 offset:23552
	global_load_lds_dwordx4 v64, s[16:17]
	s_add_i32 m0, s42, 0x2000
	s_add_u32 s42, s16, 0x80000
	s_addc_u32 s43, s17, 0
	s_add_i32 s44, s44, s22
	global_load_lds_dwordx4 v130, s[16:17]
	s_mov_b32 m0, s44
	s_mov_b64 s[100:101], s[18:19]
	global_load_lds_dwordx4 v64, s[42:43]
	s_add_i32 m0, s44, 0x2000
	s_nop 0
	global_load_lds_dwordx4 v130, s[42:43]
	s_mov_b32 m0, s23
	s_nop 0
	global_load_lds_dwordx4 v134, s[18:19]
	s_mov_b32 m0, s24
	s_nop 0
	global_load_lds_dwordx4 v132, s[18:19]
	s_cmp_eq_u32 s46, 1
	s_cbranch_scc0 .Ldf2_1n
	s_waitcnt vmcnt(24)
	s_mov_b32 s46, 0
	s_branch .Ldf2_1d

; #define PG8_STAGE(bufoff, gbase, voff) do { _Pragma("unroll") for (int _i = 0; _i < 2; ++_i) \
;         __builtin_amdgcn_global_load_lds((const unsigned*)((const char*)(gbase) + (voff)[_i]), (PG8_LAS unsigned*)(lds + (bufoff) + ldsw + _i * 8192), 16, 0, 0); } while (0)
; #define PG8_LDA(dst, b, h) do { _Pragma("unroll") for (int m = 0; m < 4; ++m) _Pragma("unroll") for (int k = 0; k < 2; ++k) dst[m][k] = *(const PG8_LAS bf16x8*)(lds + PG8_SA(b, h) + aoff + m * 2048 + k * 1024); } while (0)
; #define PG8_LDB(dst, b, h) do { _Pragma("unroll") for (int n = 0; n < 2; ++n) _Pragma("unroll") for (int k = 0; k < 2; ++k) dst[n][k] = *(const PG8_LAS bf16x8*)(lds + PG8_SB(b, h) + boff + n * 2048 + k * 1024); } while (0)
; #define PG8_MMA(ai, bj, At, Bt) do { __builtin_amdgcn_s_setprio(1); _Pragma("unroll") for (int m = 0; m < 4; ++m) _Pragma("unroll") for (int n = 0; n < 2; ++n) _Pragma("unroll") for (int k = 0; k < 2; ++k) \
;         acc[ai][bj][m][n] = __builtin_amdgcn_mfma_f32_16x16x32_bf16(Bt[n][k], At[m][k], acc[ai][bj][m][n], 0, 0, 0); __builtin_amdgcn_s_setprio(0); } while (0)
; #define PG8_WAIT_V(n) asm volatile("s_waitcnt vmcnt(" #n ")" ::: "memory")
; #define PG8_WAIT_L(n) asm volatile("s_waitcnt lgkmcnt(" #n ")" ::: "memory")
; #define PG8_BAR __builtin_amdgcn_s_barrier()
; #define PG8_SCHED __builtin_amdgcn_sched_barrier(0)
; template <class Epi, class Sched, bool ALIGN_EPI = false, bool SP2 = false>
; __device__ __forceinline__ void gemm_phase(PG8_LAS unsigned char* lds, const Gemm g, const Sched& S, const Epi& E, const int wave0) {
;     ...
;             PG8_WAIT_V(8); PG8_WAIT_L(0); PG8_BAR; PG8_MMA(1, 0, At, B0); PG8_MMA(1, 1, At, B1); PG8_BAR; PG8_SCHED;
;             PG8_LDB(B0, 1, 0); PG8_LDB(B1, 1, 1); PG8_SCHED; PG8_LDA(At, 1, 0); PG8_STAGE(PG8_SA(0, 1), a2 + hstepA, voffA);
;             PG8_WAIT_V(8); PG8_WAIT_L(0); PG8_BAR; PG8_MMA(0, 0, At, B0); PG8_MMA(0, 1, At, B1); PG8_BAR; PG8_SCHED;
.Ldf2_1d:
	s_waitcnt lgkmcnt(0)
	s_barrier
	s_setprio 1
	s_waitcnt lgkmcnt(0)
	v_mfma_f32_16x16x32_bf16 v[60:63], v[144:147], v[194:197], v[60:63]
	v_mfma_f32_16x16x32_bf16 v[56:59], v[152:155], v[194:197], v[56:59]
	v_mfma_f32_16x16x32_bf16 v[52:55], v[144:147], v[212:215], v[52:55]
	v_mfma_f32_16x16x32_bf16 v[48:51], v[152:155], v[212:215], v[48:51]
	v_mfma_f32_16x16x32_bf16 v[36:39], v[144:147], v[220:223], v[36:39]
	v_mfma_f32_16x16x32_bf16 v[32:35], v[152:155], v[220:223], v[32:35]
	v_mfma_f32_16x16x32_bf16 v[20:23], v[144:147], v[228:231], v[20:23]
	v_mfma_f32_16x16x32_bf16 v[16:19], v[152:155], v[228:231], v[16:19]
	v_mfma_f32_16x16x32_bf16 v[60:63], v[148:151], v[208:211], v[60:63]
	v_mfma_f32_16x16x32_bf16 v[56:59], v[156:159], v[208:211], v[56:59]
	v_mfma_f32_16x16x32_bf16 v[52:55], v[148:151], v[216:219], v[52:55]
	v_mfma_f32_16x16x32_bf16 v[48:51], v[156:159], v[216:219], v[48:51]
	v_mfma_f32_16x16x32_bf16 v[36:39], v[148:151], v[224:227], v[36:39]
	v_mfma_f32_16x16x32_bf16 v[32:35], v[156:159], v[224:227], v[32:35]
	v_mfma_f32_16x16x32_bf16 v[20:23], v[148:151], v[232:235], v[20:23]
	v_mfma_f32_16x16x32_bf16 v[16:19], v[156:159], v[232:235], v[16:19]
	s_setprio 0
	s_setprio 1
	v_mfma_f32_16x16x32_bf16 v[44:47], v[178:181], v[194:197], v[44:47]
	v_mfma_f32_16x16x32_bf16 v[40:43], v[186:189], v[194:197], v[40:43]
	v_mfma_f32_16x16x32_bf16 v[28:31], v[178:181], v[212:215], v[28:31]
	v_mfma_f32_16x16x32_bf16 v[24:27], v[186:189], v[212:215], v[24:27]
	v_mfma_f32_16x16x32_bf16 v[12:15], v[178:181], v[220:223], v[12:15]
	v_mfma_f32_16x16x32_bf16 v[8:11], v[186:189], v[220:223], v[8:11]
	v_mfma_f32_16x16x32_bf16 v[4:7], v[178:181], v[228:231], v[4:7]
	v_mfma_f32_16x16x32_bf16 v[0:3], v[186:189], v[228:231], v[0:3]
	v_mfma_f32_16x16x32_bf16 v[44:47], v[182:185], v[208:211], v[44:47]
	v_mfma_f32_16x16x32_bf16 v[40:43], v[190:193], v[208:211], v[40:43]
	v_mfma_f32_16x16x32_bf16 v[28:31], v[182:185], v[216:219], v[28:31]
	v_mfma_f32_16x16x32_bf16 v[24:27], v[190:193], v[216:219], v[24:27]
	v_mfma_f32_16x16x32_bf16 v[12:15], v[182:185], v[224:227], v[12:15]
	v_mfma_f32_16x16x32_bf16 v[8:11], v[190:193], v[224:227], v[8:11]
	v_mfma_f32_16x16x32_bf16 v[4:7], v[182:185], v[232:235], v[4:7]
	v_mfma_f32_16x16x32_bf16 v[0:3], v[190:193], v[232:235], v[0:3]
	s_setprio 0
	s_barrier
	s_add_i32 s42, 0, 0x18000
	s_add_i32 s43, 0, 0x1c000
	ds_read_b128 v[144:147], v254
	ds_read_b128 v[148:151], v254 offset:1024
	ds_read_b128 v[152:155], v254 offset:2048
	ds_read_b128 v[156:159], v254 offset:3072
	ds_read_b128 v[178:181], v255
	ds_read_b128 v[182:185], v255 offset:1024
	ds_read_b128 v[186:189], v255 offset:2048
	ds_read_b128 v[190:193], v255 offset:3072
	s_add_u32 s18, s18, 0x80000
	s_addc_u32 s19, s19, 0
	s_mov_b32 m0, s25
	ds_read_b128 v[194:197], v143 offset:32768
	ds_read_b128 v[208:211], v143 offset:33792
	ds_read_b128 v[212:215], v143 offset:34816
	ds_read_b128 v[216:219], v143 offset:35840
	ds_read_b128 v[220:223], v143 offset:36864
	ds_read_b128 v[224:227], v143 offset:37888
	ds_read_b128 v[228:231], v143 offset:38912
	ds_read_b128 v[232:235], v143 offset:39936
	global_load_lds_dwordx4 v134, s[18:19]
	s_mov_b32 m0, s33
	s_nop 0
	global_load_lds_dwordx4 v132, s[18:19]
	s_waitcnt vmcnt(8)
	s_waitcnt lgkmcnt(0)
	s_barrier
	s_setprio 1
	s_waitcnt lgkmcnt(0)
	v_mfma_f32_16x16x32_bf16 v[126:129], v[144:147], v[194:197], v[126:129]
	v_mfma_f32_16x16x32_bf16 v[122:125], v[152:155], v[194:197], v[122:125]
	v_mfma_f32_16x16x32_bf16 v[118:121], v[144:147], v[212:215], v[118:121]
	v_mfma_f32_16x16x32_bf16 v[114:117], v[152:155], v[212:215], v[114:117]
	v_mfma_f32_16x16x32_bf16 v[102:105], v[144:147], v[220:223], v[102:105]
	v_mfma_f32_16x16x32_bf16 v[98:101], v[152:155], v[220:223], v[98:101]
	v_mfma_f32_16x16x32_bf16 v[86:89], v[144:147], v[228:231], v[86:89]
	v_mfma_f32_16x16x32_bf16 v[82:85], v[152:155], v[228:231], v[82:85]
	v_mfma_f32_16x16x32_bf16 v[126:129], v[148:151], v[208:211], v[126:129]
	v_mfma_f32_16x16x32_bf16 v[122:125], v[156:159], v[208:211], v[122:125]
	v_mfma_f32_16x16x32_bf16 v[118:121], v[148:151], v[216:219], v[118:121]
	v_mfma_f32_16x16x32_bf16 v[114:117], v[156:159], v[216:219], v[114:117]
	v_mfma_f32_16x16x32_bf16 v[102:105], v[148:151], v[224:227], v[102:105]
	v_mfma_f32_16x16x32_bf16 v[98:101], v[156:159], v[224:227], v[98:101]
	v_mfma_f32_16x16x32_bf16 v[86:89], v[148:151], v[232:235], v[86:89]
	v_mfma_f32_16x16x32_bf16 v[82:85], v[156:159], v[232:235], v[82:85]
	s_setprio 0
	s_setprio 1
	v_mfma_f32_16x16x32_bf16 v[110:113], v[178:181], v[194:197], v[110:113]
	v_mfma_f32_16x16x32_bf16 v[106:109], v[186:189], v[194:197], v[106:109]
	v_mfma_f32_16x16x32_bf16 v[94:97], v[178:181], v[212:215], v[94:97]
	v_mfma_f32_16x16x32_bf16 v[90:93], v[186:189], v[212:215], v[90:93]
	v_mfma_f32_16x16x32_bf16 v[78:81], v[178:181], v[220:223], v[78:81]
	v_mfma_f32_16x16x32_bf16 v[74:77], v[186:189], v[220:223], v[74:77]
	v_mfma_f32_16x16x32_bf16 v[70:73], v[178:181], v[228:231], v[70:73]
	v_mfma_f32_16x16x32_bf16 v[66:69], v[186:189], v[228:231], v[66:69]
	v_mfma_f32_16x16x32_bf16 v[110:113], v[182:185], v[208:211], v[110:113]
	v_mfma_f32_16x16x32_bf16 v[106:109], v[190:193], v[208:211], v[106:109]
	v_mfma_f32_16x16x32_bf16 v[94:97], v[182:185], v[216:219], v[94:97]
	v_mfma_f32_16x16x32_bf16 v[90:93], v[190:193], v[216:219], v[90:93]
	v_mfma_f32_16x16x32_bf16 v[78:81], v[182:185], v[224:227], v[78:81]
	v_mfma_f32_16x16x32_bf16 v[74:77], v[190:193], v[224:227], v[74:77]
	v_mfma_f32_16x16x32_bf16 v[70:73], v[182:185], v[232:235], v[70:73]
	v_mfma_f32_16x16x32_bf16 v[66:69], v[190:193], v[232:235], v[66:69]
	s_setprio 0
	s_barrier
; #define PG8_STAGE(bufoff, gbase, voff) do { _Pragma("unroll") for (int _i = 0; _i < 2; ++_i) \
;         __builtin_amdgcn_global_load_lds((const unsigned*)((const char*)(gbase) + (voff)[_i]), (PG8_LAS unsigned*)(lds + (bufoff) + ldsw + _i * 8192), 16, 0, 0); } while (0)
; #define PG8_LDA(dst, b, h) do { _Pragma("unroll") for (int m = 0; m < 4; ++m) _Pragma("unroll") for (int k = 0; k < 2; ++k) dst[m][k] = *(const PG8_LAS bf16x8*)(lds + PG8_SA(b, h) + aoff + m * 2048 + k * 1024); } while (0)
; #define PG8_LDB(dst, b, h) do { _Pragma("unroll") for (int n = 0; n < 2; ++n) _Pragma("unroll") for (int k = 0; k < 2; ++k) dst[n][k] = *(const PG8_LAS bf16x8*)(lds + PG8_SB(b, h) + boff + n * 2048 + k * 1024); } while (0)
; #define PG8_MMA(ai, bj, At, Bt) do { __builtin_amdgcn_s_setprio(1); _Pragma("unroll") for (int m = 0; m < 4; ++m) _Pragma("unroll") for (int n = 0; n < 2; ++n) _Pragma("unroll") for (int k = 0; k < 2; ++k) \
;         acc[ai][bj][m][n] = __builtin_amdgcn_mfma_f32_16x16x32_bf16(Bt[n][k], At[m][k], acc[ai][bj][m][n], 0, 0, 0); __builtin_amdgcn_s_setprio(0); } while (0)
; #define PG8_WAIT_V(n) asm volatile("s_waitcnt vmcnt(" #n ")" ::: "memory")
; #define PG8_WAIT_L(n) asm volatile("s_waitcnt lgkmcnt(" #n ")" ::: "memory")
; #define PG8_BAR __builtin_amdgcn_s_barrier()
; #define PG8_SCHED __builtin_amdgcn_sched_barrier(0)
; template <class Epi, class Sched, bool ALIGN_EPI = false, bool SP2 = false>
; __device__ __forceinline__ void gemm_phase(PG8_LAS unsigned char* lds, const Gemm g, const Sched& S, const Epi& E, const int wave0) {
;     ...
;             PG8_LDB(B0, 1, 0); PG8_LDB(B1, 1, 1); PG8_SCHED; PG8_LDA(At, 1, 0); PG8_STAGE(PG8_SA(0, 1), a2 + hstepA, voffA);
;             PG8_WAIT_V(8); PG8_WAIT_L(0); PG8_BAR; PG8_MMA(0, 0, At, B0); PG8_MMA(0, 1, At, B1); PG8_BAR; PG8_SCHED;
;             PG8_LDA(At, 1, 1); PG8_STAGE(PG8_SB(1, 0), b3, voffB); PG8_STAGE(PG8_SB(1, 1), b3 + hstepB, voffB); PG8_STAGE(PG8_SA(1, 0), a3, voffA);
;             PG8_WAIT_V(8); PG8_WAIT_L(0); PG8_BAR; PG8_MMA(1, 0, At, B0); PG8_MMA(1, 1, At, B1); PG8_BAR; PG8_SCHED;
	s_add_i32 s18, s42, s22
	s_add_u32 s46, s16, 0x80
	s_addc_u32 s47, s17, 0
	s_mov_b32 m0, s18
	ds_read_b128 v[194:197], v143 offset:49152
	ds_read_b128 v[208:211], v143 offset:50176
	ds_read_b128 v[212:215], v143 offset:51200
	ds_read_b128 v[216:219], v143 offset:52224
	ds_read_b128 v[220:223], v143 offset:53248
	ds_read_b128 v[224:227], v143 offset:54272
	ds_read_b128 v[228:231], v143 offset:55296
	ds_read_b128 v[232:235], v143 offset:56320
	global_load_lds_dwordx4 v64, s[46:47]
	s_add_i32 m0, s18, 0x2000
	s_add_u32 s16, s16, 0x80080
	s_addc_u32 s17, s17, 0
	s_add_i32 s18, s43, s22
	global_load_lds_dwordx4 v130, s[46:47]
	s_mov_b32 m0, s18
	s_nop 0
	global_load_lds_dwordx4 v64, s[16:17]
	s_add_i32 m0, s18, 0x2000
	s_nop 0
	global_load_lds_dwordx4 v130, s[16:17]
	s_add_u32 s100, s100, 0x80
	s_addc_u32 s101, s101, 0
	s_mov_b32 m0, s34
	s_nop 0
	global_load_lds_dwordx4 v134, s[100:101]
	s_mov_b32 m0, s35
	s_nop 0
	global_load_lds_dwordx4 v132, s[100:101]
	s_waitcnt vmcnt(8)
	s_waitcnt lgkmcnt(0)
	s_barrier
	s_setprio 1
	s_waitcnt lgkmcnt(0)
	v_mfma_f32_16x16x32_bf16 v[60:63], v[144:147], v[194:197], v[60:63]
	v_mfma_f32_16x16x32_bf16 v[56:59], v[152:155], v[194:197], v[56:59]
	v_mfma_f32_16x16x32_bf16 v[52:55], v[144:147], v[212:215], v[52:55]
	v_mfma_f32_16x16x32_bf16 v[48:51], v[152:155], v[212:215], v[48:51]
	v_mfma_f32_16x16x32_bf16 v[36:39], v[144:147], v[220:223], v[36:39]
	v_mfma_f32_16x16x32_bf16 v[32:35], v[152:155], v[220:223], v[32:35]
	v_mfma_f32_16x16x32_bf16 v[20:23], v[144:147], v[228:231], v[20:23]
	v_mfma_f32_16x16x32_bf16 v[16:19], v[152:155], v[228:231], v[16:19]
	v_mfma_f32_16x16x32_bf16 v[60:63], v[148:151], v[208:211], v[60:63]
	v_mfma_f32_16x16x32_bf16 v[56:59], v[156:159], v[208:211], v[56:59]
	v_mfma_f32_16x16x32_bf16 v[52:55], v[148:151], v[216:219], v[52:55]
	v_mfma_f32_16x16x32_bf16 v[48:51], v[156:159], v[216:219], v[48:51]
	v_mfma_f32_16x16x32_bf16 v[36:39], v[148:151], v[224:227], v[36:39]
	v_mfma_f32_16x16x32_bf16 v[32:35], v[156:159], v[224:227], v[32:35]
	v_mfma_f32_16x16x32_bf16 v[20:23], v[148:151], v[232:235], v[20:23]
	v_mfma_f32_16x16x32_bf16 v[16:19], v[156:159], v[232:235], v[16:19]
	s_setprio 0
	s_setprio 1
	v_mfma_f32_16x16x32_bf16 v[44:47], v[178:181], v[194:197], v[44:47]
	v_mfma_f32_16x16x32_bf16 v[40:43], v[186:189], v[194:197], v[40:43]
	v_mfma_f32_16x16x32_bf16 v[28:31], v[178:181], v[212:215], v[28:31]
	v_mfma_f32_16x16x32_bf16 v[24:27], v[186:189], v[212:215], v[24:27]
	v_mfma_f32_16x16x32_bf16 v[12:15], v[178:181], v[220:223], v[12:15]
	v_mfma_f32_16x16x32_bf16 v[8:11], v[186:189], v[220:223], v[8:11]
	v_mfma_f32_16x16x32_bf16 v[4:7], v[178:181], v[228:231], v[4:7]
	v_mfma_f32_16x16x32_bf16 v[0:3], v[186:189], v[228:231], v[0:3]
	v_mfma_f32_16x16x32_bf16 v[44:47], v[182:185], v[208:211], v[44:47]
	v_mfma_f32_16x16x32_bf16 v[40:43], v[190:193], v[208:211], v[40:43]
	v_mfma_f32_16x16x32_bf16 v[28:31], v[182:185], v[216:219], v[28:31]
	v_mfma_f32_16x16x32_bf16 v[24:27], v[190:193], v[216:219], v[24:27]
	v_mfma_f32_16x16x32_bf16 v[12:15], v[182:185], v[224:227], v[12:15]
	v_mfma_f32_16x16x32_bf16 v[8:11], v[190:193], v[224:227], v[8:11]
	v_mfma_f32_16x16x32_bf16 v[4:7], v[182:185], v[232:235], v[4:7]
	v_mfma_f32_16x16x32_bf16 v[0:3], v[190:193], v[232:235], v[0:3]
	s_setprio 0
	s_barrier
	s_add_i32 s41, s41, 2
	s_add_u32 s0, s0, 0x100
	s_addc_u32 s1, s1, 0
	s_add_u32 s15, s15, 0x100
	s_addc_u32 s27, s27, 0
	s_cmp_gt_u32 s41, 13
	s_cbranch_scc0 .LBB0_1360
	s_mov_b64 s[46:47], 0x80
	s_and_b64 vcc, exec, s[8:9]
	s_cbranch_vccz .LBB0_1363
	s_barrier
; __device__ __forceinline__ unsigned cvt_pk_bf16(float lo, float hi) { const f32x2_t v = {lo, hi}; const bf16x2_t b = __builtin_convertvector(v, bf16x2_t); return __builtin_bit_cast(unsigned, b); }
;     __device__ __forceinline__ void operator()(const f32x4 (&acc)[2][2][4][2], const Unit& u, int wr, int wc, int fr, int fq) const {
;         const int row0 = u.pm * BM + wr * 64 + fr; const int col0 = u.pn * BM + wc * 32 + 8 * fq;
; #pragma unroll
;         for (int ai = 0; ai < 2; ++ai)
; #pragma unroll
;             for (int m = 0; m < 4; ++m) { bf16_t* rowp = O + (size_t)u.zo * zsO + (size_t)(row0 + ai * HALF + m * 16) * ldc + col0;
; #pragma unroll
;                 for (int bj = 0; bj < 2; ++bj) { f32x4 v0 = acc[ai][bj][m][0], v1 = acc[ai][bj][m][1];
;                     if (ACT == 2) {
; #pragma unroll
;                         for (int j = 0; j < 4; ++j) { const float a = fmaxf(v0[j], 0.f), b = fmaxf(v1[j], 0.f); v0[j] = a * a; v1[j] = b * b; } }
;                     u32x4 w; w.x = cvt_pk_bf16(v0[0], v0[1]); w.y = cvt_pk_bf16(v0[2], v0[3]); w.z = cvt_pk_bf16(v1[0], v1[1]); w.w = cvt_pk_bf16(v1[2], v1[3]);
;                     *(u32x4*)(rowp + bj * HALF) = w; } }
.LBB0_1363:
	v_lshl_or_b32 v144, s31, 8, v142
	s_ashr_i32 s31, s30, 31
	v_lshl_add_u32 v146, s40, 8, v140
	s_lshl_b64 s[0:1], s[30:31], 22
	v_readlane_b32 s11, v247, 13
	s_add_u32 s0, s11, s0
	v_readlane_b32 s11, v247, 14
	v_ashrrev_i32_e32 v147, 31, v146
	v_cvt_pk_bf16_f32 v110, v110, v111
	v_cvt_pk_bf16_f32 v111, v112, v113
	v_cvt_pk_bf16_f32 v112, v106, v107
	v_or_b32_e32 v106, 16, v146
	v_cvt_pk_bf16_f32 v94, v94, v95
	v_cvt_pk_bf16_f32 v95, v96, v97
	v_cvt_pk_bf16_f32 v96, v90, v91
	v_or_b32_e32 v90, 32, v146
	v_cvt_pk_bf16_f32 v78, v78, v79
	v_cvt_pk_bf16_f32 v79, v80, v81
	v_cvt_pk_bf16_f32 v80, v74, v75
	v_or_b32_e32 v74, 48, v146
	v_ashrrev_i32_e32 v145, 31, v144
	s_addc_u32 s1, s11, s1
	v_lshlrev_b64 v[148:149], 12, v[146:147]
	v_ashrrev_i32_e32 v107, 31, v106
	v_ashrrev_i32_e32 v91, 31, v90
	v_ashrrev_i32_e32 v75, 31, v74
	v_lshl_add_u64 v[148:149], s[0:1], 0, v[148:149]
	v_lshlrev_b64 v[144:145], 1, v[144:145]
	v_lshlrev_b64 v[106:107], 12, v[106:107]
	v_lshlrev_b64 v[90:91], 12, v[90:91]
	v_lshlrev_b64 v[74:75], 12, v[74:75]
	v_lshl_add_u64 v[148:149], v[148:149], 0, v[144:145]
	v_lshl_add_u64 v[106:107], s[0:1], 0, v[106:107]
	v_lshl_add_u64 v[90:91], s[0:1], 0, v[90:91]
	v_lshl_add_u64 v[74:75], s[0:1], 0, v[74:75]
	s_mov_b64 s[0:1], 0x80000
	v_cvt_pk_bf16_f32 v70, v70, v71
	v_cvt_pk_bf16_f32 v71, v72, v73
	v_cvt_pk_bf16_f32 v72, v66, v67
	v_lshl_add_u64 v[66:67], v[148:149], 0, s[0:1]
	s_mov_b32 s0, 0x80000
	v_cvt_pk_bf16_f32 v60, v60, v61
	v_cvt_pk_bf16_f32 v61, v62, v63
	v_cvt_pk_bf16_f32 v62, v56, v57
	v_add_co_u32_e32 v56, vcc, s0, v148
	v_cvt_pk_bf16_f32 v44, v44, v45
	v_cvt_pk_bf16_f32 v45, v46, v47
	v_cvt_pk_bf16_f32 v46, v40, v41
	v_cvt_pk_bf16_f32 v47, v42, v43
	s_mov_b64 s[0:1], 0x90000
	v_addc_co_u32_e32 v57, vcc, 0, v149, vcc
	global_store_dwordx4 v[66:67], v[44:47], off offset:256
	v_cvt_pk_bf16_f32 v28, v28, v29
	v_cvt_pk_bf16_f32 v29, v30, v31
	v_lshl_add_u64 v[44:45], v[148:149], 0, s[0:1]
	s_mov_b32 s0, 0x90000
	v_add_co_u32_e32 v46, vcc, s0, v148
	v_cvt_pk_bf16_f32 v30, v24, v25
	v_cvt_pk_bf16_f32 v31, v26, v27
	s_mov_b64 s[0:1], 0xa0000
	v_addc_co_u32_e32 v47, vcc, 0, v149, vcc
	global_store_dwordx4 v[44:45], v[28:31], off offset:256
	v_cvt_pk_bf16_f32 v12, v12, v13
	v_cvt_pk_bf16_f32 v13, v14, v15
	v_lshl_add_u64 v[28:29], v[148:149], 0, s[0:1]
	s_mov_b32 s0, 0xa0000
	v_add_co_u32_e32 v30, vcc, s0, v148
	v_cvt_pk_bf16_f32 v14, v8, v9
	v_cvt_pk_bf16_f32 v15, v10, v11
	s_mov_b64 s[0:1], 0xb0000
	v_cvt_pk_bf16_f32 v113, v108, v109
	v_addc_co_u32_e32 v31, vcc, 0, v149, vcc
	global_store_dwordx4 v[28:29], v[12:15], off offset:256
	global_store_dwordx4 v[148:149], v[110:113], off offset:256
	v_cvt_pk_bf16_f32 v97, v92, v93
	v_lshl_add_u64 v[12:13], v[148:149], 0, s[0:1]
	s_mov_b32 s0, 0xb0000
	v_lshl_add_u64 v[110:111], v[106:107], 0, v[144:145]
	v_add_co_u32_e32 v14, vcc, s0, v148
	global_store_dwordx4 v[110:111], v[94:97], off offset:256
	v_cvt_pk_bf16_f32 v81, v76, v77
	v_addc_co_u32_e32 v15, vcc, 0, v149, vcc
	v_lshl_add_u64 v[94:95], v[90:91], 0, v[144:145]
	v_cvt_pk_bf16_f32 v126, v126, v127
	v_cvt_pk_bf16_f32 v127, v128, v129
	v_cvt_pk_bf16_f32 v128, v122, v123
	v_cvt_pk_bf16_f32 v129, v124, v125
	v_cvt_pk_bf16_f32 v106, v118, v119
	v_cvt_pk_bf16_f32 v107, v120, v121
	v_cvt_pk_bf16_f32 v108, v114, v115
	v_cvt_pk_bf16_f32 v109, v116, v117
	v_cvt_pk_bf16_f32 v90, v102, v103
	v_cvt_pk_bf16_f32 v91, v104, v105
	v_cvt_pk_bf16_f32 v92, v98, v99
	v_cvt_pk_bf16_f32 v93, v100, v101
	global_store_dwordx4 v[94:95], v[78:81], off offset:256
	v_cvt_pk_bf16_f32 v76, v82, v83
	v_cvt_pk_bf16_f32 v77, v84, v85
	v_lshl_add_u64 v[78:79], v[74:75], 0, v[144:145]
	v_cvt_pk_bf16_f32 v74, v86, v87
	v_cvt_pk_bf16_f32 v75, v88, v89
	v_cvt_pk_bf16_f32 v73, v68, v69
	v_cvt_pk_bf16_f32 v63, v58, v59
	v_cvt_pk_bf16_f32 v40, v52, v53
	v_cvt_pk_bf16_f32 v41, v54, v55
	v_cvt_pk_bf16_f32 v42, v48, v49
	v_cvt_pk_bf16_f32 v43, v50, v51
	v_cvt_pk_bf16_f32 v24, v36, v37
	v_cvt_pk_bf16_f32 v25, v38, v39
	v_cvt_pk_bf16_f32 v26, v32, v33
	v_cvt_pk_bf16_f32 v27, v34, v35
	v_cvt_pk_bf16_f32 v8, v20, v21
	v_cvt_pk_bf16_f32 v9, v22, v23
	v_cvt_pk_bf16_f32 v10, v16, v17
	v_cvt_pk_bf16_f32 v11, v18, v19
	v_cvt_pk_bf16_f32 v4, v4, v5
	v_cvt_pk_bf16_f32 v5, v6, v7
	v_cvt_pk_bf16_f32 v6, v0, v1
	v_cvt_pk_bf16_f32 v7, v2, v3
	s_andn2_b64 vcc, exec, s[2:3]
	s_mov_b64 s[0:1], -1
	global_store_dwordx4 v[148:149], v[126:129], off
	global_store_dwordx4 v[110:111], v[106:109], off
	global_store_dwordx4 v[94:95], v[90:93], off
	global_store_dwordx4 v[78:79], v[74:77], off
	global_store_dwordx4 v[78:79], v[70:73], off offset:256
	global_store_dwordx4 v[56:57], v[60:63], off
	global_store_dwordx4 v[46:47], v[40:43], off
	global_store_dwordx4 v[30:31], v[24:27], off
	global_store_dwordx4 v[14:15], v[8:11], off
	global_store_dwordx4 v[12:13], v[4:7], off offset:256
	v_writelane_b32 v244, 1, 63
	s_cbranch_vccnz .LBB0_1354
	s_andn2_b64 vcc, exec, s[6:7]
	s_cbranch_vccnz .LBB0_1353
	s_barrier
	s_branch .LBB0_1353

; #define PG8_STAGE(bufoff, gbase, voff) do { _Pragma("unroll") for (int _i = 0; _i < 2; ++_i) \
;         __builtin_amdgcn_global_load_lds((const unsigned*)((const char*)(gbase) + (voff)[_i]), (PG8_LAS unsigned*)(lds + (bufoff) + ldsw + _i * 8192), 16, 0, 0); } while (0)
; #define PG8_WAIT_V(n) asm volatile("s_waitcnt vmcnt(" #n ")" ::: "memory")
; #define PG8_BAR __builtin_amdgcn_s_barrier()
; template <class Epi, class Sched, bool ALIGN_EPI = false, bool SP2 = false>
; __device__ __forceinline__ void gemm_phase(PG8_LAS unsigned char* lds, const Gemm g, const Sched& S, const Epi& E, const int wave0) {
;     ...
;     if constexpr (SP2) {
;         PG8_STAGE(PG8_SB(0, 0), cB, voffB); PG8_STAGE(PG8_SB(0, 1), cB + hstepB, voffB); PG8_STAGE(PG8_SA(0, 0), cA, voffA); PG8_STAGE(PG8_SA(0, 1), cA + hstepA, voffA);
;         if (wr == 1) PG8_BAR;
;         PG8_WAIT_V(2); PG8_BAR;
;         PG8_STAGE(PG8_SB(1, 0), cB + kstep, voffB); PG8_STAGE(PG8_SA(1, 0), cA + kstep, voffA); PG8_STAGE(PG8_SB(1, 1), cB + hstepB + kstep, voffB);
;         PG8_WAIT_V(6); PG8_BAR;
.LBB0_1565:
	v_lshrrev_b32_e32 v16, 1, v14
	v_and_b32_e32 v16, 24, v16
	s_lshl_b32 s5, s5, 5
	v_and_b32_e32 v15, 15, v14
	v_lshlrev_b32_e32 v17, 1, v16
	v_lshlrev_b32_e32 v14, 2, v14
	s_and_b32 s8, s5, 0x60
	s_add_i32 m0, s15, 0x18000
	v_lshl_add_u64 v[6:7], v[6:7], 0, s[36:37]
	v_lshl_or_b32 v144, s6, 6, v15
	v_lshl_or_b32 v15, v15, 6, v17
	s_lshl_b32 s6, s6, 13
	v_and_b32_e32 v14, 32, v14
	s_lshl_b32 s5, s8, 7
	s_waitcnt vmcnt(2)
	s_barrier
	global_load_lds_dwordx4 v[6:7], off
	v_lshl_add_u64 v[4:5], v[4:5], 0, s[36:37]
	s_add_i32 m0, s15, 0x1a000
	s_add_i32 s31, s15, 0x8000
	s_add_i32 s34, s15, 0xa000
	v_bitop3_b32 v17, v15, s6, v14 bitop3:0xde
	global_load_lds_dwordx4 v[4:5], off
	v_lshl_add_u64 v[0:1], v[0:1], 0, s[36:37]
	s_mov_b32 m0, s31
	s_add_u32 s6, s16, 0x80080
	global_load_lds_dwordx4 v[0:1], off
	v_lshl_add_u64 v[0:1], v[2:3], 0, s[36:37]
	s_mov_b32 m0, s34
	s_addc_u32 s7, s17, 0
	global_load_lds_dwordx4 v[0:1], off
	s_add_i32 m0, s15, 0x1c000
	v_lshl_add_u64 v[0:1], s[6:7], 0, v[64:65]
	global_load_lds_dwordx4 v[0:1], off
	v_lshl_add_u64 v[0:1], s[6:7], 0, v[130:131]
	s_add_i32 m0, s15, 0x1e000
	s_cmpk_lt_u32 s4, 0x100
	global_load_lds_dwordx4 v[0:1], off
	v_lshlrev_b32_e32 v0, 15, v12
	v_and_b32_e32 v0, 0xffff0000, v0
	v_lshl_add_u32 v0, v11, 12, v0
	v_and_b32_e32 v1, 1, v12
	v_lshl_or_b32 v0, v1, 6, v0
	v_lshl_add_u32 v136, v13, 1, v0
	v_lshlrev_b32_e32 v0, 15, v8
	v_and_b32_e32 v0, 0xffff0000, v0
	v_writelane_b32 v244, 0, 63
	s_waitcnt vmcnt(6)
	v_lshl_add_u32 v0, v9, 12, v0
	v_and_b32_e32 v1, 1, v8
	v_lshl_or_b32 v0, v1, 6, v0
	v_bitop3_b32 v145, v15, s5, v14 bitop3:0xde
	s_cselect_b64 s[4:5], -1, 0
	v_or_b32_e32 v146, s8, v16
	v_mov_b32_e32 v137, v65
	v_lshl_add_u32 v138, v10, 1, v0
	v_mov_b32_e32 v139, v65
	s_mov_b32 s35, 0
	v_add_u32_e32 v147, 0, v17
	s_barrier
	s_branch .LBB0_1568

;     __host__ __device__ bool next(int i, Unit& u) const { return tile((long)i * G + c, u); }
;     __host__ __device__ bool next(int i, Unit& u) const { if (!tile((long)(i / NZ) * G + c, u)) return false; u.z = i % NZ; return true; }
; #define PG8_STAGE(bufoff, gbase, voff) do { _Pragma("unroll") for (int _i = 0; _i < 2; ++_i) \
;         __builtin_amdgcn_global_load_lds((const unsigned*)((const char*)(gbase) + (voff)[_i]), (PG8_LAS unsigned*)(lds + (bufoff) + ldsw + _i * 8192), 16, 0, 0); } while (0)
; #define PG8_LDA(dst, b, h) do { _Pragma("unroll") for (int m = 0; m < 4; ++m) _Pragma("unroll") for (int k = 0; k < 2; ++k) dst[m][k] = *(const PG8_LAS bf16x8*)(lds + PG8_SA(b, h) + aoff + m * 2048 + k * 1024); } while (0)
; #define PG8_WAIT_V(n) asm volatile("s_waitcnt vmcnt(" #n ")" ::: "memory")
; template <class Epi, class Sched, bool ALIGN_EPI = false, bool SP2 = false>
; __device__ __forceinline__ void gemm_phase(PG8_LAS unsigned char* lds, const Gemm g, const Sched& S, const Epi& E, const int wave0) {
;     ...
;         const bool has_next = S.next(ui + 1, nxt);
;         const char* nA = has_next ? (const char*)g.A + (size_t)nxt.z * g.zsA + (size_t)nxt.pm * tstepA + (size_t)nxt.k0 * 2 : cA; const char* nB = has_next ? (const char*)g.Bt + (size_t)nxt.z * g.zsB + (size_t)nxt.pn * tstepB + (size_t)nxt.k0 * 2 : cB;
;         for (int t = 0; t < nt; t += 2) {
;             const bool last = (t == nt - 2);
;             const char* a1 = cA + (size_t)(t + 1) * kstep;
;             const char* a2 = last ? nA : cA + (size_t)(t + 2) * kstep; const char* b2 = last ? nB : cB + (size_t)(t + 2) * kstep;
;             const char* a3 = a2 + kstep; const char* b3 = b2 + kstep;
;             if (last && has_next) S.a_ready(nxt);
;             if constexpr (SP2) {
;             PG8_LDB(B0, 0, 0); PG8_LDB(B1, 0, 1); PG8_SCHED; PG8_LDA(At, 0, 0); PG8_STAGE(PG8_SA(1, 1), a1 + hstepA, voffA);
;             PG8_WAIT_V(8); PG8_WAIT_L(0); PG8_BAR; PG8_MMA(0, 0, At, B0); PG8_MMA(0, 1, At, B1); PG8_BAR; PG8_SCHED;
;     ...
; #pragma unroll
;         for (int a = 0; a < 2; ++a)
; #pragma unroll
;             for (int b = 0; b < 2; ++b)
; #pragma unroll
;                 for (int m = 0; m < 4; ++m)
; #pragma unroll
;                     for (int n = 0; n < 2; ++n) acc[a][b][m][n] = (f32x4){0.f, 0.f, 0.f, 0.f};
;         cur = nxt; cA = nA; cB = nB; ++ui;
.LBB0_1570:
	s_ashr_i32 s9, s8, 31
	s_lshl_b64 s[10:11], s[8:9], 20
	v_readlane_b32 s12, v245, 1
	v_readlane_b32 s13, v245, 2
	s_add_u32 s10, s12, s10
	s_addc_u32 s11, s13, s11
	s_and_b64 s[12:13], s[42:43], exec
	s_cselect_b32 s9, s11, s1
	s_cselect_b32 s33, s10, s0
	s_ashr_i32 s7, s6, 31
	s_lshl_b64 s[12:13], s[6:7], 20
	s_add_u32 s12, s20, s12
	s_addc_u32 s13, s21, s13
	s_and_b64 s[18:19], s[42:43], exec
	s_cselect_b32 s7, s13, s17
	s_cselect_b32 s36, s12, s16
	s_add_u32 s0, s0, 0x80080
	s_addc_u32 s1, s1, 0
	s_add_u32 s37, s16, 0x100
	v_mov_b32_e32 v0, 0
	s_addc_u32 s44, s17, 0
	s_mov_b32 s45, -2
	v_mov_b32_e32 v1, v0
	v_mov_b64_e32 v[2:3], 0
	v_mov_b64_e32 v[4:5], 0
	v_mov_b64_e32 v[6:7], 0
	v_mov_b64_e32 v[16:17], 0
	v_mov_b64_e32 v[18:19], 0
	v_mov_b64_e32 v[20:21], 0
	v_mov_b64_e32 v[22:23], 0
	v_mov_b64_e32 v[32:33], 0
	v_mov_b64_e32 v[34:35], 0
	v_mov_b64_e32 v[36:37], 0
	v_mov_b64_e32 v[38:39], 0
	v_mov_b64_e32 v[48:49], 0
	v_mov_b64_e32 v[50:51], 0
	v_mov_b64_e32 v[52:53], 0
	v_mov_b64_e32 v[54:55], 0
	v_mov_b64_e32 v[8:9], 0
	v_mov_b64_e32 v[10:11], 0
	v_mov_b64_e32 v[12:13], 0
	v_mov_b64_e32 v[14:15], 0
	v_mov_b64_e32 v[24:25], 0
	v_mov_b64_e32 v[26:27], 0
	v_mov_b64_e32 v[28:29], 0
	v_mov_b64_e32 v[30:31], 0
	v_mov_b64_e32 v[40:41], 0
	v_mov_b64_e32 v[42:43], 0
	v_mov_b64_e32 v[44:45], 0
	v_mov_b64_e32 v[46:47], 0
	v_mov_b64_e32 v[56:57], 0
	v_mov_b64_e32 v[58:59], 0
	v_mov_b64_e32 v[60:61], 0
	v_mov_b64_e32 v[62:63], 0
	v_mov_b64_e32 v[66:67], 0
	v_mov_b64_e32 v[68:69], 0
	v_mov_b64_e32 v[70:71], 0
	v_mov_b64_e32 v[72:73], 0
	v_mov_b64_e32 v[82:83], 0
	v_mov_b64_e32 v[84:85], 0
	v_mov_b64_e32 v[86:87], 0
	v_mov_b64_e32 v[88:89], 0
	v_mov_b64_e32 v[98:99], 0
	v_mov_b64_e32 v[100:101], 0
	v_mov_b64_e32 v[102:103], 0
	v_mov_b64_e32 v[104:105], 0
	v_mov_b64_e32 v[114:115], 0
	v_mov_b64_e32 v[116:117], 0
	v_mov_b64_e32 v[118:119], 0
	v_mov_b64_e32 v[120:121], 0
	v_mov_b64_e32 v[74:75], 0
	v_mov_b64_e32 v[76:77], 0
	v_mov_b64_e32 v[78:79], 0
	v_mov_b64_e32 v[80:81], 0
	v_mov_b64_e32 v[90:91], 0
	v_mov_b64_e32 v[92:93], 0
	v_mov_b64_e32 v[94:95], 0
	v_mov_b64_e32 v[96:97], 0
	v_mov_b64_e32 v[106:107], 0
	v_mov_b64_e32 v[108:109], 0
	v_mov_b64_e32 v[110:111], 0
	v_mov_b64_e32 v[112:113], 0
	v_mov_b64_e32 v[122:123], 0
	v_mov_b64_e32 v[124:125], 0
	v_mov_b64_e32 v[126:127], 0
	v_mov_b64_e32 v[128:129], 0
	s_mov_b64 s[50:51], 0x80
	v_add_u32_e32 v252, 0x10000, v145
	v_add_u32_e32 v253, 0x14000, v145
	v_add_u32_e32 v254, 0x18000, v145
	v_add_u32_e32 v255, 0x1c000, v145
	v_readlane_b32 s50, v244, 63
	v_writelane_b32 v244, 0, 63
.LBB0_1571:
	s_add_u32 s16, s0, 0xfff80080
	s_addc_u32 s17, s1, -1
	s_add_i32 s46, 0, 0x10000
	s_cmp_eq_u32 s45, 28
	s_cselect_b32 s19, s9, s17
	s_cselect_b32 s18, s33, s16
	s_cselect_b32 s17, s7, s44
	s_cselect_b32 s16, s36, s37
	s_add_i32 s48, 0, 0x14000
	ds_read_b128 v[140:143], v252
	ds_read_b128 v[148:151], v252 offset:1024
	ds_read_b128 v[152:155], v252 offset:2048
	ds_read_b128 v[156:159], v252 offset:3072
	ds_read_b128 v[178:181], v253
	ds_read_b128 v[182:185], v253 offset:1024
	ds_read_b128 v[186:189], v253 offset:2048
	ds_read_b128 v[190:193], v253 offset:3072
	s_add_i32 m0, s15, 0xc000
	ds_read_b128 v[194:197], v147
	ds_read_b128 v[208:211], v147 offset:1024
	ds_read_b128 v[212:215], v147 offset:2048
	ds_read_b128 v[216:219], v147 offset:3072
	ds_read_b128 v[220:223], v147 offset:4096
	ds_read_b128 v[224:227], v147 offset:5120
	ds_read_b128 v[228:231], v147 offset:6144
	ds_read_b128 v[232:235], v147 offset:7168
	global_load_lds_dwordx4 v136, s[0:1]
	s_add_i32 m0, s15, 0xe000
	s_nop 0
	global_load_lds_dwordx4 v138, s[0:1]
	s_cmp_eq_u32 s50, 1
	s_cbranch_scc0 .Ldf3_0n
	s_waitcnt vmcnt(24)
	s_branch .Ldf3_0d

; #define PG8_STAGE(bufoff, gbase, voff) do { _Pragma("unroll") for (int _i = 0; _i < 2; ++_i) \
;         __builtin_amdgcn_global_load_lds((const unsigned*)((const char*)(gbase) + (voff)[_i]), (PG8_LAS unsigned*)(lds + (bufoff) + ldsw + _i * 8192), 16, 0, 0); } while (0)
; #define PG8_LDA(dst, b, h) do { _Pragma("unroll") for (int m = 0; m < 4; ++m) _Pragma("unroll") for (int k = 0; k < 2; ++k) dst[m][k] = *(const PG8_LAS bf16x8*)(lds + PG8_SA(b, h) + aoff + m * 2048 + k * 1024); } while (0)
; #define PG8_MMA(ai, bj, At, Bt) do { __builtin_amdgcn_s_setprio(1); _Pragma("unroll") for (int m = 0; m < 4; ++m) _Pragma("unroll") for (int n = 0; n < 2; ++n) _Pragma("unroll") for (int k = 0; k < 2; ++k) \
;         acc[ai][bj][m][n] = __builtin_amdgcn_mfma_f32_16x16x32_bf16(Bt[n][k], At[m][k], acc[ai][bj][m][n], 0, 0, 0); __builtin_amdgcn_s_setprio(0); } while (0)
; #define PG8_WAIT_V(n) asm volatile("s_waitcnt vmcnt(" #n ")" ::: "memory")
; #define PG8_WAIT_L(n) asm volatile("s_waitcnt lgkmcnt(" #n ")" ::: "memory")
; #define PG8_BAR __builtin_amdgcn_s_barrier()
; #define PG8_SCHED __builtin_amdgcn_sched_barrier(0)
; template <class Epi, class Sched, bool ALIGN_EPI = false, bool SP2 = false>
; __device__ __forceinline__ void gemm_phase(PG8_LAS unsigned char* lds, const Gemm g, const Sched& S, const Epi& E, const int wave0) {
;     ...
;             PG8_WAIT_V(8); PG8_WAIT_L(0); PG8_BAR; PG8_MMA(0, 0, At, B0); PG8_MMA(0, 1, At, B1); PG8_BAR; PG8_SCHED;
;             PG8_LDA(At, 0, 1); PG8_STAGE(PG8_SB(0, 0), b2, voffB); PG8_STAGE(PG8_SB(0, 1), b2 + hstepB, voffB); PG8_STAGE(PG8_SA(0, 0), a2, voffA);
;             PG8_WAIT_V(8); PG8_WAIT_L(0); PG8_BAR; PG8_MMA(1, 0, At, B0); PG8_MMA(1, 1, At, B1); PG8_BAR; PG8_SCHED;
.Ldf3_0d:
	s_waitcnt lgkmcnt(0)
	s_barrier
	s_setprio 1
	s_waitcnt lgkmcnt(0)
	v_mfma_f32_16x16x32_bf16 v[126:129], v[140:143], v[194:197], v[126:129]
	v_mfma_f32_16x16x32_bf16 v[122:125], v[152:155], v[194:197], v[122:125]
	v_mfma_f32_16x16x32_bf16 v[110:113], v[140:143], v[212:215], v[110:113]
	v_mfma_f32_16x16x32_bf16 v[106:109], v[152:155], v[212:215], v[106:109]
	v_mfma_f32_16x16x32_bf16 v[94:97], v[140:143], v[220:223], v[94:97]
	v_mfma_f32_16x16x32_bf16 v[90:93], v[152:155], v[220:223], v[90:93]
	v_mfma_f32_16x16x32_bf16 v[78:81], v[140:143], v[228:231], v[78:81]
	v_mfma_f32_16x16x32_bf16 v[74:77], v[152:155], v[228:231], v[74:77]
	v_mfma_f32_16x16x32_bf16 v[126:129], v[148:151], v[208:211], v[126:129]
	v_mfma_f32_16x16x32_bf16 v[122:125], v[156:159], v[208:211], v[122:125]
	v_mfma_f32_16x16x32_bf16 v[110:113], v[148:151], v[216:219], v[110:113]
	v_mfma_f32_16x16x32_bf16 v[106:109], v[156:159], v[216:219], v[106:109]
	v_mfma_f32_16x16x32_bf16 v[94:97], v[148:151], v[224:227], v[94:97]
	v_mfma_f32_16x16x32_bf16 v[90:93], v[156:159], v[224:227], v[90:93]
	v_mfma_f32_16x16x32_bf16 v[78:81], v[148:151], v[232:235], v[78:81]
	v_mfma_f32_16x16x32_bf16 v[74:77], v[156:159], v[232:235], v[74:77]
	s_setprio 0
	s_setprio 1
	v_mfma_f32_16x16x32_bf16 v[118:121], v[178:181], v[194:197], v[118:121]
	v_mfma_f32_16x16x32_bf16 v[114:117], v[186:189], v[194:197], v[114:117]
	v_mfma_f32_16x16x32_bf16 v[102:105], v[178:181], v[212:215], v[102:105]
	v_mfma_f32_16x16x32_bf16 v[98:101], v[186:189], v[212:215], v[98:101]
	v_mfma_f32_16x16x32_bf16 v[86:89], v[178:181], v[220:223], v[86:89]
	v_mfma_f32_16x16x32_bf16 v[82:85], v[186:189], v[220:223], v[82:85]
	v_mfma_f32_16x16x32_bf16 v[70:73], v[178:181], v[228:231], v[70:73]
	v_mfma_f32_16x16x32_bf16 v[66:69], v[186:189], v[228:231], v[66:69]
	v_mfma_f32_16x16x32_bf16 v[118:121], v[182:185], v[208:211], v[118:121]
	v_mfma_f32_16x16x32_bf16 v[114:117], v[190:193], v[208:211], v[114:117]
	v_mfma_f32_16x16x32_bf16 v[102:105], v[182:185], v[216:219], v[102:105]
	v_mfma_f32_16x16x32_bf16 v[98:101], v[190:193], v[216:219], v[98:101]
	v_mfma_f32_16x16x32_bf16 v[86:89], v[182:185], v[224:227], v[86:89]
	v_mfma_f32_16x16x32_bf16 v[82:85], v[190:193], v[224:227], v[82:85]
	v_mfma_f32_16x16x32_bf16 v[70:73], v[182:185], v[232:235], v[70:73]
	v_mfma_f32_16x16x32_bf16 v[66:69], v[190:193], v[232:235], v[66:69]
	s_setprio 0
	s_barrier
	s_add_i32 s46, s46, s28
	s_mov_b32 m0, s46
	ds_read_b128 v[194:197], v147 offset:16384
	ds_read_b128 v[208:211], v147 offset:17408
	ds_read_b128 v[212:215], v147 offset:18432
	ds_read_b128 v[216:219], v147 offset:19456
	ds_read_b128 v[220:223], v147 offset:20480
	ds_read_b128 v[224:227], v147 offset:21504
	ds_read_b128 v[228:231], v147 offset:22528
	ds_read_b128 v[232:235], v147 offset:23552
	global_load_lds_dwordx4 v64, s[16:17]
	s_add_i32 m0, s46, 0x2000
	s_add_u32 s46, s16, 0x80000
	s_addc_u32 s47, s17, 0
	s_add_i32 s48, s48, s28
	global_load_lds_dwordx4 v130, s[16:17]
	s_mov_b32 m0, s48
	s_mov_b64 s[100:101], s[18:19]
	global_load_lds_dwordx4 v64, s[46:47]
	s_add_i32 m0, s48, 0x2000
	s_nop 0
	global_load_lds_dwordx4 v130, s[46:47]
	s_mov_b32 m0, s15
	s_nop 0
	global_load_lds_dwordx4 v134, s[18:19]
	s_mov_b32 m0, s27
	s_nop 0
	global_load_lds_dwordx4 v132, s[18:19]
	s_cmp_eq_u32 s50, 1
	s_cbranch_scc0 .Ldf3_1n
	s_waitcnt vmcnt(24)
	s_mov_b32 s50, 0
	s_branch .Ldf3_1d

; #define PG8_STAGE(bufoff, gbase, voff) do { _Pragma("unroll") for (int _i = 0; _i < 2; ++_i) \
;         __builtin_amdgcn_global_load_lds((const unsigned*)((const char*)(gbase) + (voff)[_i]), (PG8_LAS unsigned*)(lds + (bufoff) + ldsw + _i * 8192), 16, 0, 0); } while (0)
; #define PG8_LDA(dst, b, h) do { _Pragma("unroll") for (int m = 0; m < 4; ++m) _Pragma("unroll") for (int k = 0; k < 2; ++k) dst[m][k] = *(const PG8_LAS bf16x8*)(lds + PG8_SA(b, h) + aoff + m * 2048 + k * 1024); } while (0)
; #define PG8_LDB(dst, b, h) do { _Pragma("unroll") for (int n = 0; n < 2; ++n) _Pragma("unroll") for (int k = 0; k < 2; ++k) dst[n][k] = *(const PG8_LAS bf16x8*)(lds + PG8_SB(b, h) + boff + n * 2048 + k * 1024); } while (0)
; #define PG8_MMA(ai, bj, At, Bt) do { __builtin_amdgcn_s_setprio(1); _Pragma("unroll") for (int m = 0; m < 4; ++m) _Pragma("unroll") for (int n = 0; n < 2; ++n) _Pragma("unroll") for (int k = 0; k < 2; ++k) \
;         acc[ai][bj][m][n] = __builtin_amdgcn_mfma_f32_16x16x32_bf16(Bt[n][k], At[m][k], acc[ai][bj][m][n], 0, 0, 0); __builtin_amdgcn_s_setprio(0); } while (0)
; #define PG8_WAIT_V(n) asm volatile("s_waitcnt vmcnt(" #n ")" ::: "memory")
; #define PG8_WAIT_L(n) asm volatile("s_waitcnt lgkmcnt(" #n ")" ::: "memory")
; #define PG8_BAR __builtin_amdgcn_s_barrier()
; #define PG8_SCHED __builtin_amdgcn_sched_barrier(0)
; template <class Epi, class Sched, bool ALIGN_EPI = false, bool SP2 = false>
; __device__ __forceinline__ void gemm_phase(PG8_LAS unsigned char* lds, const Gemm g, const Sched& S, const Epi& E, const int wave0) {
;     ...
;             PG8_WAIT_V(8); PG8_WAIT_L(0); PG8_BAR; PG8_MMA(1, 0, At, B0); PG8_MMA(1, 1, At, B1); PG8_BAR; PG8_SCHED;
;             PG8_LDB(B0, 1, 0); PG8_LDB(B1, 1, 1); PG8_SCHED; PG8_LDA(At, 1, 0); PG8_STAGE(PG8_SA(0, 1), a2 + hstepA, voffA);
;             PG8_WAIT_V(8); PG8_WAIT_L(0); PG8_BAR; PG8_MMA(0, 0, At, B0); PG8_MMA(0, 1, At, B1); PG8_BAR; PG8_SCHED;
.Ldf3_1d:
	s_waitcnt lgkmcnt(0)
	s_barrier
	s_setprio 1
	s_waitcnt lgkmcnt(0)
	v_mfma_f32_16x16x32_bf16 v[60:63], v[140:143], v[194:197], v[60:63]
	v_mfma_f32_16x16x32_bf16 v[56:59], v[152:155], v[194:197], v[56:59]
	v_mfma_f32_16x16x32_bf16 v[44:47], v[140:143], v[212:215], v[44:47]
	v_mfma_f32_16x16x32_bf16 v[40:43], v[152:155], v[212:215], v[40:43]
	v_mfma_f32_16x16x32_bf16 v[28:31], v[140:143], v[220:223], v[28:31]
	v_mfma_f32_16x16x32_bf16 v[24:27], v[152:155], v[220:223], v[24:27]
	v_mfma_f32_16x16x32_bf16 v[12:15], v[140:143], v[228:231], v[12:15]
	v_mfma_f32_16x16x32_bf16 v[8:11], v[152:155], v[228:231], v[8:11]
	v_mfma_f32_16x16x32_bf16 v[60:63], v[148:151], v[208:211], v[60:63]
	v_mfma_f32_16x16x32_bf16 v[56:59], v[156:159], v[208:211], v[56:59]
	v_mfma_f32_16x16x32_bf16 v[44:47], v[148:151], v[216:219], v[44:47]
	v_mfma_f32_16x16x32_bf16 v[40:43], v[156:159], v[216:219], v[40:43]
	v_mfma_f32_16x16x32_bf16 v[28:31], v[148:151], v[224:227], v[28:31]
	v_mfma_f32_16x16x32_bf16 v[24:27], v[156:159], v[224:227], v[24:27]
	v_mfma_f32_16x16x32_bf16 v[12:15], v[148:151], v[232:235], v[12:15]
	v_mfma_f32_16x16x32_bf16 v[8:11], v[156:159], v[232:235], v[8:11]
	s_setprio 0
	s_setprio 1
	v_mfma_f32_16x16x32_bf16 v[52:55], v[178:181], v[194:197], v[52:55]
	v_mfma_f32_16x16x32_bf16 v[48:51], v[186:189], v[194:197], v[48:51]
	v_mfma_f32_16x16x32_bf16 v[36:39], v[178:181], v[212:215], v[36:39]
	v_mfma_f32_16x16x32_bf16 v[32:35], v[186:189], v[212:215], v[32:35]
	v_mfma_f32_16x16x32_bf16 v[20:23], v[178:181], v[220:223], v[20:23]
	v_mfma_f32_16x16x32_bf16 v[16:19], v[186:189], v[220:223], v[16:19]
	v_mfma_f32_16x16x32_bf16 v[4:7], v[178:181], v[228:231], v[4:7]
	v_mfma_f32_16x16x32_bf16 v[0:3], v[186:189], v[228:231], v[0:3]
	v_mfma_f32_16x16x32_bf16 v[52:55], v[182:185], v[208:211], v[52:55]
	v_mfma_f32_16x16x32_bf16 v[48:51], v[190:193], v[208:211], v[48:51]
	v_mfma_f32_16x16x32_bf16 v[36:39], v[182:185], v[216:219], v[36:39]
	v_mfma_f32_16x16x32_bf16 v[32:35], v[190:193], v[216:219], v[32:35]
	v_mfma_f32_16x16x32_bf16 v[20:23], v[182:185], v[224:227], v[20:23]
	v_mfma_f32_16x16x32_bf16 v[16:19], v[190:193], v[224:227], v[16:19]
	v_mfma_f32_16x16x32_bf16 v[4:7], v[182:185], v[232:235], v[4:7]
	v_mfma_f32_16x16x32_bf16 v[0:3], v[190:193], v[232:235], v[0:3]
	s_setprio 0
	s_barrier
	s_add_i32 s46, 0, 0x18000
	s_add_i32 s47, 0, 0x1c000
	ds_read_b128 v[140:143], v254
	ds_read_b128 v[148:151], v254 offset:1024
	ds_read_b128 v[152:155], v254 offset:2048
	ds_read_b128 v[156:159], v254 offset:3072
	ds_read_b128 v[178:181], v255
	ds_read_b128 v[182:185], v255 offset:1024
	ds_read_b128 v[186:189], v255 offset:2048
	ds_read_b128 v[190:193], v255 offset:3072
	s_add_u32 s18, s18, 0x80000
	s_addc_u32 s19, s19, 0
	s_mov_b32 m0, s29
	ds_read_b128 v[194:197], v147 offset:32768
	ds_read_b128 v[208:211], v147 offset:33792
	ds_read_b128 v[212:215], v147 offset:34816
	ds_read_b128 v[216:219], v147 offset:35840
	ds_read_b128 v[220:223], v147 offset:36864
	ds_read_b128 v[224:227], v147 offset:37888
	ds_read_b128 v[228:231], v147 offset:38912
	ds_read_b128 v[232:235], v147 offset:39936
	global_load_lds_dwordx4 v134, s[18:19]
	s_mov_b32 m0, s30
	s_nop 0
	global_load_lds_dwordx4 v132, s[18:19]
	s_waitcnt vmcnt(8)
	s_waitcnt lgkmcnt(0)
	s_barrier
	s_setprio 1
	s_waitcnt lgkmcnt(0)
	v_mfma_f32_16x16x32_bf16 v[126:129], v[140:143], v[194:197], v[126:129]
	v_mfma_f32_16x16x32_bf16 v[122:125], v[152:155], v[194:197], v[122:125]
	v_mfma_f32_16x16x32_bf16 v[110:113], v[140:143], v[212:215], v[110:113]
	v_mfma_f32_16x16x32_bf16 v[106:109], v[152:155], v[212:215], v[106:109]
	v_mfma_f32_16x16x32_bf16 v[94:97], v[140:143], v[220:223], v[94:97]
	v_mfma_f32_16x16x32_bf16 v[90:93], v[152:155], v[220:223], v[90:93]
	v_mfma_f32_16x16x32_bf16 v[78:81], v[140:143], v[228:231], v[78:81]
	v_mfma_f32_16x16x32_bf16 v[74:77], v[152:155], v[228:231], v[74:77]
	v_mfma_f32_16x16x32_bf16 v[126:129], v[148:151], v[208:211], v[126:129]
	v_mfma_f32_16x16x32_bf16 v[122:125], v[156:159], v[208:211], v[122:125]
	v_mfma_f32_16x16x32_bf16 v[110:113], v[148:151], v[216:219], v[110:113]
	v_mfma_f32_16x16x32_bf16 v[106:109], v[156:159], v[216:219], v[106:109]
	v_mfma_f32_16x16x32_bf16 v[94:97], v[148:151], v[224:227], v[94:97]
	v_mfma_f32_16x16x32_bf16 v[90:93], v[156:159], v[224:227], v[90:93]
	v_mfma_f32_16x16x32_bf16 v[78:81], v[148:151], v[232:235], v[78:81]
	v_mfma_f32_16x16x32_bf16 v[74:77], v[156:159], v[232:235], v[74:77]
	s_setprio 0
	s_setprio 1
	v_mfma_f32_16x16x32_bf16 v[118:121], v[178:181], v[194:197], v[118:121]
	v_mfma_f32_16x16x32_bf16 v[114:117], v[186:189], v[194:197], v[114:117]
	v_mfma_f32_16x16x32_bf16 v[102:105], v[178:181], v[212:215], v[102:105]
	v_mfma_f32_16x16x32_bf16 v[98:101], v[186:189], v[212:215], v[98:101]
	v_mfma_f32_16x16x32_bf16 v[86:89], v[178:181], v[220:223], v[86:89]
	v_mfma_f32_16x16x32_bf16 v[82:85], v[186:189], v[220:223], v[82:85]
	v_mfma_f32_16x16x32_bf16 v[70:73], v[178:181], v[228:231], v[70:73]
	v_mfma_f32_16x16x32_bf16 v[66:69], v[186:189], v[228:231], v[66:69]
	v_mfma_f32_16x16x32_bf16 v[118:121], v[182:185], v[208:211], v[118:121]
	v_mfma_f32_16x16x32_bf16 v[114:117], v[190:193], v[208:211], v[114:117]
	v_mfma_f32_16x16x32_bf16 v[102:105], v[182:185], v[216:219], v[102:105]
	v_mfma_f32_16x16x32_bf16 v[98:101], v[190:193], v[216:219], v[98:101]
	v_mfma_f32_16x16x32_bf16 v[86:89], v[182:185], v[224:227], v[86:89]
	v_mfma_f32_16x16x32_bf16 v[82:85], v[190:193], v[224:227], v[82:85]
	v_mfma_f32_16x16x32_bf16 v[70:73], v[182:185], v[232:235], v[70:73]
	v_mfma_f32_16x16x32_bf16 v[66:69], v[190:193], v[232:235], v[66:69]
	s_setprio 0
	s_barrier
; __device__ __forceinline__ unsigned cvt_pk_bf16(float lo, float hi) { const f32x2_t v = {lo, hi}; const bf16x2_t b = __builtin_convertvector(v, bf16x2_t); return __builtin_bit_cast(unsigned, b); }
; #define PG8_STAGE(bufoff, gbase, voff) do { _Pragma("unroll") for (int _i = 0; _i < 2; ++_i) \
;         __builtin_amdgcn_global_load_lds((const unsigned*)((const char*)(gbase) + (voff)[_i]), (PG8_LAS unsigned*)(lds + (bufoff) + ldsw + _i * 8192), 16, 0, 0); } while (0)
; #define PG8_LDA(dst, b, h) do { _Pragma("unroll") for (int m = 0; m < 4; ++m) _Pragma("unroll") for (int k = 0; k < 2; ++k) dst[m][k] = *(const PG8_LAS bf16x8*)(lds + PG8_SA(b, h) + aoff + m * 2048 + k * 1024); } while (0)
; #define PG8_WAIT_V(n) asm volatile("s_waitcnt vmcnt(" #n ")" ::: "memory")
; #define PG8_WAIT_L(n) asm volatile("s_waitcnt lgkmcnt(" #n ")" ::: "memory")
; #define PG8_BAR __builtin_amdgcn_s_barrier()
;     __device__ __forceinline__ void operator()(const f32x4 (&acc)[2][2][4][2], const Unit& u, int wr, int wc, int fr, int fq) const {
;         const int row0 = u.pm * BM + wr * 64 + fr; const int col0 = u.pn * BM + wc * 32 + 8 * fq;
; #pragma unroll
;         for (int ai = 0; ai < 2; ++ai)
; #pragma unroll
;             for (int m = 0; m < 4; ++m) { bf16_t* rowp = O + (size_t)u.zo * zsO + (size_t)(row0 + ai * HALF + m * 16) * ldc + col0;
; #pragma unroll
;                 for (int bj = 0; bj < 2; ++bj) { f32x4 v0 = acc[ai][bj][m][0], v1 = acc[ai][bj][m][1];
;                     if (ACT == 2) {
; #pragma unroll
;                         for (int j = 0; j < 4; ++j) { const float a = fmaxf(v0[j], 0.f), b = fmaxf(v1[j], 0.f); v0[j] = a * a; v1[j] = b * b; } }
;                     u32x4 w; w.x = cvt_pk_bf16(v0[0], v0[1]); w.y = cvt_pk_bf16(v0[2], v0[3]); w.z = cvt_pk_bf16(v1[0], v1[1]); w.w = cvt_pk_bf16(v1[2], v1[3]);
;                     *(u32x4*)(rowp + bj * HALF) = w; } }
; template <class Epi, class Sched, bool ALIGN_EPI = false, bool SP2 = false>
; __device__ __forceinline__ void gemm_phase(PG8_LAS unsigned char* lds, const Gemm g, const Sched& S, const Epi& E, const int wave0) {
;     ...
;             PG8_LDA(At, 1, 1); PG8_STAGE(PG8_SB(1, 0), b3, voffB); PG8_STAGE(PG8_SB(1, 1), b3 + hstepB, voffB); PG8_STAGE(PG8_SA(1, 0), a3, voffA);
;             PG8_WAIT_V(8); PG8_WAIT_L(0); PG8_BAR; PG8_MMA(1, 0, At, B0); PG8_MMA(1, 1, At, B1); PG8_BAR; PG8_SCHED;
	s_add_i32 s18, s46, s28
	s_add_u32 s50, s16, 0x80
	s_addc_u32 s51, s17, 0
	s_mov_b32 m0, s18
	ds_read_b128 v[194:197], v147 offset:49152
	ds_read_b128 v[208:211], v147 offset:50176
	ds_read_b128 v[212:215], v147 offset:51200
	ds_read_b128 v[216:219], v147 offset:52224
	ds_read_b128 v[220:223], v147 offset:53248
	ds_read_b128 v[224:227], v147 offset:54272
	ds_read_b128 v[228:231], v147 offset:55296
	ds_read_b128 v[232:235], v147 offset:56320
	global_load_lds_dwordx4 v64, s[50:51]
	s_add_i32 m0, s18, 0x2000
	s_add_u32 s16, s16, 0x80080
	s_addc_u32 s17, s17, 0
	s_add_i32 s18, s47, s28
	global_load_lds_dwordx4 v130, s[50:51]
	s_mov_b32 m0, s18
	s_nop 0
	global_load_lds_dwordx4 v64, s[16:17]
	s_add_i32 m0, s18, 0x2000
	s_nop 0
	global_load_lds_dwordx4 v130, s[16:17]
	s_add_u32 s100, s100, 0x80
	s_addc_u32 s101, s101, 0
	s_mov_b32 m0, s31
	s_nop 0
	global_load_lds_dwordx4 v134, s[100:101]
	s_mov_b32 m0, s34
	s_nop 0
	global_load_lds_dwordx4 v132, s[100:101]
	s_waitcnt vmcnt(8)
	s_waitcnt lgkmcnt(0)
	s_barrier
	s_setprio 1
	s_waitcnt lgkmcnt(0)
	v_mfma_f32_16x16x32_bf16 v[60:63], v[140:143], v[194:197], v[60:63]
	v_mfma_f32_16x16x32_bf16 v[56:59], v[152:155], v[194:197], v[56:59]
	v_mfma_f32_16x16x32_bf16 v[44:47], v[140:143], v[212:215], v[44:47]
	v_mfma_f32_16x16x32_bf16 v[40:43], v[152:155], v[212:215], v[40:43]
	v_mfma_f32_16x16x32_bf16 v[28:31], v[140:143], v[220:223], v[28:31]
	v_mfma_f32_16x16x32_bf16 v[24:27], v[152:155], v[220:223], v[24:27]
	v_mfma_f32_16x16x32_bf16 v[12:15], v[140:143], v[228:231], v[12:15]
	v_mfma_f32_16x16x32_bf16 v[8:11], v[152:155], v[228:231], v[8:11]
	v_mfma_f32_16x16x32_bf16 v[60:63], v[148:151], v[208:211], v[60:63]
	v_mfma_f32_16x16x32_bf16 v[56:59], v[156:159], v[208:211], v[56:59]
	v_mfma_f32_16x16x32_bf16 v[44:47], v[148:151], v[216:219], v[44:47]
	v_mfma_f32_16x16x32_bf16 v[40:43], v[156:159], v[216:219], v[40:43]
	v_mfma_f32_16x16x32_bf16 v[28:31], v[148:151], v[224:227], v[28:31]
	v_mfma_f32_16x16x32_bf16 v[24:27], v[156:159], v[224:227], v[24:27]
	v_mfma_f32_16x16x32_bf16 v[12:15], v[148:151], v[232:235], v[12:15]
	v_mfma_f32_16x16x32_bf16 v[8:11], v[156:159], v[232:235], v[8:11]
	s_setprio 0
	s_setprio 1
	v_mfma_f32_16x16x32_bf16 v[52:55], v[178:181], v[194:197], v[52:55]
	v_mfma_f32_16x16x32_bf16 v[48:51], v[186:189], v[194:197], v[48:51]
	v_mfma_f32_16x16x32_bf16 v[36:39], v[178:181], v[212:215], v[36:39]
	v_mfma_f32_16x16x32_bf16 v[32:35], v[186:189], v[212:215], v[32:35]
	v_mfma_f32_16x16x32_bf16 v[20:23], v[178:181], v[220:223], v[20:23]
	v_mfma_f32_16x16x32_bf16 v[16:19], v[186:189], v[220:223], v[16:19]
	v_mfma_f32_16x16x32_bf16 v[4:7], v[178:181], v[228:231], v[4:7]
	v_mfma_f32_16x16x32_bf16 v[0:3], v[186:189], v[228:231], v[0:3]
	v_mfma_f32_16x16x32_bf16 v[52:55], v[182:185], v[208:211], v[52:55]
	v_mfma_f32_16x16x32_bf16 v[48:51], v[190:193], v[208:211], v[48:51]
	v_mfma_f32_16x16x32_bf16 v[36:39], v[182:185], v[216:219], v[36:39]
	v_mfma_f32_16x16x32_bf16 v[32:35], v[190:193], v[216:219], v[32:35]
	v_mfma_f32_16x16x32_bf16 v[20:23], v[182:185], v[224:227], v[20:23]
	v_mfma_f32_16x16x32_bf16 v[16:19], v[190:193], v[224:227], v[16:19]
	v_mfma_f32_16x16x32_bf16 v[4:7], v[182:185], v[232:235], v[4:7]
	v_mfma_f32_16x16x32_bf16 v[0:3], v[190:193], v[232:235], v[0:3]
	s_setprio 0
	s_barrier
	s_add_i32 s45, s45, 2
	s_add_u32 s0, s0, 0x100
	s_addc_u32 s1, s1, 0
	s_add_u32 s37, s37, 0x100
	s_addc_u32 s44, s44, 0
	s_cmp_gt_u32 s45, 29
	s_cbranch_scc0 .LBB0_1571
	s_mov_b64 s[50:51], 0x80
	s_and_b64 vcc, exec, s[4:5]
	s_cbranch_vccz .LBB0_1574
	s_barrier
.LBB0_1574:
	v_lshl_add_u32 v142, s26, 8, v144
	v_lshl_or_b32 v140, s14, 8, v146
	v_ashrrev_i32_e32 v143, 31, v142
	v_readlane_b32 s0, v246, 44
	v_ashrrev_i32_e32 v141, 31, v140
	v_lshlrev_b64 v[148:149], 14, v[142:143]
	v_readlane_b32 s1, v246, 45
	v_max_f32_e32 v122, v122, v122
	v_max_f32_e32 v123, v123, v123
	v_lshl_add_u64 v[148:149], s[0:1], 0, v[148:149]
	v_lshlrev_b64 v[150:151], 1, v[140:141]
	v_max_f32_e32 v122, 0, v122
	v_max_f32_e32 v123, 0, v123
	v_lshl_add_u64 v[140:141], v[148:149], 0, v[150:151]
	v_pk_mul_f32 v[148:149], v[122:123], v[122:123]
	v_max_f32_e32 v123, v124, v124
	v_max_f32_e32 v126, v126, v126
	v_max_f32_e32 v127, v127, v127
	v_max_f32_e32 v122, v128, v128
	v_max_f32_e32 v124, 0, v123
	v_max_f32_e32 v123, v129, v129
	v_max_f32_e32 v125, v125, v125
	v_max_f32_e32 v126, 0, v126
	v_max_f32_e32 v127, 0, v127
	v_max_f32_e32 v122, 0, v122
	v_max_f32_e32 v123, 0, v123
	v_max_f32_e32 v125, 0, v125
	v_pk_mul_f32 v[126:127], v[126:127], v[126:127]
	v_pk_mul_f32 v[128:129], v[122:123], v[122:123]
	v_pk_mul_f32 v[152:153], v[124:125], v[124:125]
	v_max_f32_e32 v114, v114, v114
	v_max_f32_e32 v115, v115, v115
	v_cvt_pk_bf16_f32 v122, v126, v127
	v_cvt_pk_bf16_f32 v123, v128, v129
	v_cvt_pk_bf16_f32 v124, v148, v149
	v_cvt_pk_bf16_f32 v125, v152, v153
	v_max_f32_e32 v114, 0, v114
	v_max_f32_e32 v115, 0, v115
	global_store_dwordx4 v[140:141], v[122:125], off
	v_max_f32_e32 v118, v118, v118
	v_max_f32_e32 v119, v119, v119
	v_pk_mul_f32 v[122:123], v[114:115], v[114:115]
	v_max_f32_e32 v115, v116, v116
	v_max_f32_e32 v114, v120, v120
	v_max_f32_e32 v116, 0, v115
	v_max_f32_e32 v115, v121, v121
	v_max_f32_e32 v117, v117, v117
	v_max_f32_e32 v118, 0, v118
	v_max_f32_e32 v119, 0, v119
	v_max_f32_e32 v114, 0, v114
	v_max_f32_e32 v115, 0, v115
	v_max_f32_e32 v117, 0, v117
	v_pk_mul_f32 v[118:119], v[118:119], v[118:119]
	v_pk_mul_f32 v[120:121], v[114:115], v[114:115]
	v_pk_mul_f32 v[124:125], v[116:117], v[116:117]
	v_max_f32_e32 v106, v106, v106
	v_max_f32_e32 v107, v107, v107
	v_cvt_pk_bf16_f32 v114, v118, v119
	v_cvt_pk_bf16_f32 v115, v120, v121
; __device__ __forceinline__ unsigned cvt_pk_bf16(float lo, float hi) { const f32x2_t v = {lo, hi}; const bf16x2_t b = __builtin_convertvector(v, bf16x2_t); return __builtin_bit_cast(unsigned, b); }
;     __device__ __forceinline__ void operator()(const f32x4 (&acc)[2][2][4][2], const Unit& u, int wr, int wc, int fr, int fq) const {
;     ...
;             for (int m = 0; m < 4; ++m) { bf16_t* rowp = O + (size_t)u.zo * zsO + (size_t)(row0 + ai * HALF + m * 16) * ldc + col0;
; #pragma unroll
;                 for (int bj = 0; bj < 2; ++bj) { f32x4 v0 = acc[ai][bj][m][0], v1 = acc[ai][bj][m][1];
;                     if (ACT == 2) {
; #pragma unroll
;                         for (int j = 0; j < 4; ++j) { const float a = fmaxf(v0[j], 0.f), b = fmaxf(v1[j], 0.f); v0[j] = a * a; v1[j] = b * b; } }
;                     u32x4 w; w.x = cvt_pk_bf16(v0[0], v0[1]); w.y = cvt_pk_bf16(v0[2], v0[3]); w.z = cvt_pk_bf16(v1[0], v1[1]); w.w = cvt_pk_bf16(v1[2], v1[3]);
;                     *(u32x4*)(rowp + bj * HALF) = w; } }
	v_cvt_pk_bf16_f32 v116, v122, v123
	v_cvt_pk_bf16_f32 v117, v124, v125
	v_max_f32_e32 v106, 0, v106
	v_max_f32_e32 v107, 0, v107
	global_store_dwordx4 v[140:141], v[114:117], off offset:256
	v_max_f32_e32 v110, v110, v110
	v_max_f32_e32 v111, v111, v111
	v_or_b32_e32 v114, 16, v142
	v_pk_mul_f32 v[116:117], v[106:107], v[106:107]
	v_max_f32_e32 v107, v108, v108
	v_ashrrev_i32_e32 v115, 31, v114
	v_max_f32_e32 v106, v112, v112
	v_max_f32_e32 v108, 0, v107
	v_max_f32_e32 v107, v113, v113
	v_max_f32_e32 v109, v109, v109
	v_lshlrev_b64 v[114:115], 14, v[114:115]
	v_max_f32_e32 v110, 0, v110
	v_max_f32_e32 v111, 0, v111
	v_max_f32_e32 v106, 0, v106
	v_max_f32_e32 v107, 0, v107
	v_max_f32_e32 v109, 0, v109
	v_lshl_add_u64 v[114:115], s[0:1], 0, v[114:115]
	v_pk_mul_f32 v[110:111], v[110:111], v[110:111]
	v_pk_mul_f32 v[112:113], v[106:107], v[106:107]
	v_pk_mul_f32 v[118:119], v[108:109], v[108:109]
	v_max_f32_e32 v98, v98, v98
	v_max_f32_e32 v99, v99, v99
	v_lshl_add_u64 v[114:115], v[114:115], 0, v[150:151]
	v_cvt_pk_bf16_f32 v106, v110, v111
	v_cvt_pk_bf16_f32 v107, v112, v113
	v_cvt_pk_bf16_f32 v108, v116, v117
	v_cvt_pk_bf16_f32 v109, v118, v119
	v_max_f32_e32 v98, 0, v98
	v_max_f32_e32 v99, 0, v99
	global_store_dwordx4 v[114:115], v[106:109], off
	v_max_f32_e32 v102, v102, v102
	v_max_f32_e32 v103, v103, v103
	v_pk_mul_f32 v[106:107], v[98:99], v[98:99]
	v_max_f32_e32 v99, v100, v100
	v_max_f32_e32 v98, v104, v104
	v_max_f32_e32 v100, 0, v99
	v_max_f32_e32 v99, v105, v105
	v_max_f32_e32 v101, v101, v101
	v_max_f32_e32 v102, 0, v102
	v_max_f32_e32 v103, 0, v103
	v_max_f32_e32 v98, 0, v98
	v_max_f32_e32 v99, 0, v99
	v_max_f32_e32 v101, 0, v101
	v_pk_mul_f32 v[102:103], v[102:103], v[102:103]
	v_pk_mul_f32 v[104:105], v[98:99], v[98:99]
	v_pk_mul_f32 v[108:109], v[100:101], v[100:101]
	v_max_f32_e32 v90, v90, v90
	v_max_f32_e32 v91, v91, v91
	v_cvt_pk_bf16_f32 v98, v102, v103
	v_cvt_pk_bf16_f32 v99, v104, v105
	v_cvt_pk_bf16_f32 v100, v106, v107
	v_cvt_pk_bf16_f32 v101, v108, v109
	v_max_f32_e32 v90, 0, v90
	v_max_f32_e32 v91, 0, v91
	global_store_dwordx4 v[114:115], v[98:101], off offset:256
	v_max_f32_e32 v94, v94, v94
	v_max_f32_e32 v95, v95, v95
	v_or_b32_e32 v98, 32, v142
	v_pk_mul_f32 v[100:101], v[90:91], v[90:91]
	v_max_f32_e32 v91, v92, v92
	v_ashrrev_i32_e32 v99, 31, v98
	v_max_f32_e32 v90, v96, v96
	v_max_f32_e32 v92, 0, v91
	v_max_f32_e32 v91, v97, v97
	v_max_f32_e32 v93, v93, v93
	v_lshlrev_b64 v[98:99], 14, v[98:99]
	v_max_f32_e32 v94, 0, v94
	v_max_f32_e32 v95, 0, v95
	v_max_f32_e32 v90, 0, v90
	v_max_f32_e32 v91, 0, v91
	v_max_f32_e32 v93, 0, v93
	v_lshl_add_u64 v[98:99], s[0:1], 0, v[98:99]
	v_pk_mul_f32 v[94:95], v[94:95], v[94:95]
	v_pk_mul_f32 v[96:97], v[90:91], v[90:91]
	v_pk_mul_f32 v[102:103], v[92:93], v[92:93]
	v_max_f32_e32 v82, v82, v82
	v_max_f32_e32 v83, v83, v83
	v_lshl_add_u64 v[98:99], v[98:99], 0, v[150:151]
	v_cvt_pk_bf16_f32 v90, v94, v95
	v_cvt_pk_bf16_f32 v91, v96, v97
	v_cvt_pk_bf16_f32 v92, v100, v101
	v_cvt_pk_bf16_f32 v93, v102, v103
	v_max_f32_e32 v82, 0, v82
	v_max_f32_e32 v83, 0, v83
	global_store_dwordx4 v[98:99], v[90:93], off
	v_max_f32_e32 v86, v86, v86
	v_max_f32_e32 v87, v87, v87
	v_pk_mul_f32 v[90:91], v[82:83], v[82:83]
	v_max_f32_e32 v83, v84, v84
	v_max_f32_e32 v82, v88, v88
	v_max_f32_e32 v84, 0, v83
	v_max_f32_e32 v83, v89, v89
	v_max_f32_e32 v85, v85, v85
	v_max_f32_e32 v86, 0, v86
	v_max_f32_e32 v87, 0, v87
	v_max_f32_e32 v82, 0, v82
	v_max_f32_e32 v83, 0, v83
	v_max_f32_e32 v85, 0, v85
	v_pk_mul_f32 v[86:87], v[86:87], v[86:87]
	v_pk_mul_f32 v[88:89], v[82:83], v[82:83]
	v_pk_mul_f32 v[92:93], v[84:85], v[84:85]
	v_max_f32_e32 v74, v74, v74
	v_max_f32_e32 v75, v75, v75
	v_cvt_pk_bf16_f32 v82, v86, v87
	v_cvt_pk_bf16_f32 v83, v88, v89
	v_cvt_pk_bf16_f32 v84, v90, v91
	v_cvt_pk_bf16_f32 v85, v92, v93
	v_max_f32_e32 v74, 0, v74
	v_max_f32_e32 v75, 0, v75
	global_store_dwordx4 v[98:99], v[82:85], off offset:256
	v_max_f32_e32 v78, v78, v78
	v_max_f32_e32 v79, v79, v79
	v_or_b32_e32 v82, 48, v142
	v_pk_mul_f32 v[84:85], v[74:75], v[74:75]
	v_max_f32_e32 v75, v76, v76
	v_ashrrev_i32_e32 v83, 31, v82
	v_max_f32_e32 v74, v80, v80
	v_max_f32_e32 v76, 0, v75
	v_max_f32_e32 v75, v81, v81
	v_max_f32_e32 v77, v77, v77
	v_lshlrev_b64 v[82:83], 14, v[82:83]
	v_max_f32_e32 v78, 0, v78
	v_max_f32_e32 v79, 0, v79
	v_max_f32_e32 v74, 0, v74
	v_max_f32_e32 v75, 0, v75
	v_max_f32_e32 v77, 0, v77
	v_lshl_add_u64 v[82:83], s[0:1], 0, v[82:83]
	v_pk_mul_f32 v[78:79], v[78:79], v[78:79]
	v_pk_mul_f32 v[80:81], v[74:75], v[74:75]
	v_pk_mul_f32 v[86:87], v[76:77], v[76:77]
	v_max_f32_e32 v66, v66, v66
	v_max_f32_e32 v67, v67, v67
	v_lshl_add_u64 v[82:83], v[82:83], 0, v[150:151]
	v_cvt_pk_bf16_f32 v74, v78, v79
	v_cvt_pk_bf16_f32 v75, v80, v81
	v_cvt_pk_bf16_f32 v76, v84, v85
	v_cvt_pk_bf16_f32 v77, v86, v87
	v_max_f32_e32 v66, 0, v66
	v_max_f32_e32 v67, 0, v67
	global_store_dwordx4 v[82:83], v[74:77], off
	v_max_f32_e32 v70, v70, v70
	v_max_f32_e32 v71, v71, v71
	v_pk_mul_f32 v[74:75], v[66:67], v[66:67]
	v_max_f32_e32 v67, v68, v68
	v_max_f32_e32 v66, v72, v72
	v_max_f32_e32 v68, 0, v67
	v_max_f32_e32 v67, v73, v73
	v_max_f32_e32 v69, v69, v69
	v_max_f32_e32 v70, 0, v70
	v_max_f32_e32 v71, 0, v71
	v_max_f32_e32 v66, 0, v66
	v_max_f32_e32 v67, 0, v67
	v_max_f32_e32 v69, 0, v69
	v_pk_mul_f32 v[70:71], v[70:71], v[70:71]
	v_pk_mul_f32 v[72:73], v[66:67], v[66:67]
	v_pk_mul_f32 v[76:77], v[68:69], v[68:69]
	v_max_f32_e32 v56, v56, v56
	v_max_f32_e32 v57, v57, v57
	v_cvt_pk_bf16_f32 v66, v70, v71
	v_cvt_pk_bf16_f32 v67, v72, v73
	v_cvt_pk_bf16_f32 v68, v74, v75
	v_cvt_pk_bf16_f32 v69, v76, v77
; __device__ __forceinline__ unsigned cvt_pk_bf16(float lo, float hi) { const f32x2_t v = {lo, hi}; const bf16x2_t b = __builtin_convertvector(v, bf16x2_t); return __builtin_bit_cast(unsigned, b); }
;     __device__ __forceinline__ void operator()(const f32x4 (&acc)[2][2][4][2], const Unit& u, int wr, int wc, int fr, int fq) const {
;     ...
;             for (int m = 0; m < 4; ++m) { bf16_t* rowp = O + (size_t)u.zo * zsO + (size_t)(row0 + ai * HALF + m * 16) * ldc + col0;
; #pragma unroll
;                 for (int bj = 0; bj < 2; ++bj) { f32x4 v0 = acc[ai][bj][m][0], v1 = acc[ai][bj][m][1];
;                     if (ACT == 2) {
; #pragma unroll
;                         for (int j = 0; j < 4; ++j) { const float a = fmaxf(v0[j], 0.f), b = fmaxf(v1[j], 0.f); v0[j] = a * a; v1[j] = b * b; } }
;                     u32x4 w; w.x = cvt_pk_bf16(v0[0], v0[1]); w.y = cvt_pk_bf16(v0[2], v0[3]); w.z = cvt_pk_bf16(v1[0], v1[1]); w.w = cvt_pk_bf16(v1[2], v1[3]);
;                     *(u32x4*)(rowp + bj * HALF) = w; } }
	v_max_f32_e32 v56, 0, v56
	v_max_f32_e32 v57, 0, v57
	global_store_dwordx4 v[82:83], v[66:69], off offset:256
	v_max_f32_e32 v60, v60, v60
	v_max_f32_e32 v61, v61, v61
	v_pk_mul_f32 v[68:69], v[56:57], v[56:57]
	v_max_f32_e32 v57, v58, v58
	s_mov_b64 s[0:1], 0x200000
	v_max_f32_e32 v60, 0, v60
	v_max_f32_e32 v61, 0, v61
	v_max_f32_e32 v56, v62, v62
	v_max_f32_e32 v58, 0, v57
	v_max_f32_e32 v57, v63, v63
	v_max_f32_e32 v59, v59, v59
	v_lshl_add_u64 v[66:67], v[140:141], 0, s[0:1]
	v_pk_mul_f32 v[60:61], v[60:61], v[60:61]
	v_max_f32_e32 v56, 0, v56
	v_max_f32_e32 v57, 0, v57
	v_max_f32_e32 v59, 0, v59
	s_mov_b32 s0, 0x200000
	v_pk_mul_f32 v[62:63], v[56:57], v[56:57]
	v_pk_mul_f32 v[70:71], v[58:59], v[58:59]
	v_cvt_pk_bf16_f32 v56, v60, v61
	v_add_co_u32_e32 v60, vcc, s0, v140
	v_max_f32_e32 v48, v48, v48
	v_max_f32_e32 v49, v49, v49
	v_cvt_pk_bf16_f32 v57, v62, v63
	v_cvt_pk_bf16_f32 v58, v68, v69
	v_cvt_pk_bf16_f32 v59, v70, v71
	v_addc_co_u32_e32 v61, vcc, 0, v141, vcc
	v_max_f32_e32 v48, 0, v48
	v_max_f32_e32 v49, 0, v49
	global_store_dwordx4 v[60:61], v[56:59], off
	v_max_f32_e32 v52, v52, v52
	v_max_f32_e32 v53, v53, v53
	v_pk_mul_f32 v[56:57], v[48:49], v[48:49]
	v_max_f32_e32 v49, v50, v50
	v_max_f32_e32 v48, v54, v54
	v_max_f32_e32 v50, 0, v49
	v_max_f32_e32 v49, v55, v55
	v_max_f32_e32 v51, v51, v51
	v_max_f32_e32 v52, 0, v52
	v_max_f32_e32 v53, 0, v53
	v_max_f32_e32 v48, 0, v48
	v_max_f32_e32 v49, 0, v49
	v_max_f32_e32 v51, 0, v51
	v_pk_mul_f32 v[52:53], v[52:53], v[52:53]
	v_pk_mul_f32 v[54:55], v[48:49], v[48:49]
	v_pk_mul_f32 v[58:59], v[50:51], v[50:51]
	v_max_f32_e32 v40, v40, v40
	v_max_f32_e32 v41, v41, v41
	v_cvt_pk_bf16_f32 v48, v52, v53
	v_cvt_pk_bf16_f32 v49, v54, v55
	v_cvt_pk_bf16_f32 v50, v56, v57
	v_cvt_pk_bf16_f32 v51, v58, v59
	v_max_f32_e32 v40, 0, v40
	v_max_f32_e32 v41, 0, v41
	global_store_dwordx4 v[66:67], v[48:51], off offset:256
	v_max_f32_e32 v44, v44, v44
	v_max_f32_e32 v45, v45, v45
	v_pk_mul_f32 v[50:51], v[40:41], v[40:41]
	v_max_f32_e32 v41, v42, v42
	s_mov_b64 s[0:1], 0x240000
	v_max_f32_e32 v44, 0, v44
	v_max_f32_e32 v45, 0, v45
	v_max_f32_e32 v40, v46, v46
	v_max_f32_e32 v42, 0, v41
	v_max_f32_e32 v41, v47, v47
	v_max_f32_e32 v43, v43, v43
	v_lshl_add_u64 v[48:49], v[140:141], 0, s[0:1]
	v_pk_mul_f32 v[44:45], v[44:45], v[44:45]
	v_max_f32_e32 v40, 0, v40
	v_max_f32_e32 v41, 0, v41
	v_max_f32_e32 v43, 0, v43
	s_mov_b32 s0, 0x240000
	v_pk_mul_f32 v[46:47], v[40:41], v[40:41]
	v_pk_mul_f32 v[52:53], v[42:43], v[42:43]
	v_cvt_pk_bf16_f32 v40, v44, v45
	v_add_co_u32_e32 v44, vcc, s0, v140
	v_max_f32_e32 v32, v32, v32
	v_max_f32_e32 v33, v33, v33
	v_cvt_pk_bf16_f32 v41, v46, v47
	v_cvt_pk_bf16_f32 v42, v50, v51
	v_cvt_pk_bf16_f32 v43, v52, v53
	v_addc_co_u32_e32 v45, vcc, 0, v141, vcc
	v_max_f32_e32 v32, 0, v32
	v_max_f32_e32 v33, 0, v33
	global_store_dwordx4 v[44:45], v[40:43], off
	v_max_f32_e32 v36, v36, v36
	v_max_f32_e32 v37, v37, v37
	v_pk_mul_f32 v[40:41], v[32:33], v[32:33]
	v_max_f32_e32 v33, v34, v34
	v_max_f32_e32 v32, v38, v38
	v_max_f32_e32 v34, 0, v33
	v_max_f32_e32 v33, v39, v39
	v_max_f32_e32 v35, v35, v35
	v_max_f32_e32 v36, 0, v36
	v_max_f32_e32 v37, 0, v37
	v_max_f32_e32 v32, 0, v32
	v_max_f32_e32 v33, 0, v33
	v_max_f32_e32 v35, 0, v35
	v_pk_mul_f32 v[36:37], v[36:37], v[36:37]
	v_pk_mul_f32 v[38:39], v[32:33], v[32:33]
	v_pk_mul_f32 v[42:43], v[34:35], v[34:35]
	v_max_f32_e32 v24, v24, v24
	v_max_f32_e32 v25, v25, v25
	v_cvt_pk_bf16_f32 v32, v36, v37
	v_cvt_pk_bf16_f32 v33, v38, v39
	v_cvt_pk_bf16_f32 v34, v40, v41
	v_cvt_pk_bf16_f32 v35, v42, v43
	v_max_f32_e32 v24, 0, v24
	v_max_f32_e32 v25, 0, v25
; __device__ __forceinline__ unsigned cvt_pk_bf16(float lo, float hi) { const f32x2_t v = {lo, hi}; const bf16x2_t b = __builtin_convertvector(v, bf16x2_t); return __builtin_bit_cast(unsigned, b); }
;     __device__ __forceinline__ void operator()(const f32x4 (&acc)[2][2][4][2], const Unit& u, int wr, int wc, int fr, int fq) const {
;     ...
;             for (int m = 0; m < 4; ++m) { bf16_t* rowp = O + (size_t)u.zo * zsO + (size_t)(row0 + ai * HALF + m * 16) * ldc + col0;
; #pragma unroll
;                 for (int bj = 0; bj < 2; ++bj) { f32x4 v0 = acc[ai][bj][m][0], v1 = acc[ai][bj][m][1];
;                     if (ACT == 2) {
; #pragma unroll
;                         for (int j = 0; j < 4; ++j) { const float a = fmaxf(v0[j], 0.f), b = fmaxf(v1[j], 0.f); v0[j] = a * a; v1[j] = b * b; } }
;                     u32x4 w; w.x = cvt_pk_bf16(v0[0], v0[1]); w.y = cvt_pk_bf16(v0[2], v0[3]); w.z = cvt_pk_bf16(v1[0], v1[1]); w.w = cvt_pk_bf16(v1[2], v1[3]);
;                     *(u32x4*)(rowp + bj * HALF) = w; } }
	global_store_dwordx4 v[48:49], v[32:35], off offset:256
	v_max_f32_e32 v28, v28, v28
	v_max_f32_e32 v29, v29, v29
	v_pk_mul_f32 v[34:35], v[24:25], v[24:25]
	v_max_f32_e32 v25, v26, v26
	s_mov_b64 s[0:1], 0x280000
	v_max_f32_e32 v28, 0, v28
	v_max_f32_e32 v29, 0, v29
	v_max_f32_e32 v24, v30, v30
	v_max_f32_e32 v26, 0, v25
	v_max_f32_e32 v25, v31, v31
	v_max_f32_e32 v27, v27, v27
	v_lshl_add_u64 v[32:33], v[140:141], 0, s[0:1]
	v_pk_mul_f32 v[28:29], v[28:29], v[28:29]
	v_max_f32_e32 v24, 0, v24
	v_max_f32_e32 v25, 0, v25
	v_max_f32_e32 v27, 0, v27
	s_mov_b32 s0, 0x280000
	v_pk_mul_f32 v[30:31], v[24:25], v[24:25]
	v_pk_mul_f32 v[36:37], v[26:27], v[26:27]
	v_cvt_pk_bf16_f32 v24, v28, v29
	v_add_co_u32_e32 v28, vcc, s0, v140
	v_max_f32_e32 v16, v16, v16
	v_max_f32_e32 v17, v17, v17
	v_cvt_pk_bf16_f32 v25, v30, v31
	v_cvt_pk_bf16_f32 v26, v34, v35
	v_cvt_pk_bf16_f32 v27, v36, v37
	v_addc_co_u32_e32 v29, vcc, 0, v141, vcc
	v_max_f32_e32 v16, 0, v16
	v_max_f32_e32 v17, 0, v17
	global_store_dwordx4 v[28:29], v[24:27], off
	v_max_f32_e32 v20, v20, v20
	v_max_f32_e32 v21, v21, v21
	v_pk_mul_f32 v[24:25], v[16:17], v[16:17]
	v_max_f32_e32 v17, v18, v18
	v_max_f32_e32 v16, v22, v22
	v_max_f32_e32 v18, 0, v17
	v_max_f32_e32 v17, v23, v23
	v_max_f32_e32 v19, v19, v19
	v_max_f32_e32 v20, 0, v20
	v_max_f32_e32 v21, 0, v21
	v_max_f32_e32 v16, 0, v16
	v_max_f32_e32 v17, 0, v17
	v_max_f32_e32 v19, 0, v19
	v_pk_mul_f32 v[20:21], v[20:21], v[20:21]
	v_pk_mul_f32 v[22:23], v[16:17], v[16:17]
	v_pk_mul_f32 v[26:27], v[18:19], v[18:19]
	v_max_f32_e32 v8, v8, v8
	v_max_f32_e32 v9, v9, v9
	v_cvt_pk_bf16_f32 v16, v20, v21
	v_cvt_pk_bf16_f32 v17, v22, v23
	v_cvt_pk_bf16_f32 v18, v24, v25
	v_cvt_pk_bf16_f32 v19, v26, v27
	v_max_f32_e32 v8, 0, v8
	v_max_f32_e32 v9, 0, v9
	global_store_dwordx4 v[32:33], v[16:19], off offset:256
	v_max_f32_e32 v12, v12, v12
	v_max_f32_e32 v13, v13, v13
	v_pk_mul_f32 v[18:19], v[8:9], v[8:9]
	v_max_f32_e32 v9, v10, v10
	s_mov_b64 s[0:1], 0x2c0000
	v_max_f32_e32 v12, 0, v12
	v_max_f32_e32 v13, 0, v13
	v_max_f32_e32 v8, v14, v14
	v_max_f32_e32 v10, 0, v9
	v_max_f32_e32 v9, v15, v15
	v_max_f32_e32 v11, v11, v11
	v_lshl_add_u64 v[16:17], v[140:141], 0, s[0:1]
	v_pk_mul_f32 v[12:13], v[12:13], v[12:13]
	v_max_f32_e32 v8, 0, v8
	v_max_f32_e32 v9, 0, v9
	v_max_f32_e32 v11, 0, v11
	s_mov_b32 s0, 0x2c0000
	v_pk_mul_f32 v[14:15], v[8:9], v[8:9]
	v_pk_mul_f32 v[20:21], v[10:11], v[10:11]
	v_cvt_pk_bf16_f32 v8, v12, v13
	v_add_co_u32_e32 v12, vcc, s0, v140
	v_max_f32_e32 v0, v0, v0
	v_max_f32_e32 v1, v1, v1
	v_cvt_pk_bf16_f32 v9, v14, v15
	v_cvt_pk_bf16_f32 v10, v18, v19
	v_cvt_pk_bf16_f32 v11, v20, v21
	v_addc_co_u32_e32 v13, vcc, 0, v141, vcc
	v_max_f32_e32 v0, 0, v0
	v_max_f32_e32 v1, 0, v1
	global_store_dwordx4 v[12:13], v[8:11], off
	v_max_f32_e32 v4, v4, v4
	v_max_f32_e32 v5, v5, v5
	v_pk_mul_f32 v[8:9], v[0:1], v[0:1]
	v_max_f32_e32 v1, v2, v2
	v_max_f32_e32 v0, v6, v6
	v_max_f32_e32 v2, 0, v1
	v_max_f32_e32 v1, v7, v7
	v_max_f32_e32 v3, v3, v3
	v_max_f32_e32 v4, 0, v4
	v_max_f32_e32 v5, 0, v5
	v_max_f32_e32 v0, 0, v0
	v_max_f32_e32 v1, 0, v1
	v_max_f32_e32 v3, 0, v3
	v_pk_mul_f32 v[4:5], v[4:5], v[4:5]
	v_pk_mul_f32 v[6:7], v[0:1], v[0:1]
	v_pk_mul_f32 v[10:11], v[2:3], v[2:3]
	v_cvt_pk_bf16_f32 v0, v4, v5
	v_cvt_pk_bf16_f32 v1, v6, v7
	v_cvt_pk_bf16_f32 v2, v8, v9
	v_cvt_pk_bf16_f32 v3, v10, v11
	s_andn2_b64 vcc, exec, s[42:43]
	s_mov_b64 s[0:1], -1
	s_mov_b64 s[36:37], 0x80
	global_store_dwordx4 v[16:17], v[0:3], off offset:256
	v_writelane_b32 v244, 1, 63
	s_cbranch_vccnz .LBB0_1567
	s_andn2_b64 vcc, exec, s[2:3]
	s_cbranch_vccnz .LBB0_1566
	s_barrier
	s_branch .LBB0_1566

; #define PG8_STAGE(bufoff, gbase, voff) do { _Pragma("unroll") for (int _i = 0; _i < 2; ++_i) \
;         __builtin_amdgcn_global_load_lds((const unsigned*)((const char*)(gbase) + (voff)[_i]), (PG8_LAS unsigned*)(lds + (bufoff) + ldsw + _i * 8192), 16, 0, 0); } while (0)
; #define PG8_WAIT_V(n) asm volatile("s_waitcnt vmcnt(" #n ")" ::: "memory")
; #define PG8_BAR __builtin_amdgcn_s_barrier()
; template <class Epi, class Sched, bool ALIGN_EPI = false, bool SP2 = false>
; __device__ __forceinline__ void gemm_phase(PG8_LAS unsigned char* lds, const Gemm g, const Sched& S, const Epi& E, const int wave0) {
;     ...
;     if constexpr (SP2) {
;         PG8_STAGE(PG8_SB(0, 0), cB, voffB); PG8_STAGE(PG8_SB(0, 1), cB + hstepB, voffB); PG8_STAGE(PG8_SA(0, 0), cA, voffA); PG8_STAGE(PG8_SA(0, 1), cA + hstepA, voffA);
;         if (wr == 1) PG8_BAR;
;         PG8_WAIT_V(2); PG8_BAR;
;         PG8_STAGE(PG8_SB(1, 0), cB + kstep, voffB); PG8_STAGE(PG8_SA(1, 0), cA + kstep, voffA); PG8_STAGE(PG8_SB(1, 1), cB + hstepB + kstep, voffB);
;         PG8_WAIT_V(6); PG8_BAR;
.LBB0_1675:
	v_lshrrev_b32_e32 v16, 1, v6
	v_and_b32_e32 v16, 24, v16
	v_and_b32_e32 v7, 15, v6
	v_lshlrev_b32_e32 v17, 1, v16
	v_lshlrev_b32_e32 v6, 2, v6
	s_lshl_b32 s1, s1, 5
	v_lshl_or_b32 v140, s2, 6, v7
	v_lshl_or_b32 v7, v7, 6, v17
	s_lshl_b32 s2, s2, 13
	v_and_b32_e32 v6, 32, v6
	s_and_b32 s1, s1, 0x60
	v_lshl_add_u64 v[8:9], s[16:17], 0, v[64:65]
	v_mov_b32_e32 v131, v65
	v_readlane_b32 s12, v246, 46
	v_bitop3_b32 v17, v7, s2, v6 bitop3:0xde
	s_lshl_b32 s2, s1, 7
	v_lshl_add_u64 v[10:11], s[16:17], 0, v[130:131]
	v_mov_b32_e32 v135, v65
	v_readlane_b32 s13, v246, 47
	v_bitop3_b32 v141, v7, s2, v6 bitop3:0xde
	s_add_i32 m0, s21, 0x18000
	v_lshl_add_u64 v[6:7], v[8:9], 0, s[36:37]
	v_lshl_add_u64 v[12:13], s[12:13], 0, v[134:135]
	v_mov_b32_e32 v133, v65
	s_waitcnt vmcnt(2)
	s_barrier
	global_load_lds_dwordx4 v[6:7], off
	v_lshl_add_u64 v[6:7], v[10:11], 0, s[36:37]
	s_add_i32 m0, s21, 0x1a000
	s_add_i32 s28, s21, 0x8000
	s_add_i32 s29, s21, 0xa000
	v_lshl_add_u64 v[14:15], s[12:13], 0, v[132:133]
	global_load_lds_dwordx4 v[6:7], off
	v_lshl_add_u64 v[6:7], v[12:13], 0, s[36:37]
	s_mov_b32 m0, s28
	s_add_u32 s2, s16, 0x200080
	global_load_lds_dwordx4 v[6:7], off
	v_lshl_add_u64 v[6:7], v[14:15], 0, s[36:37]
	s_mov_b32 m0, s29
	s_addc_u32 s3, s17, 0
	global_load_lds_dwordx4 v[6:7], off
	s_add_i32 m0, s21, 0x1c000
	v_lshl_add_u64 v[6:7], s[2:3], 0, v[64:65]
	global_load_lds_dwordx4 v[6:7], off
	v_lshl_add_u64 v[6:7], s[2:3], 0, v[130:131]
	s_add_i32 m0, s21, 0x1e000
	s_cmpk_lt_u32 s0, 0x100
	global_load_lds_dwordx4 v[6:7], off
	v_lshlrev_b32_e32 v6, 17, v4
	v_and_b32_e32 v6, 0xfffc0000, v6
	v_lshl_add_u32 v3, v3, 14, v6
	v_and_b32_e32 v4, 1, v4
	v_lshl_or_b32 v3, v4, 6, v3
	v_lshl_add_u32 v136, v5, 1, v3
	v_lshlrev_b32_e32 v3, 17, v0
	v_and_b32_e32 v3, 0xfffc0000, v3
	v_writelane_b32 v244, 0, 63
	s_waitcnt vmcnt(6)
	v_or_b32_e32 v142, s1, v16
	v_lshl_add_u32 v1, v1, 14, v3
	v_and_b32_e32 v0, 1, v0
	v_readlane_b32 s0, v246, 42
	v_lshl_or_b32 v0, v0, 6, v1
	v_readlane_b32 s1, v246, 43
	s_cselect_b64 s[6:7], -1, 0
	v_mov_b32_e32 v137, v65
	v_lshl_add_u32 v138, v2, 1, v0
	v_mov_b32_e32 v139, v65
	s_mov_b32 s30, 0
	v_add_u32_e32 v143, 0, v17
	v_readlane_b32 s31, v246, 39
	s_mov_b32 s33, s0
	s_mov_b64 s[0:1], s[12:13]
	s_barrier
	s_branch .LBB0_1678

;     __host__ __device__ bool next(int i, Unit& u) const { return tile((long)i * G + c, u); }
;     __host__ __device__ bool next(int i, Unit& u) const { if (!tile((long)(i / NZ) * G + c, u)) return false; u.z = i % NZ; return true; }
; #define PG8_STAGE(bufoff, gbase, voff) do { _Pragma("unroll") for (int _i = 0; _i < 2; ++_i) \
;         __builtin_amdgcn_global_load_lds((const unsigned*)((const char*)(gbase) + (voff)[_i]), (PG8_LAS unsigned*)(lds + (bufoff) + ldsw + _i * 8192), 16, 0, 0); } while (0)
; #define PG8_LDA(dst, b, h) do { _Pragma("unroll") for (int m = 0; m < 4; ++m) _Pragma("unroll") for (int k = 0; k < 2; ++k) dst[m][k] = *(const PG8_LAS bf16x8*)(lds + PG8_SA(b, h) + aoff + m * 2048 + k * 1024); } while (0)
; #define PG8_LDB(dst, b, h) do { _Pragma("unroll") for (int n = 0; n < 2; ++n) _Pragma("unroll") for (int k = 0; k < 2; ++k) dst[n][k] = *(const PG8_LAS bf16x8*)(lds + PG8_SB(b, h) + boff + n * 2048 + k * 1024); } while (0)
; template <class Epi, class Sched, bool ALIGN_EPI = false, bool SP2 = false>
; __device__ __forceinline__ void gemm_phase(PG8_LAS unsigned char* lds, const Gemm g, const Sched& S, const Epi& E, const int wave0) {
;     ...
;         const bool has_next = S.next(ui + 1, nxt);
;         const char* nA = has_next ? (const char*)g.A + (size_t)nxt.z * g.zsA + (size_t)nxt.pm * tstepA + (size_t)nxt.k0 * 2 : cA; const char* nB = has_next ? (const char*)g.Bt + (size_t)nxt.z * g.zsB + (size_t)nxt.pn * tstepB + (size_t)nxt.k0 * 2 : cB;
;         for (int t = 0; t < nt; t += 2) {
;             const bool last = (t == nt - 2);
;             const char* a1 = cA + (size_t)(t + 1) * kstep;
;             const char* a2 = last ? nA : cA + (size_t)(t + 2) * kstep; const char* b2 = last ? nB : cB + (size_t)(t + 2) * kstep;
;             const char* a3 = a2 + kstep; const char* b3 = b2 + kstep;
;             if (last && has_next) S.a_ready(nxt);
;             if constexpr (SP2) {
;             PG8_LDB(B0, 0, 0); PG8_LDB(B1, 0, 1); PG8_SCHED; PG8_LDA(At, 0, 0); PG8_STAGE(PG8_SA(1, 1), a1 + hstepA, voffA);
;     ...
; #pragma unroll
;         for (int a = 0; a < 2; ++a)
; #pragma unroll
;             for (int b = 0; b < 2; ++b)
; #pragma unroll
;                 for (int m = 0; m < 4; ++m)
; #pragma unroll
;                     for (int n = 0; n < 2; ++n) acc[a][b][m][n] = (f32x4){0.f, 0.f, 0.f, 0.f};
;         cur = nxt; cA = nA; cB = nB; ++ui;
.LBB0_1684:
	s_ashr_i32 s11, s10, 31
	s_lshl_b64 s[12:13], s[10:11], 22
	v_readlane_b32 s14, v246, 44
	v_readlane_b32 s15, v246, 45
	s_add_u32 s12, s14, s12
	s_addc_u32 s13, s15, s13
	s_and_b64 s[14:15], s[2:3], exec
	s_cselect_b32 s11, s13, s1
	s_cselect_b32 s34, s12, s0
	s_ashr_i32 s9, s8, 31
	s_lshl_b64 s[14:15], s[8:9], 22
	s_add_u32 s14, s23, s14
	s_addc_u32 s15, s24, s15
	s_and_b64 s[18:19], s[2:3], exec
	s_cselect_b32 s9, s15, s17
	s_cselect_b32 s35, s14, s16
	s_add_u32 s0, s0, 0x200080
	s_addc_u32 s1, s1, 0
	s_add_u32 s36, s16, 0x100
	v_mov_b32_e32 v0, 0
	s_addc_u32 s37, s17, 0
	s_mov_b32 s42, -2
	v_mov_b32_e32 v1, v0
	v_mov_b64_e32 v[2:3], 0
	v_mov_b64_e32 v[4:5], 0
	v_mov_b64_e32 v[6:7], 0
	v_mov_b64_e32 v[8:9], 0
	v_mov_b64_e32 v[10:11], 0
	v_mov_b64_e32 v[12:13], 0
	v_mov_b64_e32 v[14:15], 0
	v_mov_b64_e32 v[24:25], 0
	v_mov_b64_e32 v[26:27], 0
	v_mov_b64_e32 v[28:29], 0
	v_mov_b64_e32 v[30:31], 0
	v_mov_b64_e32 v[40:41], 0
	v_mov_b64_e32 v[42:43], 0
	v_mov_b64_e32 v[44:45], 0
	v_mov_b64_e32 v[46:47], 0
	v_mov_b64_e32 v[16:17], 0
	v_mov_b64_e32 v[18:19], 0
	v_mov_b64_e32 v[20:21], 0
	v_mov_b64_e32 v[22:23], 0
	v_mov_b64_e32 v[32:33], 0
	v_mov_b64_e32 v[34:35], 0
	v_mov_b64_e32 v[36:37], 0
	v_mov_b64_e32 v[38:39], 0
	v_mov_b64_e32 v[48:49], 0
	v_mov_b64_e32 v[50:51], 0
	v_mov_b64_e32 v[52:53], 0
	v_mov_b64_e32 v[54:55], 0
	v_mov_b64_e32 v[56:57], 0
	v_mov_b64_e32 v[58:59], 0
	v_mov_b64_e32 v[60:61], 0
	v_mov_b64_e32 v[62:63], 0
	v_mov_b64_e32 v[66:67], 0
	v_mov_b64_e32 v[68:69], 0
	v_mov_b64_e32 v[70:71], 0
	v_mov_b64_e32 v[72:73], 0
	v_mov_b64_e32 v[74:75], 0
	v_mov_b64_e32 v[76:77], 0
	v_mov_b64_e32 v[78:79], 0
	v_mov_b64_e32 v[80:81], 0
	v_mov_b64_e32 v[90:91], 0
	v_mov_b64_e32 v[92:93], 0
	v_mov_b64_e32 v[94:95], 0
	v_mov_b64_e32 v[96:97], 0
	v_mov_b64_e32 v[106:107], 0
	v_mov_b64_e32 v[108:109], 0
	v_mov_b64_e32 v[110:111], 0
	v_mov_b64_e32 v[112:113], 0
	v_mov_b64_e32 v[82:83], 0
	v_mov_b64_e32 v[84:85], 0
	v_mov_b64_e32 v[86:87], 0
	v_mov_b64_e32 v[88:89], 0
	v_mov_b64_e32 v[98:99], 0
	v_mov_b64_e32 v[100:101], 0
	v_mov_b64_e32 v[102:103], 0
	v_mov_b64_e32 v[104:105], 0
	v_mov_b64_e32 v[114:115], 0
	v_mov_b64_e32 v[116:117], 0
	v_mov_b64_e32 v[118:119], 0
	v_mov_b64_e32 v[120:121], 0
	v_mov_b64_e32 v[122:123], 0
	v_mov_b64_e32 v[124:125], 0
	v_mov_b64_e32 v[126:127], 0
	v_mov_b64_e32 v[128:129], 0
	s_mov_b64 s[48:49], 0x80
	v_add_u32_e32 v252, 0x10000, v141
	v_add_u32_e32 v253, 0x14000, v141
	v_add_u32_e32 v254, 0x18000, v141
	v_add_u32_e32 v255, 0x1c000, v141
	v_readlane_b32 s48, v244, 63
	v_writelane_b32 v244, 0, 63
.LBB0_1685:
	s_add_u32 s16, s0, 0xffe00080
	s_addc_u32 s17, s1, -1
	s_add_i32 s43, 0, 0x10000
	s_cmpk_eq_i32 s42, 0x7c
	s_cselect_b32 s19, s11, s17
	s_cselect_b32 s18, s34, s16
	s_cselect_b32 s17, s9, s37
	s_cselect_b32 s16, s35, s36
	s_add_i32 s46, 0, 0x14000
	ds_read_b128 v[144:147], v252
	ds_read_b128 v[148:151], v252 offset:1024
	ds_read_b128 v[152:155], v252 offset:2048
	ds_read_b128 v[156:159], v252 offset:3072
	ds_read_b128 v[178:181], v253
	ds_read_b128 v[182:185], v253 offset:1024
	ds_read_b128 v[186:189], v253 offset:2048
	ds_read_b128 v[190:193], v253 offset:3072
	s_add_i32 m0, s21, 0xc000
	ds_read_b128 v[194:197], v143
	ds_read_b128 v[208:211], v143 offset:1024
	ds_read_b128 v[212:215], v143 offset:2048
	ds_read_b128 v[216:219], v143 offset:3072
	ds_read_b128 v[220:223], v143 offset:4096
	ds_read_b128 v[224:227], v143 offset:5120
	ds_read_b128 v[228:231], v143 offset:6144
	ds_read_b128 v[232:235], v143 offset:7168
	global_load_lds_dwordx4 v136, s[0:1]
	s_add_i32 m0, s21, 0xe000
	s_nop 0
	global_load_lds_dwordx4 v138, s[0:1]
	s_cmp_eq_u32 s48, 1
	s_cbranch_scc0 .Ldf4_0n
	s_waitcnt vmcnt(24)
	s_branch .Ldf4_0d

; #define PG8_STAGE(bufoff, gbase, voff) do { _Pragma("unroll") for (int _i = 0; _i < 2; ++_i) \
;         __builtin_amdgcn_global_load_lds((const unsigned*)((const char*)(gbase) + (voff)[_i]), (PG8_LAS unsigned*)(lds + (bufoff) + ldsw + _i * 8192), 16, 0, 0); } while (0)
; #define PG8_LDA(dst, b, h) do { _Pragma("unroll") for (int m = 0; m < 4; ++m) _Pragma("unroll") for (int k = 0; k < 2; ++k) dst[m][k] = *(const PG8_LAS bf16x8*)(lds + PG8_SA(b, h) + aoff + m * 2048 + k * 1024); } while (0)
; #define PG8_MMA(ai, bj, At, Bt) do { __builtin_amdgcn_s_setprio(1); _Pragma("unroll") for (int m = 0; m < 4; ++m) _Pragma("unroll") for (int n = 0; n < 2; ++n) _Pragma("unroll") for (int k = 0; k < 2; ++k) \
;         acc[ai][bj][m][n] = __builtin_amdgcn_mfma_f32_16x16x32_bf16(Bt[n][k], At[m][k], acc[ai][bj][m][n], 0, 0, 0); __builtin_amdgcn_s_setprio(0); } while (0)
; #define PG8_WAIT_V(n) asm volatile("s_waitcnt vmcnt(" #n ")" ::: "memory")
; #define PG8_WAIT_L(n) asm volatile("s_waitcnt lgkmcnt(" #n ")" ::: "memory")
; #define PG8_BAR __builtin_amdgcn_s_barrier()
; #define PG8_SCHED __builtin_amdgcn_sched_barrier(0)
; template <class Epi, class Sched, bool ALIGN_EPI = false, bool SP2 = false>
; __device__ __forceinline__ void gemm_phase(PG8_LAS unsigned char* lds, const Gemm g, const Sched& S, const Epi& E, const int wave0) {
;     ...
;             PG8_WAIT_V(8); PG8_WAIT_L(0); PG8_BAR; PG8_MMA(0, 0, At, B0); PG8_MMA(0, 1, At, B1); PG8_BAR; PG8_SCHED;
;             PG8_LDA(At, 0, 1); PG8_STAGE(PG8_SB(0, 0), b2, voffB); PG8_STAGE(PG8_SB(0, 1), b2 + hstepB, voffB); PG8_STAGE(PG8_SA(0, 0), a2, voffA);
;             PG8_WAIT_V(8); PG8_WAIT_L(0); PG8_BAR; PG8_MMA(1, 0, At, B0); PG8_MMA(1, 1, At, B1); PG8_BAR; PG8_SCHED;
.Ldf4_0d:
	s_waitcnt lgkmcnt(0)
	s_barrier
	s_setprio 1
	s_waitcnt lgkmcnt(0)
	v_mfma_f32_16x16x32_bf16 v[126:129], v[144:147], v[194:197], v[126:129]
	v_mfma_f32_16x16x32_bf16 v[122:125], v[152:155], v[194:197], v[122:125]
	v_mfma_f32_16x16x32_bf16 v[118:121], v[144:147], v[212:215], v[118:121]
	v_mfma_f32_16x16x32_bf16 v[114:117], v[152:155], v[212:215], v[114:117]
	v_mfma_f32_16x16x32_bf16 v[102:105], v[144:147], v[220:223], v[102:105]
	v_mfma_f32_16x16x32_bf16 v[98:101], v[152:155], v[220:223], v[98:101]
	v_mfma_f32_16x16x32_bf16 v[86:89], v[144:147], v[228:231], v[86:89]
	v_mfma_f32_16x16x32_bf16 v[82:85], v[152:155], v[228:231], v[82:85]
	v_mfma_f32_16x16x32_bf16 v[126:129], v[148:151], v[208:211], v[126:129]
	v_mfma_f32_16x16x32_bf16 v[122:125], v[156:159], v[208:211], v[122:125]
	v_mfma_f32_16x16x32_bf16 v[118:121], v[148:151], v[216:219], v[118:121]
	v_mfma_f32_16x16x32_bf16 v[114:117], v[156:159], v[216:219], v[114:117]
	v_mfma_f32_16x16x32_bf16 v[102:105], v[148:151], v[224:227], v[102:105]
	v_mfma_f32_16x16x32_bf16 v[98:101], v[156:159], v[224:227], v[98:101]
	v_mfma_f32_16x16x32_bf16 v[86:89], v[148:151], v[232:235], v[86:89]
	v_mfma_f32_16x16x32_bf16 v[82:85], v[156:159], v[232:235], v[82:85]
	s_setprio 0
	s_setprio 1
	v_mfma_f32_16x16x32_bf16 v[110:113], v[178:181], v[194:197], v[110:113]
	v_mfma_f32_16x16x32_bf16 v[106:109], v[186:189], v[194:197], v[106:109]
	v_mfma_f32_16x16x32_bf16 v[94:97], v[178:181], v[212:215], v[94:97]
	v_mfma_f32_16x16x32_bf16 v[90:93], v[186:189], v[212:215], v[90:93]
	v_mfma_f32_16x16x32_bf16 v[78:81], v[178:181], v[220:223], v[78:81]
	v_mfma_f32_16x16x32_bf16 v[74:77], v[186:189], v[220:223], v[74:77]
	v_mfma_f32_16x16x32_bf16 v[70:73], v[178:181], v[228:231], v[70:73]
	v_mfma_f32_16x16x32_bf16 v[66:69], v[186:189], v[228:231], v[66:69]
	v_mfma_f32_16x16x32_bf16 v[110:113], v[182:185], v[208:211], v[110:113]
	v_mfma_f32_16x16x32_bf16 v[106:109], v[190:193], v[208:211], v[106:109]
	v_mfma_f32_16x16x32_bf16 v[94:97], v[182:185], v[216:219], v[94:97]
	v_mfma_f32_16x16x32_bf16 v[90:93], v[190:193], v[216:219], v[90:93]
	v_mfma_f32_16x16x32_bf16 v[78:81], v[182:185], v[224:227], v[78:81]
	v_mfma_f32_16x16x32_bf16 v[74:77], v[190:193], v[224:227], v[74:77]
	v_mfma_f32_16x16x32_bf16 v[70:73], v[182:185], v[232:235], v[70:73]
	v_mfma_f32_16x16x32_bf16 v[66:69], v[190:193], v[232:235], v[66:69]
	s_setprio 0
	s_barrier
	s_add_i32 s43, s43, s20
	s_mov_b32 m0, s43
	ds_read_b128 v[194:197], v143 offset:16384
	ds_read_b128 v[208:211], v143 offset:17408
	ds_read_b128 v[212:215], v143 offset:18432
	ds_read_b128 v[216:219], v143 offset:19456
	ds_read_b128 v[220:223], v143 offset:20480
	ds_read_b128 v[224:227], v143 offset:21504
	ds_read_b128 v[228:231], v143 offset:22528
	ds_read_b128 v[232:235], v143 offset:23552
	global_load_lds_dwordx4 v64, s[16:17]
	s_add_i32 m0, s43, 0x2000
	s_add_u32 s44, s16, 0x200000
	s_addc_u32 s45, s17, 0
	s_add_i32 s43, s46, s20
	global_load_lds_dwordx4 v130, s[16:17]
	s_mov_b32 m0, s43
	s_mov_b64 s[100:101], s[18:19]
	global_load_lds_dwordx4 v64, s[44:45]
	s_add_i32 m0, s43, 0x2000
	s_nop 0
	global_load_lds_dwordx4 v130, s[44:45]
	s_mov_b32 m0, s21
	s_nop 0
	global_load_lds_dwordx4 v134, s[18:19]
	s_mov_b32 m0, s25
	s_nop 0
	global_load_lds_dwordx4 v132, s[18:19]
	s_cmp_eq_u32 s48, 1
	s_cbranch_scc0 .Ldf4_1n
	s_waitcnt vmcnt(24)
	s_mov_b32 s48, 0
	s_branch .Ldf4_1d

; #define PG8_STAGE(bufoff, gbase, voff) do { _Pragma("unroll") for (int _i = 0; _i < 2; ++_i) \
;         __builtin_amdgcn_global_load_lds((const unsigned*)((const char*)(gbase) + (voff)[_i]), (PG8_LAS unsigned*)(lds + (bufoff) + ldsw + _i * 8192), 16, 0, 0); } while (0)
; #define PG8_LDA(dst, b, h) do { _Pragma("unroll") for (int m = 0; m < 4; ++m) _Pragma("unroll") for (int k = 0; k < 2; ++k) dst[m][k] = *(const PG8_LAS bf16x8*)(lds + PG8_SA(b, h) + aoff + m * 2048 + k * 1024); } while (0)
; #define PG8_LDB(dst, b, h) do { _Pragma("unroll") for (int n = 0; n < 2; ++n) _Pragma("unroll") for (int k = 0; k < 2; ++k) dst[n][k] = *(const PG8_LAS bf16x8*)(lds + PG8_SB(b, h) + boff + n * 2048 + k * 1024); } while (0)
; #define PG8_MMA(ai, bj, At, Bt) do { __builtin_amdgcn_s_setprio(1); _Pragma("unroll") for (int m = 0; m < 4; ++m) _Pragma("unroll") for (int n = 0; n < 2; ++n) _Pragma("unroll") for (int k = 0; k < 2; ++k) \
;         acc[ai][bj][m][n] = __builtin_amdgcn_mfma_f32_16x16x32_bf16(Bt[n][k], At[m][k], acc[ai][bj][m][n], 0, 0, 0); __builtin_amdgcn_s_setprio(0); } while (0)
; #define PG8_WAIT_V(n) asm volatile("s_waitcnt vmcnt(" #n ")" ::: "memory")
; #define PG8_WAIT_L(n) asm volatile("s_waitcnt lgkmcnt(" #n ")" ::: "memory")
; #define PG8_BAR __builtin_amdgcn_s_barrier()
; #define PG8_SCHED __builtin_amdgcn_sched_barrier(0)
; template <class Epi, class Sched, bool ALIGN_EPI = false, bool SP2 = false>
; __device__ __forceinline__ void gemm_phase(PG8_LAS unsigned char* lds, const Gemm g, const Sched& S, const Epi& E, const int wave0) {
;     ...
;             PG8_WAIT_V(8); PG8_WAIT_L(0); PG8_BAR; PG8_MMA(1, 0, At, B0); PG8_MMA(1, 1, At, B1); PG8_BAR; PG8_SCHED;
;             PG8_LDB(B0, 1, 0); PG8_LDB(B1, 1, 1); PG8_SCHED; PG8_LDA(At, 1, 0); PG8_STAGE(PG8_SA(0, 1), a2 + hstepA, voffA);
;             PG8_WAIT_V(8); PG8_WAIT_L(0); PG8_BAR; PG8_MMA(0, 0, At, B0); PG8_MMA(0, 1, At, B1); PG8_BAR; PG8_SCHED;
.Ldf4_1d:
	s_waitcnt lgkmcnt(0)
	s_barrier
	s_setprio 1
	s_waitcnt lgkmcnt(0)
	v_mfma_f32_16x16x32_bf16 v[60:63], v[144:147], v[194:197], v[60:63]
	v_mfma_f32_16x16x32_bf16 v[56:59], v[152:155], v[194:197], v[56:59]
	v_mfma_f32_16x16x32_bf16 v[52:55], v[144:147], v[212:215], v[52:55]
	v_mfma_f32_16x16x32_bf16 v[48:51], v[152:155], v[212:215], v[48:51]
	v_mfma_f32_16x16x32_bf16 v[36:39], v[144:147], v[220:223], v[36:39]
	v_mfma_f32_16x16x32_bf16 v[32:35], v[152:155], v[220:223], v[32:35]
	v_mfma_f32_16x16x32_bf16 v[20:23], v[144:147], v[228:231], v[20:23]
	v_mfma_f32_16x16x32_bf16 v[16:19], v[152:155], v[228:231], v[16:19]
	v_mfma_f32_16x16x32_bf16 v[60:63], v[148:151], v[208:211], v[60:63]
	v_mfma_f32_16x16x32_bf16 v[56:59], v[156:159], v[208:211], v[56:59]
	v_mfma_f32_16x16x32_bf16 v[52:55], v[148:151], v[216:219], v[52:55]
	v_mfma_f32_16x16x32_bf16 v[48:51], v[156:159], v[216:219], v[48:51]
	v_mfma_f32_16x16x32_bf16 v[36:39], v[148:151], v[224:227], v[36:39]
	v_mfma_f32_16x16x32_bf16 v[32:35], v[156:159], v[224:227], v[32:35]
	v_mfma_f32_16x16x32_bf16 v[20:23], v[148:151], v[232:235], v[20:23]
	v_mfma_f32_16x16x32_bf16 v[16:19], v[156:159], v[232:235], v[16:19]
	s_setprio 0
	s_setprio 1
	v_mfma_f32_16x16x32_bf16 v[44:47], v[178:181], v[194:197], v[44:47]
	v_mfma_f32_16x16x32_bf16 v[40:43], v[186:189], v[194:197], v[40:43]
	v_mfma_f32_16x16x32_bf16 v[28:31], v[178:181], v[212:215], v[28:31]
	v_mfma_f32_16x16x32_bf16 v[24:27], v[186:189], v[212:215], v[24:27]
	v_mfma_f32_16x16x32_bf16 v[12:15], v[178:181], v[220:223], v[12:15]
	v_mfma_f32_16x16x32_bf16 v[8:11], v[186:189], v[220:223], v[8:11]
	v_mfma_f32_16x16x32_bf16 v[4:7], v[178:181], v[228:231], v[4:7]
	v_mfma_f32_16x16x32_bf16 v[0:3], v[186:189], v[228:231], v[0:3]
	v_mfma_f32_16x16x32_bf16 v[44:47], v[182:185], v[208:211], v[44:47]
	v_mfma_f32_16x16x32_bf16 v[40:43], v[190:193], v[208:211], v[40:43]
	v_mfma_f32_16x16x32_bf16 v[28:31], v[182:185], v[216:219], v[28:31]
	v_mfma_f32_16x16x32_bf16 v[24:27], v[190:193], v[216:219], v[24:27]
	v_mfma_f32_16x16x32_bf16 v[12:15], v[182:185], v[224:227], v[12:15]
	v_mfma_f32_16x16x32_bf16 v[8:11], v[190:193], v[224:227], v[8:11]
	v_mfma_f32_16x16x32_bf16 v[4:7], v[182:185], v[232:235], v[4:7]
	v_mfma_f32_16x16x32_bf16 v[0:3], v[190:193], v[232:235], v[0:3]
	s_setprio 0
	s_barrier
	s_add_i32 s43, 0, 0x18000
	s_add_i32 s44, 0, 0x1c000
	ds_read_b128 v[144:147], v254
	ds_read_b128 v[148:151], v254 offset:1024
	ds_read_b128 v[152:155], v254 offset:2048
	ds_read_b128 v[156:159], v254 offset:3072
	ds_read_b128 v[178:181], v255
	ds_read_b128 v[182:185], v255 offset:1024
	ds_read_b128 v[186:189], v255 offset:2048
	ds_read_b128 v[190:193], v255 offset:3072
	s_add_u32 s18, s18, 0x200000
	s_addc_u32 s19, s19, 0
	s_mov_b32 m0, s26
	ds_read_b128 v[194:197], v143 offset:32768
	ds_read_b128 v[208:211], v143 offset:33792
	ds_read_b128 v[212:215], v143 offset:34816
	ds_read_b128 v[216:219], v143 offset:35840
	ds_read_b128 v[220:223], v143 offset:36864
	ds_read_b128 v[224:227], v143 offset:37888
	ds_read_b128 v[228:231], v143 offset:38912
	ds_read_b128 v[232:235], v143 offset:39936
	global_load_lds_dwordx4 v134, s[18:19]
	s_mov_b32 m0, s27
	s_nop 0
	global_load_lds_dwordx4 v132, s[18:19]
	s_waitcnt vmcnt(8)
	s_waitcnt lgkmcnt(0)
	s_barrier
	s_setprio 1
	s_waitcnt lgkmcnt(0)
	v_mfma_f32_16x16x32_bf16 v[126:129], v[144:147], v[194:197], v[126:129]
	v_mfma_f32_16x16x32_bf16 v[122:125], v[152:155], v[194:197], v[122:125]
	v_mfma_f32_16x16x32_bf16 v[118:121], v[144:147], v[212:215], v[118:121]
	v_mfma_f32_16x16x32_bf16 v[114:117], v[152:155], v[212:215], v[114:117]
	v_mfma_f32_16x16x32_bf16 v[102:105], v[144:147], v[220:223], v[102:105]
	v_mfma_f32_16x16x32_bf16 v[98:101], v[152:155], v[220:223], v[98:101]
	v_mfma_f32_16x16x32_bf16 v[86:89], v[144:147], v[228:231], v[86:89]
	v_mfma_f32_16x16x32_bf16 v[82:85], v[152:155], v[228:231], v[82:85]
	v_mfma_f32_16x16x32_bf16 v[126:129], v[148:151], v[208:211], v[126:129]
	v_mfma_f32_16x16x32_bf16 v[122:125], v[156:159], v[208:211], v[122:125]
	v_mfma_f32_16x16x32_bf16 v[118:121], v[148:151], v[216:219], v[118:121]
	v_mfma_f32_16x16x32_bf16 v[114:117], v[156:159], v[216:219], v[114:117]
	v_mfma_f32_16x16x32_bf16 v[102:105], v[148:151], v[224:227], v[102:105]
	v_mfma_f32_16x16x32_bf16 v[98:101], v[156:159], v[224:227], v[98:101]
	v_mfma_f32_16x16x32_bf16 v[86:89], v[148:151], v[232:235], v[86:89]
	v_mfma_f32_16x16x32_bf16 v[82:85], v[156:159], v[232:235], v[82:85]
	s_setprio 0
	s_setprio 1
	v_mfma_f32_16x16x32_bf16 v[110:113], v[178:181], v[194:197], v[110:113]
	v_mfma_f32_16x16x32_bf16 v[106:109], v[186:189], v[194:197], v[106:109]
	v_mfma_f32_16x16x32_bf16 v[94:97], v[178:181], v[212:215], v[94:97]
	v_mfma_f32_16x16x32_bf16 v[90:93], v[186:189], v[212:215], v[90:93]
	v_mfma_f32_16x16x32_bf16 v[78:81], v[178:181], v[220:223], v[78:81]
	v_mfma_f32_16x16x32_bf16 v[74:77], v[186:189], v[220:223], v[74:77]
	v_mfma_f32_16x16x32_bf16 v[70:73], v[178:181], v[228:231], v[70:73]
	v_mfma_f32_16x16x32_bf16 v[66:69], v[186:189], v[228:231], v[66:69]
	v_mfma_f32_16x16x32_bf16 v[110:113], v[182:185], v[208:211], v[110:113]
	v_mfma_f32_16x16x32_bf16 v[106:109], v[190:193], v[208:211], v[106:109]
	v_mfma_f32_16x16x32_bf16 v[94:97], v[182:185], v[216:219], v[94:97]
	v_mfma_f32_16x16x32_bf16 v[90:93], v[190:193], v[216:219], v[90:93]
	v_mfma_f32_16x16x32_bf16 v[78:81], v[182:185], v[224:227], v[78:81]
	v_mfma_f32_16x16x32_bf16 v[74:77], v[190:193], v[224:227], v[74:77]
	v_mfma_f32_16x16x32_bf16 v[70:73], v[182:185], v[232:235], v[70:73]
	v_mfma_f32_16x16x32_bf16 v[66:69], v[190:193], v[232:235], v[66:69]
	s_setprio 0
	s_barrier
; #define PG8_STAGE(bufoff, gbase, voff) do { _Pragma("unroll") for (int _i = 0; _i < 2; ++_i) \
;         __builtin_amdgcn_global_load_lds((const unsigned*)((const char*)(gbase) + (voff)[_i]), (PG8_LAS unsigned*)(lds + (bufoff) + ldsw + _i * 8192), 16, 0, 0); } while (0)
; #define PG8_LDA(dst, b, h) do { _Pragma("unroll") for (int m = 0; m < 4; ++m) _Pragma("unroll") for (int k = 0; k < 2; ++k) dst[m][k] = *(const PG8_LAS bf16x8*)(lds + PG8_SA(b, h) + aoff + m * 2048 + k * 1024); } while (0)
; #define PG8_MMA(ai, bj, At, Bt) do { __builtin_amdgcn_s_setprio(1); _Pragma("unroll") for (int m = 0; m < 4; ++m) _Pragma("unroll") for (int n = 0; n < 2; ++n) _Pragma("unroll") for (int k = 0; k < 2; ++k) \
;         acc[ai][bj][m][n] = __builtin_amdgcn_mfma_f32_16x16x32_bf16(Bt[n][k], At[m][k], acc[ai][bj][m][n], 0, 0, 0); __builtin_amdgcn_s_setprio(0); } while (0)
; #define PG8_WAIT_V(n) asm volatile("s_waitcnt vmcnt(" #n ")" ::: "memory")
; #define PG8_WAIT_L(n) asm volatile("s_waitcnt lgkmcnt(" #n ")" ::: "memory")
; #define PG8_BAR __builtin_amdgcn_s_barrier()
; #define PG8_SCHED __builtin_amdgcn_sched_barrier(0)
; template <class Epi, class Sched, bool ALIGN_EPI = false, bool SP2 = false>
; __device__ __forceinline__ void gemm_phase(PG8_LAS unsigned char* lds, const Gemm g, const Sched& S, const Epi& E, const int wave0) {
;     ...
;             PG8_LDA(At, 1, 1); PG8_STAGE(PG8_SB(1, 0), b3, voffB); PG8_STAGE(PG8_SB(1, 1), b3 + hstepB, voffB); PG8_STAGE(PG8_SA(1, 0), a3, voffA);
;             PG8_WAIT_V(8); PG8_WAIT_L(0); PG8_BAR; PG8_MMA(1, 0, At, B0); PG8_MMA(1, 1, At, B1); PG8_BAR; PG8_SCHED;
	s_add_i32 s18, s43, s20
	s_add_u32 s48, s16, 0x80
	s_addc_u32 s49, s17, 0
	s_mov_b32 m0, s18
	ds_read_b128 v[194:197], v143 offset:49152
	ds_read_b128 v[208:211], v143 offset:50176
	ds_read_b128 v[212:215], v143 offset:51200
	ds_read_b128 v[216:219], v143 offset:52224
	ds_read_b128 v[220:223], v143 offset:53248
	ds_read_b128 v[224:227], v143 offset:54272
	ds_read_b128 v[228:231], v143 offset:55296
	ds_read_b128 v[232:235], v143 offset:56320
	global_load_lds_dwordx4 v64, s[48:49]
	s_add_i32 m0, s18, 0x2000
	s_add_u32 s16, s16, 0x200080
	s_addc_u32 s17, s17, 0
	s_add_i32 s18, s44, s20
	global_load_lds_dwordx4 v130, s[48:49]
	s_mov_b32 m0, s18
	s_nop 0
	global_load_lds_dwordx4 v64, s[16:17]
	s_add_i32 m0, s18, 0x2000
	s_nop 0
	global_load_lds_dwordx4 v130, s[16:17]
	s_add_u32 s100, s100, 0x80
	s_addc_u32 s101, s101, 0
	s_mov_b32 m0, s28
	s_nop 0
	global_load_lds_dwordx4 v134, s[100:101]
	s_mov_b32 m0, s29
	s_nop 0
	global_load_lds_dwordx4 v132, s[100:101]
	s_waitcnt vmcnt(8)
	s_waitcnt lgkmcnt(0)
	s_barrier
	s_setprio 1
	s_waitcnt lgkmcnt(0)
	v_mfma_f32_16x16x32_bf16 v[60:63], v[144:147], v[194:197], v[60:63]
	v_mfma_f32_16x16x32_bf16 v[56:59], v[152:155], v[194:197], v[56:59]
	v_mfma_f32_16x16x32_bf16 v[52:55], v[144:147], v[212:215], v[52:55]
	v_mfma_f32_16x16x32_bf16 v[48:51], v[152:155], v[212:215], v[48:51]
	v_mfma_f32_16x16x32_bf16 v[36:39], v[144:147], v[220:223], v[36:39]
	v_mfma_f32_16x16x32_bf16 v[32:35], v[152:155], v[220:223], v[32:35]
	v_mfma_f32_16x16x32_bf16 v[20:23], v[144:147], v[228:231], v[20:23]
	v_mfma_f32_16x16x32_bf16 v[16:19], v[152:155], v[228:231], v[16:19]
	v_mfma_f32_16x16x32_bf16 v[60:63], v[148:151], v[208:211], v[60:63]
	v_mfma_f32_16x16x32_bf16 v[56:59], v[156:159], v[208:211], v[56:59]
	v_mfma_f32_16x16x32_bf16 v[52:55], v[148:151], v[216:219], v[52:55]
	v_mfma_f32_16x16x32_bf16 v[48:51], v[156:159], v[216:219], v[48:51]
	v_mfma_f32_16x16x32_bf16 v[36:39], v[148:151], v[224:227], v[36:39]
	v_mfma_f32_16x16x32_bf16 v[32:35], v[156:159], v[224:227], v[32:35]
	v_mfma_f32_16x16x32_bf16 v[20:23], v[148:151], v[232:235], v[20:23]
	v_mfma_f32_16x16x32_bf16 v[16:19], v[156:159], v[232:235], v[16:19]
	s_setprio 0
	s_setprio 1
	v_mfma_f32_16x16x32_bf16 v[44:47], v[178:181], v[194:197], v[44:47]
	v_mfma_f32_16x16x32_bf16 v[40:43], v[186:189], v[194:197], v[40:43]
	v_mfma_f32_16x16x32_bf16 v[28:31], v[178:181], v[212:215], v[28:31]
	v_mfma_f32_16x16x32_bf16 v[24:27], v[186:189], v[212:215], v[24:27]
	v_mfma_f32_16x16x32_bf16 v[12:15], v[178:181], v[220:223], v[12:15]
	v_mfma_f32_16x16x32_bf16 v[8:11], v[186:189], v[220:223], v[8:11]
	v_mfma_f32_16x16x32_bf16 v[4:7], v[178:181], v[228:231], v[4:7]
	v_mfma_f32_16x16x32_bf16 v[0:3], v[186:189], v[228:231], v[0:3]
	v_mfma_f32_16x16x32_bf16 v[44:47], v[182:185], v[208:211], v[44:47]
	v_mfma_f32_16x16x32_bf16 v[40:43], v[190:193], v[208:211], v[40:43]
	v_mfma_f32_16x16x32_bf16 v[28:31], v[182:185], v[216:219], v[28:31]
	v_mfma_f32_16x16x32_bf16 v[24:27], v[190:193], v[216:219], v[24:27]
	v_mfma_f32_16x16x32_bf16 v[12:15], v[182:185], v[224:227], v[12:15]
	v_mfma_f32_16x16x32_bf16 v[8:11], v[190:193], v[224:227], v[8:11]
	v_mfma_f32_16x16x32_bf16 v[4:7], v[182:185], v[232:235], v[4:7]
	v_mfma_f32_16x16x32_bf16 v[0:3], v[190:193], v[232:235], v[0:3]
	s_setprio 0
	s_barrier
	s_add_i32 s42, s42, 2
	s_add_u32 s0, s0, 0x100
	s_addc_u32 s1, s1, 0
	s_add_u32 s36, s36, 0x100
	s_addc_u32 s37, s37, 0
	s_cmpk_gt_u32 s42, 0x7d
	s_cbranch_scc0 .LBB0_1685
	s_mov_b64 s[48:49], 0x80
	s_and_b64 vcc, exec, s[6:7]
	s_mov_b64 s[34:35], 0x45000
	s_cbranch_vccz .LBB0_1688
	s_barrier
; __device__ __forceinline__ unsigned cvt_pk_bf16(float lo, float hi) { const f32x2_t v = {lo, hi}; const bf16x2_t b = __builtin_convertvector(v, bf16x2_t); return __builtin_bit_cast(unsigned, b); }
;     __device__ __forceinline__ void operator()(const f32x4 (&acc)[2][2][4][2], const Unit& u, int wr, int wc, int fr, int fq) const {
;         const int row0 = u.pm * BM + wr * 64 + fr; const int col0 = u.pn * BM + wc * 32 + 8 * fq;
; #pragma unroll
;         for (int ai = 0; ai < 2; ++ai)
; #pragma unroll
;             for (int m = 0; m < 4; ++m) { bf16_t* rowp = O + (size_t)u.zo * zsO + (size_t)(row0 + ai * HALF + m * 16) * ldc + col0;
; #pragma unroll
;                 for (int bj = 0; bj < 2; ++bj) { f32x4 v0 = acc[ai][bj][m][0], v1 = acc[ai][bj][m][1];
;                     if (ACT == 2) {
; #pragma unroll
;                         for (int j = 0; j < 4; ++j) { const float a = fmaxf(v0[j], 0.f), b = fmaxf(v1[j], 0.f); v0[j] = a * a; v1[j] = b * b; } }
;                     u32x4 w; w.x = cvt_pk_bf16(v0[0], v0[1]); w.y = cvt_pk_bf16(v0[2], v0[3]); w.z = cvt_pk_bf16(v1[0], v1[1]); w.w = cvt_pk_bf16(v1[2], v1[3]);
;                     *(u32x4*)(rowp + bj * HALF) = w; } }
.LBB0_1688:
	v_lshl_add_u32 v146, s33, 8, v140
	v_lshl_or_b32 v144, s31, 8, v142
	v_ashrrev_i32_e32 v147, 31, v146
	v_readlane_b32 s0, v247, 44
	v_cvt_pk_bf16_f32 v110, v110, v111
	v_cvt_pk_bf16_f32 v111, v112, v113
	v_cvt_pk_bf16_f32 v112, v106, v107
	v_or_b32_e32 v106, 16, v146
	v_cvt_pk_bf16_f32 v94, v94, v95
	v_cvt_pk_bf16_f32 v95, v96, v97
	v_cvt_pk_bf16_f32 v96, v90, v91
	v_or_b32_e32 v90, 32, v146
	v_cvt_pk_bf16_f32 v78, v78, v79
	v_cvt_pk_bf16_f32 v79, v80, v81
	v_cvt_pk_bf16_f32 v80, v74, v75
	v_or_b32_e32 v74, 48, v146
	v_ashrrev_i32_e32 v145, 31, v144
	v_lshlrev_b64 v[148:149], 12, v[146:147]
	v_readlane_b32 s1, v247, 45
	v_ashrrev_i32_e32 v107, 31, v106
	v_ashrrev_i32_e32 v91, 31, v90
	v_ashrrev_i32_e32 v75, 31, v74
	v_lshl_add_u64 v[148:149], s[0:1], 0, v[148:149]
	v_lshlrev_b64 v[144:145], 1, v[144:145]
	v_lshlrev_b64 v[106:107], 12, v[106:107]
	v_lshlrev_b64 v[90:91], 12, v[90:91]
	v_lshlrev_b64 v[74:75], 12, v[74:75]
	v_lshl_add_u64 v[148:149], v[148:149], 0, v[144:145]
	v_lshl_add_u64 v[106:107], s[0:1], 0, v[106:107]
	v_lshl_add_u64 v[90:91], s[0:1], 0, v[90:91]
	v_lshl_add_u64 v[74:75], s[0:1], 0, v[74:75]
	s_mov_b64 s[0:1], 0x80000
	v_cvt_pk_bf16_f32 v70, v70, v71
	v_cvt_pk_bf16_f32 v71, v72, v73
	v_cvt_pk_bf16_f32 v72, v66, v67
	v_lshl_add_u64 v[66:67], v[148:149], 0, s[0:1]
	s_mov_b32 s0, 0x80000
	v_cvt_pk_bf16_f32 v60, v60, v61
	v_cvt_pk_bf16_f32 v61, v62, v63
	v_cvt_pk_bf16_f32 v62, v56, v57
	v_add_co_u32_e32 v56, vcc, s0, v148
	v_cvt_pk_bf16_f32 v44, v44, v45
	v_cvt_pk_bf16_f32 v45, v46, v47
	v_cvt_pk_bf16_f32 v46, v40, v41
	v_cvt_pk_bf16_f32 v47, v42, v43
	s_mov_b64 s[0:1], 0x90000
	v_addc_co_u32_e32 v57, vcc, 0, v149, vcc
	global_store_dwordx4 v[66:67], v[44:47], off offset:256
	v_cvt_pk_bf16_f32 v28, v28, v29
	v_cvt_pk_bf16_f32 v29, v30, v31
	v_lshl_add_u64 v[44:45], v[148:149], 0, s[0:1]
	s_mov_b32 s0, 0x90000
	v_add_co_u32_e32 v46, vcc, s0, v148
	v_cvt_pk_bf16_f32 v30, v24, v25
	v_cvt_pk_bf16_f32 v31, v26, v27
	s_mov_b64 s[0:1], 0xa0000
	v_addc_co_u32_e32 v47, vcc, 0, v149, vcc
	global_store_dwordx4 v[44:45], v[28:31], off offset:256
	v_cvt_pk_bf16_f32 v12, v12, v13
	v_cvt_pk_bf16_f32 v13, v14, v15
	v_lshl_add_u64 v[28:29], v[148:149], 0, s[0:1]
	s_mov_b32 s0, 0xa0000
	v_add_co_u32_e32 v30, vcc, s0, v148
	v_cvt_pk_bf16_f32 v14, v8, v9
	v_cvt_pk_bf16_f32 v15, v10, v11
	s_mov_b64 s[0:1], 0xb0000
	v_cvt_pk_bf16_f32 v113, v108, v109
	v_addc_co_u32_e32 v31, vcc, 0, v149, vcc
	global_store_dwordx4 v[28:29], v[12:15], off offset:256
	global_store_dwordx4 v[148:149], v[110:113], off offset:256
	v_cvt_pk_bf16_f32 v97, v92, v93
	v_lshl_add_u64 v[12:13], v[148:149], 0, s[0:1]
	s_mov_b32 s0, 0xb0000
	v_lshl_add_u64 v[110:111], v[106:107], 0, v[144:145]
	v_add_co_u32_e32 v14, vcc, s0, v148
	global_store_dwordx4 v[110:111], v[94:97], off offset:256
	v_cvt_pk_bf16_f32 v81, v76, v77
	v_addc_co_u32_e32 v15, vcc, 0, v149, vcc
	v_lshl_add_u64 v[94:95], v[90:91], 0, v[144:145]
	v_cvt_pk_bf16_f32 v126, v126, v127
	v_cvt_pk_bf16_f32 v127, v128, v129
	v_cvt_pk_bf16_f32 v128, v122, v123
	v_cvt_pk_bf16_f32 v129, v124, v125
	v_cvt_pk_bf16_f32 v106, v118, v119
	v_cvt_pk_bf16_f32 v107, v120, v121
	v_cvt_pk_bf16_f32 v108, v114, v115
	v_cvt_pk_bf16_f32 v109, v116, v117
	v_cvt_pk_bf16_f32 v90, v102, v103
	v_cvt_pk_bf16_f32 v91, v104, v105
	v_cvt_pk_bf16_f32 v92, v98, v99
	v_cvt_pk_bf16_f32 v93, v100, v101
	global_store_dwordx4 v[94:95], v[78:81], off offset:256
	v_cvt_pk_bf16_f32 v76, v82, v83
	v_cvt_pk_bf16_f32 v77, v84, v85
	v_lshl_add_u64 v[78:79], v[74:75], 0, v[144:145]
	v_cvt_pk_bf16_f32 v74, v86, v87
	v_cvt_pk_bf16_f32 v75, v88, v89
	v_cvt_pk_bf16_f32 v73, v68, v69
	v_cvt_pk_bf16_f32 v63, v58, v59
	v_cvt_pk_bf16_f32 v40, v52, v53
	v_cvt_pk_bf16_f32 v41, v54, v55
	v_cvt_pk_bf16_f32 v42, v48, v49
	v_cvt_pk_bf16_f32 v43, v50, v51
	v_cvt_pk_bf16_f32 v24, v36, v37
	v_cvt_pk_bf16_f32 v25, v38, v39
	v_cvt_pk_bf16_f32 v26, v32, v33
	v_cvt_pk_bf16_f32 v27, v34, v35
	v_cvt_pk_bf16_f32 v8, v20, v21
	v_cvt_pk_bf16_f32 v9, v22, v23
	v_cvt_pk_bf16_f32 v10, v16, v17
	v_cvt_pk_bf16_f32 v11, v18, v19
	v_cvt_pk_bf16_f32 v4, v4, v5
	v_cvt_pk_bf16_f32 v5, v6, v7
	v_cvt_pk_bf16_f32 v6, v0, v1
	v_cvt_pk_bf16_f32 v7, v2, v3
	s_andn2_b64 vcc, exec, s[2:3]
	s_mov_b64 s[0:1], -1
	s_mov_b64 s[36:37], 0x80
	global_store_dwordx4 v[148:149], v[126:129], off
	global_store_dwordx4 v[110:111], v[106:109], off
	global_store_dwordx4 v[94:95], v[90:93], off
	global_store_dwordx4 v[78:79], v[74:77], off
	global_store_dwordx4 v[78:79], v[70:73], off offset:256
	global_store_dwordx4 v[56:57], v[60:63], off
	global_store_dwordx4 v[46:47], v[40:43], off
	global_store_dwordx4 v[30:31], v[24:27], off
	global_store_dwordx4 v[14:15], v[8:11], off
	global_store_dwordx4 v[12:13], v[4:7], off offset:256
	v_writelane_b32 v244, 1, 63
	s_cbranch_vccnz .LBB0_1677
	s_andn2_b64 vcc, exec, s[4:5]
	s_cbranch_vccnz .LBB0_1676
	s_barrier
	s_branch .LBB0_1676

; #define PG8_STAGE(bufoff, gbase, voff) do { _Pragma("unroll") for (int _i = 0; _i < 2; ++_i) \
;         __builtin_amdgcn_global_load_lds((const unsigned*)((const char*)(gbase) + (voff)[_i]), (PG8_LAS unsigned*)(lds + (bufoff) + ldsw + _i * 8192), 16, 0, 0); } while (0)
; #define PG8_WAIT_V(n) asm volatile("s_waitcnt vmcnt(" #n ")" ::: "memory")
; #define PG8_BAR __builtin_amdgcn_s_barrier()
; template <class Epi, class Sched, bool ALIGN_EPI = false, bool SP2 = false>
; __device__ __forceinline__ void gemm_phase(PG8_LAS unsigned char* lds, const Gemm g, const Sched& S, const Epi& E, const int wave0) {
;     ...
;     if constexpr (SP2) {
;         PG8_STAGE(PG8_SB(0, 0), cB, voffB); PG8_STAGE(PG8_SB(0, 1), cB + hstepB, voffB); PG8_STAGE(PG8_SA(0, 0), cA, voffA); PG8_STAGE(PG8_SA(0, 1), cA + hstepA, voffA);
;         if (wr == 1) PG8_BAR;
;         PG8_WAIT_V(2); PG8_BAR;
;         PG8_STAGE(PG8_SB(1, 0), cB + kstep, voffB); PG8_STAGE(PG8_SA(1, 0), cA + kstep, voffA); PG8_STAGE(PG8_SB(1, 1), cB + hstepB + kstep, voffB);
;         PG8_WAIT_V(6); PG8_BAR;
.LBB0_1696:
	v_lshrrev_b32_e32 v16, 1, v6
	v_and_b32_e32 v16, 24, v16
	v_and_b32_e32 v7, 15, v6
	v_lshlrev_b32_e32 v17, 1, v16
	v_lshlrev_b32_e32 v6, 2, v6
	s_lshl_b32 s1, s1, 5
	v_lshl_or_b32 v140, s2, 6, v7
	v_lshl_or_b32 v7, v7, 6, v17
	s_lshl_b32 s2, s2, 13
	v_and_b32_e32 v6, 32, v6
	s_and_b32 s1, s1, 0x60
	v_bitop3_b32 v17, v7, s2, v6 bitop3:0xde
	s_lshl_b32 s2, s1, 7
	v_lshl_add_u64 v[8:9], s[18:19], 0, v[64:65]
	v_mov_b32_e32 v131, v65
	v_readlane_b32 s16, v246, 2
	v_bitop3_b32 v141, v7, s2, v6 bitop3:0xde
	s_add_u32 s2, s18, 0x200080
	v_lshl_add_u64 v[10:11], s[18:19], 0, v[130:131]
	v_mov_b32_e32 v135, v65
	v_readlane_b32 s17, v246, 3
	s_addc_u32 s3, s19, 0
	s_add_i32 m0, s28, 0x18000
	v_lshl_add_u64 v[6:7], v[8:9], 0, s[36:37]
	v_lshl_add_u64 v[12:13], s[16:17], 0, v[134:135]
	v_mov_b32_e32 v133, v65
	s_waitcnt vmcnt(2)
	s_barrier
	global_load_lds_dwordx4 v[6:7], off
	v_lshl_add_u64 v[6:7], v[10:11], 0, s[36:37]
	s_add_i32 m0, s28, 0x1a000
	s_add_i32 s33, s28, 0x8000
	v_lshl_add_u64 v[14:15], s[16:17], 0, v[132:133]
	global_load_lds_dwordx4 v[6:7], off
	v_lshl_add_u64 v[6:7], v[12:13], 0, s[36:37]
	s_mov_b32 m0, s33
	s_add_i32 s34, s28, 0xa000
	global_load_lds_dwordx4 v[6:7], off
	v_lshl_add_u64 v[6:7], v[14:15], 0, s[36:37]
	s_mov_b32 m0, s34
	v_or_b32_e32 v142, s1, v16
	global_load_lds_dwordx4 v[6:7], off
	s_add_i32 m0, s28, 0x1c000
	v_lshl_add_u64 v[6:7], s[2:3], 0, v[64:65]
	global_load_lds_dwordx4 v[6:7], off
	v_lshl_add_u64 v[6:7], s[2:3], 0, v[130:131]
	s_add_i32 m0, s28, 0x1e000
	s_cmpk_lt_u32 s0, 0x100
	global_load_lds_dwordx4 v[6:7], off
	v_lshlrev_b32_e32 v6, 17, v4
	v_and_b32_e32 v6, 0xfffc0000, v6
	v_lshl_add_u32 v3, v3, 14, v6
	v_and_b32_e32 v4, 1, v4
	v_lshl_or_b32 v3, v4, 6, v3
	v_lshl_add_u32 v136, v5, 1, v3
	v_lshlrev_b32_e32 v3, 17, v0
	v_and_b32_e32 v3, 0xfffc0000, v3
	v_writelane_b32 v244, 0, 63
	s_waitcnt vmcnt(6)
	v_lshl_add_u32 v1, v1, 14, v3
	v_and_b32_e32 v0, 1, v0
	v_readlane_b32 s0, v247, 60
	v_lshl_or_b32 v0, v0, 6, v1
	v_readlane_b32 s1, v247, 61
	v_readlane_b32 s2, v247, 58
	s_cselect_b64 s[6:7], -1, 0
	v_mov_b32_e32 v137, v65
	v_lshl_add_u32 v138, v2, 1, v0
	v_mov_b32_e32 v139, v65
	s_mov_b32 s35, 0
	v_add_u32_e32 v143, 0, v17
	s_mov_b32 s1, s0
	s_mov_b32 s37, s2
	v_readlane_b32 s0, v246, 28
	s_barrier
	v_readlane_b32 s3, v247, 59
	s_branch .LBB0_1699

;     __host__ __device__ bool next(int i, Unit& u) const { return tile((long)i * G + c, u); }
;     __host__ __device__ bool next(int i, Unit& u) const { if (!tile((long)(i / NZ) * G + c, u)) return false; u.z = i % NZ; return true; }
; #define PG8_STAGE(bufoff, gbase, voff) do { _Pragma("unroll") for (int _i = 0; _i < 2; ++_i) \
;         __builtin_amdgcn_global_load_lds((const unsigned*)((const char*)(gbase) + (voff)[_i]), (PG8_LAS unsigned*)(lds + (bufoff) + ldsw + _i * 8192), 16, 0, 0); } while (0)
; #define PG8_LDA(dst, b, h) do { _Pragma("unroll") for (int m = 0; m < 4; ++m) _Pragma("unroll") for (int k = 0; k < 2; ++k) dst[m][k] = *(const PG8_LAS bf16x8*)(lds + PG8_SA(b, h) + aoff + m * 2048 + k * 1024); } while (0)
; #define PG8_LDB(dst, b, h) do { _Pragma("unroll") for (int n = 0; n < 2; ++n) _Pragma("unroll") for (int k = 0; k < 2; ++k) dst[n][k] = *(const PG8_LAS bf16x8*)(lds + PG8_SB(b, h) + boff + n * 2048 + k * 1024); } while (0)
; template <class Epi, class Sched, bool ALIGN_EPI = false, bool SP2 = false>
; __device__ __forceinline__ void gemm_phase(PG8_LAS unsigned char* lds, const Gemm g, const Sched& S, const Epi& E, const int wave0) {
;     ...
;         const bool has_next = S.next(ui + 1, nxt);
;         const char* nA = has_next ? (const char*)g.A + (size_t)nxt.z * g.zsA + (size_t)nxt.pm * tstepA + (size_t)nxt.k0 * 2 : cA; const char* nB = has_next ? (const char*)g.Bt + (size_t)nxt.z * g.zsB + (size_t)nxt.pn * tstepB + (size_t)nxt.k0 * 2 : cB;
;         for (int t = 0; t < nt; t += 2) {
;             const bool last = (t == nt - 2);
;             const char* a1 = cA + (size_t)(t + 1) * kstep;
;             const char* a2 = last ? nA : cA + (size_t)(t + 2) * kstep; const char* b2 = last ? nB : cB + (size_t)(t + 2) * kstep;
;             const char* a3 = a2 + kstep; const char* b3 = b2 + kstep;
;             if (last && has_next) S.a_ready(nxt);
;             if constexpr (SP2) {
;             PG8_LDB(B0, 0, 0); PG8_LDB(B1, 0, 1); PG8_SCHED; PG8_LDA(At, 0, 0); PG8_STAGE(PG8_SA(1, 1), a1 + hstepA, voffA);
;     ...
; #pragma unroll
;         for (int a = 0; a < 2; ++a)
; #pragma unroll
;             for (int b = 0; b < 2; ++b)
; #pragma unroll
;                 for (int m = 0; m < 4; ++m)
; #pragma unroll
;                     for (int n = 0; n < 2; ++n) acc[a][b][m][n] = (f32x4){0.f, 0.f, 0.f, 0.f};
;         cur = nxt; cA = nA; cB = nB; ++ui;
.LBB0_1701:
	s_ashr_i32 s9, s8, 31
	s_lshl_b64 s[14:15], s[8:9], 22
	v_readlane_b32 s20, v246, 44
	v_readlane_b32 s21, v246, 45
	s_add_u32 s9, s20, s14
	s_addc_u32 s13, s21, s15
	s_ashr_i32 s11, s10, 31
	s_lshl_b64 s[20:21], s[10:11], 1
	s_add_u32 s14, s9, s20
	s_addc_u32 s15, s13, s21
	s_and_b64 s[26:27], s[2:3], exec
	s_cselect_b32 s9, s15, s17
	s_cselect_b32 s11, s14, s16
	s_ashr_i32 s13, s12, 31
	s_lshl_b64 s[26:27], s[12:13], 22
	s_add_u32 s13, s23, s26
	s_addc_u32 s27, s24, s27
	s_add_u32 s26, s13, s20
	s_addc_u32 s27, s27, s21
	s_and_b64 s[20:21], s[2:3], exec
	s_cselect_b32 s13, s27, s19
	s_cselect_b32 s38, s26, s18
	s_add_u32 s16, s16, 0x200080
	s_addc_u32 s17, s17, 0
	s_add_u32 s39, s18, 0x100
	v_mov_b32_e32 v0, 0
	s_addc_u32 s42, s19, 0
	s_mov_b32 s43, -2
	v_mov_b32_e32 v1, v0
	v_mov_b64_e32 v[2:3], 0
	v_mov_b64_e32 v[4:5], 0
	v_mov_b64_e32 v[6:7], 0
	v_mov_b64_e32 v[8:9], 0
	v_mov_b64_e32 v[10:11], 0
	v_mov_b64_e32 v[12:13], 0
	v_mov_b64_e32 v[14:15], 0
	v_mov_b64_e32 v[24:25], 0
	v_mov_b64_e32 v[26:27], 0
	v_mov_b64_e32 v[28:29], 0
	v_mov_b64_e32 v[30:31], 0
	v_mov_b64_e32 v[40:41], 0
	v_mov_b64_e32 v[42:43], 0
	v_mov_b64_e32 v[44:45], 0
	v_mov_b64_e32 v[46:47], 0
	v_mov_b64_e32 v[16:17], 0
	v_mov_b64_e32 v[18:19], 0
	v_mov_b64_e32 v[20:21], 0
	v_mov_b64_e32 v[22:23], 0
	v_mov_b64_e32 v[32:33], 0
	v_mov_b64_e32 v[34:35], 0
	v_mov_b64_e32 v[36:37], 0
	v_mov_b64_e32 v[38:39], 0
	v_mov_b64_e32 v[48:49], 0
	v_mov_b64_e32 v[50:51], 0
	v_mov_b64_e32 v[52:53], 0
	v_mov_b64_e32 v[54:55], 0
	v_mov_b64_e32 v[56:57], 0
	v_mov_b64_e32 v[58:59], 0
	v_mov_b64_e32 v[60:61], 0
	v_mov_b64_e32 v[62:63], 0
	v_mov_b64_e32 v[66:67], 0
	v_mov_b64_e32 v[68:69], 0
	v_mov_b64_e32 v[70:71], 0
	v_mov_b64_e32 v[72:73], 0
	v_mov_b64_e32 v[74:75], 0
	v_mov_b64_e32 v[76:77], 0
	v_mov_b64_e32 v[78:79], 0
	v_mov_b64_e32 v[80:81], 0
	v_mov_b64_e32 v[90:91], 0
	v_mov_b64_e32 v[92:93], 0
	v_mov_b64_e32 v[94:95], 0
	v_mov_b64_e32 v[96:97], 0
	v_mov_b64_e32 v[106:107], 0
	v_mov_b64_e32 v[108:109], 0
	v_mov_b64_e32 v[110:111], 0
	v_mov_b64_e32 v[112:113], 0
	v_mov_b64_e32 v[82:83], 0
	v_mov_b64_e32 v[84:85], 0
	v_mov_b64_e32 v[86:87], 0
	v_mov_b64_e32 v[88:89], 0
	v_mov_b64_e32 v[98:99], 0
	v_mov_b64_e32 v[100:101], 0
	v_mov_b64_e32 v[102:103], 0
	v_mov_b64_e32 v[104:105], 0
	v_mov_b64_e32 v[114:115], 0
	v_mov_b64_e32 v[116:117], 0
	v_mov_b64_e32 v[118:119], 0
	v_mov_b64_e32 v[120:121], 0
	v_mov_b64_e32 v[122:123], 0
	v_mov_b64_e32 v[124:125], 0
	v_mov_b64_e32 v[126:127], 0
	v_mov_b64_e32 v[128:129], 0
	s_mov_b64 s[48:49], 0x80
	v_add_u32_e32 v252, 0x10000, v141
	v_add_u32_e32 v253, 0x14000, v141
	v_add_u32_e32 v254, 0x18000, v141
	v_add_u32_e32 v255, 0x1c000, v141
	v_readlane_b32 s48, v244, 63
	v_writelane_b32 v244, 0, 63
.LBB0_1702:
	s_add_u32 s18, s16, 0xffe00080
	s_addc_u32 s19, s17, -1
	s_add_i32 s44, 0, 0x10000
	s_cmp_eq_u32 s43, 12
	s_cselect_b32 s21, s9, s19
	s_cselect_b32 s20, s11, s18
	s_cselect_b32 s19, s13, s42
	s_cselect_b32 s18, s38, s39
	s_add_i32 s46, 0, 0x14000
	ds_read_b128 v[144:147], v252
	ds_read_b128 v[148:151], v252 offset:1024
	ds_read_b128 v[152:155], v252 offset:2048
	ds_read_b128 v[156:159], v252 offset:3072
	ds_read_b128 v[178:181], v253
	ds_read_b128 v[182:185], v253 offset:1024
	ds_read_b128 v[186:189], v253 offset:2048
	ds_read_b128 v[190:193], v253 offset:3072
	s_add_i32 m0, s28, 0xc000
	ds_read_b128 v[194:197], v143
	ds_read_b128 v[208:211], v143 offset:1024
	ds_read_b128 v[212:215], v143 offset:2048
	ds_read_b128 v[216:219], v143 offset:3072
	ds_read_b128 v[220:223], v143 offset:4096
	ds_read_b128 v[224:227], v143 offset:5120
	ds_read_b128 v[228:231], v143 offset:6144
	ds_read_b128 v[232:235], v143 offset:7168
	global_load_lds_dwordx4 v136, s[16:17]
	s_add_i32 m0, s28, 0xe000
	s_nop 0
	global_load_lds_dwordx4 v138, s[16:17]
	s_cmp_eq_u32 s48, 1
	s_cbranch_scc0 .Ldf5_0n
	s_waitcnt vmcnt(24)
	s_branch .Ldf5_0d

; #define PG8_STAGE(bufoff, gbase, voff) do { _Pragma("unroll") for (int _i = 0; _i < 2; ++_i) \
;         __builtin_amdgcn_global_load_lds((const unsigned*)((const char*)(gbase) + (voff)[_i]), (PG8_LAS unsigned*)(lds + (bufoff) + ldsw + _i * 8192), 16, 0, 0); } while (0)
; #define PG8_LDA(dst, b, h) do { _Pragma("unroll") for (int m = 0; m < 4; ++m) _Pragma("unroll") for (int k = 0; k < 2; ++k) dst[m][k] = *(const PG8_LAS bf16x8*)(lds + PG8_SA(b, h) + aoff + m * 2048 + k * 1024); } while (0)
; #define PG8_MMA(ai, bj, At, Bt) do { __builtin_amdgcn_s_setprio(1); _Pragma("unroll") for (int m = 0; m < 4; ++m) _Pragma("unroll") for (int n = 0; n < 2; ++n) _Pragma("unroll") for (int k = 0; k < 2; ++k) \
;         acc[ai][bj][m][n] = __builtin_amdgcn_mfma_f32_16x16x32_bf16(Bt[n][k], At[m][k], acc[ai][bj][m][n], 0, 0, 0); __builtin_amdgcn_s_setprio(0); } while (0)
; #define PG8_WAIT_V(n) asm volatile("s_waitcnt vmcnt(" #n ")" ::: "memory")
; #define PG8_WAIT_L(n) asm volatile("s_waitcnt lgkmcnt(" #n ")" ::: "memory")
; #define PG8_BAR __builtin_amdgcn_s_barrier()
; #define PG8_SCHED __builtin_amdgcn_sched_barrier(0)
; template <class Epi, class Sched, bool ALIGN_EPI = false, bool SP2 = false>
; __device__ __forceinline__ void gemm_phase(PG8_LAS unsigned char* lds, const Gemm g, const Sched& S, const Epi& E, const int wave0) {
;     ...
;             PG8_WAIT_V(8); PG8_WAIT_L(0); PG8_BAR; PG8_MMA(0, 0, At, B0); PG8_MMA(0, 1, At, B1); PG8_BAR; PG8_SCHED;
;             PG8_LDA(At, 0, 1); PG8_STAGE(PG8_SB(0, 0), b2, voffB); PG8_STAGE(PG8_SB(0, 1), b2 + hstepB, voffB); PG8_STAGE(PG8_SA(0, 0), a2, voffA);
;             PG8_WAIT_V(8); PG8_WAIT_L(0); PG8_BAR; PG8_MMA(1, 0, At, B0); PG8_MMA(1, 1, At, B1); PG8_BAR; PG8_SCHED;
.Ldf5_0d:
	s_waitcnt lgkmcnt(0)
	s_barrier
	s_setprio 1
	s_waitcnt lgkmcnt(0)
	v_mfma_f32_16x16x32_bf16 v[126:129], v[144:147], v[194:197], v[126:129]
	v_mfma_f32_16x16x32_bf16 v[122:125], v[152:155], v[194:197], v[122:125]
	v_mfma_f32_16x16x32_bf16 v[118:121], v[144:147], v[212:215], v[118:121]
	v_mfma_f32_16x16x32_bf16 v[114:117], v[152:155], v[212:215], v[114:117]
	v_mfma_f32_16x16x32_bf16 v[102:105], v[144:147], v[220:223], v[102:105]
	v_mfma_f32_16x16x32_bf16 v[98:101], v[152:155], v[220:223], v[98:101]
	v_mfma_f32_16x16x32_bf16 v[86:89], v[144:147], v[228:231], v[86:89]
	v_mfma_f32_16x16x32_bf16 v[82:85], v[152:155], v[228:231], v[82:85]
	v_mfma_f32_16x16x32_bf16 v[126:129], v[148:151], v[208:211], v[126:129]
	v_mfma_f32_16x16x32_bf16 v[122:125], v[156:159], v[208:211], v[122:125]
	v_mfma_f32_16x16x32_bf16 v[118:121], v[148:151], v[216:219], v[118:121]
	v_mfma_f32_16x16x32_bf16 v[114:117], v[156:159], v[216:219], v[114:117]
	v_mfma_f32_16x16x32_bf16 v[102:105], v[148:151], v[224:227], v[102:105]
	v_mfma_f32_16x16x32_bf16 v[98:101], v[156:159], v[224:227], v[98:101]
	v_mfma_f32_16x16x32_bf16 v[86:89], v[148:151], v[232:235], v[86:89]
	v_mfma_f32_16x16x32_bf16 v[82:85], v[156:159], v[232:235], v[82:85]
	s_setprio 0
	s_setprio 1
	v_mfma_f32_16x16x32_bf16 v[110:113], v[178:181], v[194:197], v[110:113]
	v_mfma_f32_16x16x32_bf16 v[106:109], v[186:189], v[194:197], v[106:109]
	v_mfma_f32_16x16x32_bf16 v[94:97], v[178:181], v[212:215], v[94:97]
	v_mfma_f32_16x16x32_bf16 v[90:93], v[186:189], v[212:215], v[90:93]
	v_mfma_f32_16x16x32_bf16 v[78:81], v[178:181], v[220:223], v[78:81]
	v_mfma_f32_16x16x32_bf16 v[74:77], v[186:189], v[220:223], v[74:77]
	v_mfma_f32_16x16x32_bf16 v[70:73], v[178:181], v[228:231], v[70:73]
	v_mfma_f32_16x16x32_bf16 v[66:69], v[186:189], v[228:231], v[66:69]
	v_mfma_f32_16x16x32_bf16 v[110:113], v[182:185], v[208:211], v[110:113]
	v_mfma_f32_16x16x32_bf16 v[106:109], v[190:193], v[208:211], v[106:109]
	v_mfma_f32_16x16x32_bf16 v[94:97], v[182:185], v[216:219], v[94:97]
	v_mfma_f32_16x16x32_bf16 v[90:93], v[190:193], v[216:219], v[90:93]
	v_mfma_f32_16x16x32_bf16 v[78:81], v[182:185], v[224:227], v[78:81]
	v_mfma_f32_16x16x32_bf16 v[74:77], v[190:193], v[224:227], v[74:77]
	v_mfma_f32_16x16x32_bf16 v[70:73], v[182:185], v[232:235], v[70:73]
	v_mfma_f32_16x16x32_bf16 v[66:69], v[190:193], v[232:235], v[66:69]
	s_setprio 0
	s_barrier
	s_add_i32 s44, s44, s25
	s_mov_b32 m0, s44
	ds_read_b128 v[194:197], v143 offset:16384
	ds_read_b128 v[208:211], v143 offset:17408
	ds_read_b128 v[212:215], v143 offset:18432
	ds_read_b128 v[216:219], v143 offset:19456
	ds_read_b128 v[220:223], v143 offset:20480
	ds_read_b128 v[224:227], v143 offset:21504
	ds_read_b128 v[228:231], v143 offset:22528
	ds_read_b128 v[232:235], v143 offset:23552
	global_load_lds_dwordx4 v64, s[18:19]
	s_add_i32 m0, s44, 0x2000
	s_add_u32 s44, s18, 0x200000
	s_addc_u32 s45, s19, 0
	s_add_i32 s46, s46, s25
	global_load_lds_dwordx4 v130, s[18:19]
	s_mov_b32 m0, s46
	s_mov_b64 s[100:101], s[20:21]
	global_load_lds_dwordx4 v64, s[44:45]
	s_add_i32 m0, s46, 0x2000
	s_nop 0
	global_load_lds_dwordx4 v130, s[44:45]
	s_mov_b32 m0, s28
	s_nop 0
	global_load_lds_dwordx4 v134, s[20:21]
	s_mov_b32 m0, s29
	s_nop 0
	global_load_lds_dwordx4 v132, s[20:21]
	s_cmp_eq_u32 s48, 1
	s_cbranch_scc0 .Ldf5_1n
	s_waitcnt vmcnt(24)
	s_mov_b32 s48, 0
	s_branch .Ldf5_1d

; #define PG8_STAGE(bufoff, gbase, voff) do { _Pragma("unroll") for (int _i = 0; _i < 2; ++_i) \
;         __builtin_amdgcn_global_load_lds((const unsigned*)((const char*)(gbase) + (voff)[_i]), (PG8_LAS unsigned*)(lds + (bufoff) + ldsw + _i * 8192), 16, 0, 0); } while (0)
; #define PG8_LDA(dst, b, h) do { _Pragma("unroll") for (int m = 0; m < 4; ++m) _Pragma("unroll") for (int k = 0; k < 2; ++k) dst[m][k] = *(const PG8_LAS bf16x8*)(lds + PG8_SA(b, h) + aoff + m * 2048 + k * 1024); } while (0)
; #define PG8_LDB(dst, b, h) do { _Pragma("unroll") for (int n = 0; n < 2; ++n) _Pragma("unroll") for (int k = 0; k < 2; ++k) dst[n][k] = *(const PG8_LAS bf16x8*)(lds + PG8_SB(b, h) + boff + n * 2048 + k * 1024); } while (0)
; #define PG8_MMA(ai, bj, At, Bt) do { __builtin_amdgcn_s_setprio(1); _Pragma("unroll") for (int m = 0; m < 4; ++m) _Pragma("unroll") for (int n = 0; n < 2; ++n) _Pragma("unroll") for (int k = 0; k < 2; ++k) \
;         acc[ai][bj][m][n] = __builtin_amdgcn_mfma_f32_16x16x32_bf16(Bt[n][k], At[m][k], acc[ai][bj][m][n], 0, 0, 0); __builtin_amdgcn_s_setprio(0); } while (0)
; #define PG8_WAIT_V(n) asm volatile("s_waitcnt vmcnt(" #n ")" ::: "memory")
; #define PG8_WAIT_L(n) asm volatile("s_waitcnt lgkmcnt(" #n ")" ::: "memory")
; #define PG8_BAR __builtin_amdgcn_s_barrier()
; #define PG8_SCHED __builtin_amdgcn_sched_barrier(0)
; template <class Epi, class Sched, bool ALIGN_EPI = false, bool SP2 = false>
; __device__ __forceinline__ void gemm_phase(PG8_LAS unsigned char* lds, const Gemm g, const Sched& S, const Epi& E, const int wave0) {
;     ...
;             PG8_WAIT_V(8); PG8_WAIT_L(0); PG8_BAR; PG8_MMA(1, 0, At, B0); PG8_MMA(1, 1, At, B1); PG8_BAR; PG8_SCHED;
;             PG8_LDB(B0, 1, 0); PG8_LDB(B1, 1, 1); PG8_SCHED; PG8_LDA(At, 1, 0); PG8_STAGE(PG8_SA(0, 1), a2 + hstepA, voffA);
;             PG8_WAIT_V(8); PG8_WAIT_L(0); PG8_BAR; PG8_MMA(0, 0, At, B0); PG8_MMA(0, 1, At, B1); PG8_BAR; PG8_SCHED;
.Ldf5_1d:
	s_waitcnt lgkmcnt(0)
	s_barrier
	s_setprio 1
	s_waitcnt lgkmcnt(0)
	v_mfma_f32_16x16x32_bf16 v[60:63], v[144:147], v[194:197], v[60:63]
	v_mfma_f32_16x16x32_bf16 v[56:59], v[152:155], v[194:197], v[56:59]
	v_mfma_f32_16x16x32_bf16 v[52:55], v[144:147], v[212:215], v[52:55]
	v_mfma_f32_16x16x32_bf16 v[48:51], v[152:155], v[212:215], v[48:51]
	v_mfma_f32_16x16x32_bf16 v[36:39], v[144:147], v[220:223], v[36:39]
	v_mfma_f32_16x16x32_bf16 v[32:35], v[152:155], v[220:223], v[32:35]
	v_mfma_f32_16x16x32_bf16 v[20:23], v[144:147], v[228:231], v[20:23]
	v_mfma_f32_16x16x32_bf16 v[16:19], v[152:155], v[228:231], v[16:19]
	v_mfma_f32_16x16x32_bf16 v[60:63], v[148:151], v[208:211], v[60:63]
	v_mfma_f32_16x16x32_bf16 v[56:59], v[156:159], v[208:211], v[56:59]
	v_mfma_f32_16x16x32_bf16 v[52:55], v[148:151], v[216:219], v[52:55]
	v_mfma_f32_16x16x32_bf16 v[48:51], v[156:159], v[216:219], v[48:51]
	v_mfma_f32_16x16x32_bf16 v[36:39], v[148:151], v[224:227], v[36:39]
	v_mfma_f32_16x16x32_bf16 v[32:35], v[156:159], v[224:227], v[32:35]
	v_mfma_f32_16x16x32_bf16 v[20:23], v[148:151], v[232:235], v[20:23]
	v_mfma_f32_16x16x32_bf16 v[16:19], v[156:159], v[232:235], v[16:19]
	s_setprio 0
	s_setprio 1
	v_mfma_f32_16x16x32_bf16 v[44:47], v[178:181], v[194:197], v[44:47]
	v_mfma_f32_16x16x32_bf16 v[40:43], v[186:189], v[194:197], v[40:43]
	v_mfma_f32_16x16x32_bf16 v[28:31], v[178:181], v[212:215], v[28:31]
	v_mfma_f32_16x16x32_bf16 v[24:27], v[186:189], v[212:215], v[24:27]
	v_mfma_f32_16x16x32_bf16 v[12:15], v[178:181], v[220:223], v[12:15]
	v_mfma_f32_16x16x32_bf16 v[8:11], v[186:189], v[220:223], v[8:11]
	v_mfma_f32_16x16x32_bf16 v[4:7], v[178:181], v[228:231], v[4:7]
	v_mfma_f32_16x16x32_bf16 v[0:3], v[186:189], v[228:231], v[0:3]
	v_mfma_f32_16x16x32_bf16 v[44:47], v[182:185], v[208:211], v[44:47]
	v_mfma_f32_16x16x32_bf16 v[40:43], v[190:193], v[208:211], v[40:43]
	v_mfma_f32_16x16x32_bf16 v[28:31], v[182:185], v[216:219], v[28:31]
	v_mfma_f32_16x16x32_bf16 v[24:27], v[190:193], v[216:219], v[24:27]
	v_mfma_f32_16x16x32_bf16 v[12:15], v[182:185], v[224:227], v[12:15]
	v_mfma_f32_16x16x32_bf16 v[8:11], v[190:193], v[224:227], v[8:11]
	v_mfma_f32_16x16x32_bf16 v[4:7], v[182:185], v[232:235], v[4:7]
	v_mfma_f32_16x16x32_bf16 v[0:3], v[190:193], v[232:235], v[0:3]
	s_setprio 0
	s_barrier
	s_add_i32 s44, 0, 0x18000
	s_add_i32 s45, 0, 0x1c000
	ds_read_b128 v[144:147], v254
	ds_read_b128 v[148:151], v254 offset:1024
	ds_read_b128 v[152:155], v254 offset:2048
	ds_read_b128 v[156:159], v254 offset:3072
	ds_read_b128 v[178:181], v255
	ds_read_b128 v[182:185], v255 offset:1024
	ds_read_b128 v[186:189], v255 offset:2048
	ds_read_b128 v[190:193], v255 offset:3072
	s_add_u32 s20, s20, 0x200000
	s_addc_u32 s21, s21, 0
	s_mov_b32 m0, s30
	ds_read_b128 v[194:197], v143 offset:32768
	ds_read_b128 v[208:211], v143 offset:33792
	ds_read_b128 v[212:215], v143 offset:34816
	ds_read_b128 v[216:219], v143 offset:35840
	ds_read_b128 v[220:223], v143 offset:36864
	ds_read_b128 v[224:227], v143 offset:37888
	ds_read_b128 v[228:231], v143 offset:38912
	ds_read_b128 v[232:235], v143 offset:39936
	global_load_lds_dwordx4 v134, s[20:21]
	s_mov_b32 m0, s31
	s_nop 0
	global_load_lds_dwordx4 v132, s[20:21]
	s_waitcnt vmcnt(8)
	s_waitcnt lgkmcnt(0)
	s_barrier
	s_setprio 1
	s_waitcnt lgkmcnt(0)
	v_mfma_f32_16x16x32_bf16 v[126:129], v[144:147], v[194:197], v[126:129]
	v_mfma_f32_16x16x32_bf16 v[122:125], v[152:155], v[194:197], v[122:125]
	v_mfma_f32_16x16x32_bf16 v[118:121], v[144:147], v[212:215], v[118:121]
	v_mfma_f32_16x16x32_bf16 v[114:117], v[152:155], v[212:215], v[114:117]
	v_mfma_f32_16x16x32_bf16 v[102:105], v[144:147], v[220:223], v[102:105]
	v_mfma_f32_16x16x32_bf16 v[98:101], v[152:155], v[220:223], v[98:101]
	v_mfma_f32_16x16x32_bf16 v[86:89], v[144:147], v[228:231], v[86:89]
	v_mfma_f32_16x16x32_bf16 v[82:85], v[152:155], v[228:231], v[82:85]
	v_mfma_f32_16x16x32_bf16 v[126:129], v[148:151], v[208:211], v[126:129]
	v_mfma_f32_16x16x32_bf16 v[122:125], v[156:159], v[208:211], v[122:125]
	v_mfma_f32_16x16x32_bf16 v[118:121], v[148:151], v[216:219], v[118:121]
	v_mfma_f32_16x16x32_bf16 v[114:117], v[156:159], v[216:219], v[114:117]
	v_mfma_f32_16x16x32_bf16 v[102:105], v[148:151], v[224:227], v[102:105]
	v_mfma_f32_16x16x32_bf16 v[98:101], v[156:159], v[224:227], v[98:101]
	v_mfma_f32_16x16x32_bf16 v[86:89], v[148:151], v[232:235], v[86:89]
	v_mfma_f32_16x16x32_bf16 v[82:85], v[156:159], v[232:235], v[82:85]
	s_setprio 0
	s_setprio 1
	v_mfma_f32_16x16x32_bf16 v[110:113], v[178:181], v[194:197], v[110:113]
	v_mfma_f32_16x16x32_bf16 v[106:109], v[186:189], v[194:197], v[106:109]
	v_mfma_f32_16x16x32_bf16 v[94:97], v[178:181], v[212:215], v[94:97]
	v_mfma_f32_16x16x32_bf16 v[90:93], v[186:189], v[212:215], v[90:93]
	v_mfma_f32_16x16x32_bf16 v[78:81], v[178:181], v[220:223], v[78:81]
	v_mfma_f32_16x16x32_bf16 v[74:77], v[186:189], v[220:223], v[74:77]
	v_mfma_f32_16x16x32_bf16 v[70:73], v[178:181], v[228:231], v[70:73]
	v_mfma_f32_16x16x32_bf16 v[66:69], v[186:189], v[228:231], v[66:69]
	v_mfma_f32_16x16x32_bf16 v[110:113], v[182:185], v[208:211], v[110:113]
	v_mfma_f32_16x16x32_bf16 v[106:109], v[190:193], v[208:211], v[106:109]
	v_mfma_f32_16x16x32_bf16 v[94:97], v[182:185], v[216:219], v[94:97]
	v_mfma_f32_16x16x32_bf16 v[90:93], v[190:193], v[216:219], v[90:93]
	v_mfma_f32_16x16x32_bf16 v[78:81], v[182:185], v[224:227], v[78:81]
	v_mfma_f32_16x16x32_bf16 v[74:77], v[190:193], v[224:227], v[74:77]
	v_mfma_f32_16x16x32_bf16 v[70:73], v[182:185], v[232:235], v[70:73]
	v_mfma_f32_16x16x32_bf16 v[66:69], v[190:193], v[232:235], v[66:69]
	s_setprio 0
	s_barrier
; #define PG8_STAGE(bufoff, gbase, voff) do { _Pragma("unroll") for (int _i = 0; _i < 2; ++_i) \
;         __builtin_amdgcn_global_load_lds((const unsigned*)((const char*)(gbase) + (voff)[_i]), (PG8_LAS unsigned*)(lds + (bufoff) + ldsw + _i * 8192), 16, 0, 0); } while (0)
; #define PG8_LDA(dst, b, h) do { _Pragma("unroll") for (int m = 0; m < 4; ++m) _Pragma("unroll") for (int k = 0; k < 2; ++k) dst[m][k] = *(const PG8_LAS bf16x8*)(lds + PG8_SA(b, h) + aoff + m * 2048 + k * 1024); } while (0)
; #define PG8_MMA(ai, bj, At, Bt) do { __builtin_amdgcn_s_setprio(1); _Pragma("unroll") for (int m = 0; m < 4; ++m) _Pragma("unroll") for (int n = 0; n < 2; ++n) _Pragma("unroll") for (int k = 0; k < 2; ++k) \
;         acc[ai][bj][m][n] = __builtin_amdgcn_mfma_f32_16x16x32_bf16(Bt[n][k], At[m][k], acc[ai][bj][m][n], 0, 0, 0); __builtin_amdgcn_s_setprio(0); } while (0)
; #define PG8_WAIT_V(n) asm volatile("s_waitcnt vmcnt(" #n ")" ::: "memory")
; #define PG8_WAIT_L(n) asm volatile("s_waitcnt lgkmcnt(" #n ")" ::: "memory")
; #define PG8_BAR __builtin_amdgcn_s_barrier()
; #define PG8_SCHED __builtin_amdgcn_sched_barrier(0)
; template <class Epi, class Sched, bool ALIGN_EPI = false, bool SP2 = false>
; __device__ __forceinline__ void gemm_phase(PG8_LAS unsigned char* lds, const Gemm g, const Sched& S, const Epi& E, const int wave0) {
;     ...
;             PG8_LDA(At, 1, 1); PG8_STAGE(PG8_SB(1, 0), b3, voffB); PG8_STAGE(PG8_SB(1, 1), b3 + hstepB, voffB); PG8_STAGE(PG8_SA(1, 0), a3, voffA);
;             PG8_WAIT_V(8); PG8_WAIT_L(0); PG8_BAR; PG8_MMA(1, 0, At, B0); PG8_MMA(1, 1, At, B1); PG8_BAR; PG8_SCHED;
	s_add_i32 s20, s44, s25
	s_add_u32 s48, s18, 0x80
	s_addc_u32 s49, s19, 0
	s_mov_b32 m0, s20
	ds_read_b128 v[194:197], v143 offset:49152
	ds_read_b128 v[208:211], v143 offset:50176
	ds_read_b128 v[212:215], v143 offset:51200
	ds_read_b128 v[216:219], v143 offset:52224
	ds_read_b128 v[220:223], v143 offset:53248
	ds_read_b128 v[224:227], v143 offset:54272
	ds_read_b128 v[228:231], v143 offset:55296
	ds_read_b128 v[232:235], v143 offset:56320
	global_load_lds_dwordx4 v64, s[48:49]
	s_add_i32 m0, s20, 0x2000
	s_add_u32 s18, s18, 0x200080
	s_addc_u32 s19, s19, 0
	s_add_i32 s20, s45, s25
	global_load_lds_dwordx4 v130, s[48:49]
	s_mov_b32 m0, s20
	s_nop 0
	global_load_lds_dwordx4 v64, s[18:19]
	s_add_i32 m0, s20, 0x2000
	s_nop 0
	global_load_lds_dwordx4 v130, s[18:19]
	s_add_u32 s100, s100, 0x80
	s_addc_u32 s101, s101, 0
	s_mov_b32 m0, s33
	s_nop 0
	global_load_lds_dwordx4 v134, s[100:101]
	s_mov_b32 m0, s34
	s_nop 0
	global_load_lds_dwordx4 v132, s[100:101]
	s_waitcnt vmcnt(8)
	s_waitcnt lgkmcnt(0)
	s_barrier
	s_setprio 1
	s_waitcnt lgkmcnt(0)
	v_mfma_f32_16x16x32_bf16 v[60:63], v[144:147], v[194:197], v[60:63]
	v_mfma_f32_16x16x32_bf16 v[56:59], v[152:155], v[194:197], v[56:59]
	v_mfma_f32_16x16x32_bf16 v[52:55], v[144:147], v[212:215], v[52:55]
	v_mfma_f32_16x16x32_bf16 v[48:51], v[152:155], v[212:215], v[48:51]
	v_mfma_f32_16x16x32_bf16 v[36:39], v[144:147], v[220:223], v[36:39]
	v_mfma_f32_16x16x32_bf16 v[32:35], v[152:155], v[220:223], v[32:35]
	v_mfma_f32_16x16x32_bf16 v[20:23], v[144:147], v[228:231], v[20:23]
	v_mfma_f32_16x16x32_bf16 v[16:19], v[152:155], v[228:231], v[16:19]
	v_mfma_f32_16x16x32_bf16 v[60:63], v[148:151], v[208:211], v[60:63]
	v_mfma_f32_16x16x32_bf16 v[56:59], v[156:159], v[208:211], v[56:59]
	v_mfma_f32_16x16x32_bf16 v[52:55], v[148:151], v[216:219], v[52:55]
	v_mfma_f32_16x16x32_bf16 v[48:51], v[156:159], v[216:219], v[48:51]
	v_mfma_f32_16x16x32_bf16 v[36:39], v[148:151], v[224:227], v[36:39]
	v_mfma_f32_16x16x32_bf16 v[32:35], v[156:159], v[224:227], v[32:35]
	v_mfma_f32_16x16x32_bf16 v[20:23], v[148:151], v[232:235], v[20:23]
	v_mfma_f32_16x16x32_bf16 v[16:19], v[156:159], v[232:235], v[16:19]
	s_setprio 0
	s_setprio 1
	v_mfma_f32_16x16x32_bf16 v[44:47], v[178:181], v[194:197], v[44:47]
	v_mfma_f32_16x16x32_bf16 v[40:43], v[186:189], v[194:197], v[40:43]
	v_mfma_f32_16x16x32_bf16 v[28:31], v[178:181], v[212:215], v[28:31]
	v_mfma_f32_16x16x32_bf16 v[24:27], v[186:189], v[212:215], v[24:27]
	v_mfma_f32_16x16x32_bf16 v[12:15], v[178:181], v[220:223], v[12:15]
	v_mfma_f32_16x16x32_bf16 v[8:11], v[186:189], v[220:223], v[8:11]
	v_mfma_f32_16x16x32_bf16 v[4:7], v[178:181], v[228:231], v[4:7]
	v_mfma_f32_16x16x32_bf16 v[0:3], v[186:189], v[228:231], v[0:3]
	v_mfma_f32_16x16x32_bf16 v[44:47], v[182:185], v[208:211], v[44:47]
	v_mfma_f32_16x16x32_bf16 v[40:43], v[190:193], v[208:211], v[40:43]
	v_mfma_f32_16x16x32_bf16 v[28:31], v[182:185], v[216:219], v[28:31]
	v_mfma_f32_16x16x32_bf16 v[24:27], v[190:193], v[216:219], v[24:27]
	v_mfma_f32_16x16x32_bf16 v[12:15], v[182:185], v[224:227], v[12:15]
	v_mfma_f32_16x16x32_bf16 v[8:11], v[190:193], v[224:227], v[8:11]
	v_mfma_f32_16x16x32_bf16 v[4:7], v[182:185], v[232:235], v[4:7]
	v_mfma_f32_16x16x32_bf16 v[0:3], v[190:193], v[232:235], v[0:3]
	s_setprio 0
	s_barrier
	s_add_i32 s43, s43, 2
	s_add_u32 s16, s16, 0x100
	s_addc_u32 s17, s17, 0
	s_add_u32 s39, s39, 0x100
	s_addc_u32 s42, s42, 0
	s_cmp_gt_u32 s43, 13
	s_cbranch_scc0 .LBB0_1702
	s_mov_b64 s[48:49], 0x80
	s_and_b64 vcc, exec, s[6:7]
	s_cbranch_vccz .LBB0_1705
	s_barrier
; __device__ __forceinline__ unsigned cvt_pk_bf16(float lo, float hi) { const f32x2_t v = {lo, hi}; const bf16x2_t b = __builtin_convertvector(v, bf16x2_t); return __builtin_bit_cast(unsigned, b); }
;     __device__ __forceinline__ void operator()(const f32x4 (&acc)[2][2][4][2], const Unit& u, int wr, int wc, int fr, int fq) const {
;         const int row0 = u.pm * BM + wr * 64 + fr; const int col0 = u.pn * BM + wc * 32 + 8 * fq;
; #pragma unroll
;         for (int ai = 0; ai < 2; ++ai)
; #pragma unroll
;             for (int m = 0; m < 4; ++m) { bf16_t* rowp = O + (size_t)u.zo * zsO + (size_t)(row0 + ai * HALF + m * 16) * ldc + col0;
; #pragma unroll
;                 for (int bj = 0; bj < 2; ++bj) { f32x4 v0 = acc[ai][bj][m][0], v1 = acc[ai][bj][m][1];
;                     if (ACT == 2) {
; #pragma unroll
;                         for (int j = 0; j < 4; ++j) { const float a = fmaxf(v0[j], 0.f), b = fmaxf(v1[j], 0.f); v0[j] = a * a; v1[j] = b * b; } }
;                     u32x4 w; w.x = cvt_pk_bf16(v0[0], v0[1]); w.y = cvt_pk_bf16(v0[2], v0[3]); w.z = cvt_pk_bf16(v1[0], v1[1]); w.w = cvt_pk_bf16(v1[2], v1[3]);
;                     *(u32x4*)(rowp + bj * HALF) = w; } }
.LBB0_1705:
	v_lshl_or_b32 v144, s1, 8, v142
	s_ashr_i32 s1, s0, 31
	v_lshl_add_u32 v146, s37, 8, v140
	s_lshl_b64 s[0:1], s[0:1], 22
	v_readlane_b32 s9, v247, 13
	s_add_u32 s0, s9, s0
	v_readlane_b32 s9, v247, 14
	v_ashrrev_i32_e32 v147, 31, v146
	v_cvt_pk_bf16_f32 v110, v110, v111
	v_cvt_pk_bf16_f32 v111, v112, v113
	v_cvt_pk_bf16_f32 v112, v106, v107
	v_or_b32_e32 v106, 16, v146
	v_cvt_pk_bf16_f32 v94, v94, v95
	v_cvt_pk_bf16_f32 v95, v96, v97
	v_cvt_pk_bf16_f32 v96, v90, v91
	v_or_b32_e32 v90, 32, v146
	v_cvt_pk_bf16_f32 v78, v78, v79
	v_cvt_pk_bf16_f32 v79, v80, v81
	v_cvt_pk_bf16_f32 v80, v74, v75
	v_or_b32_e32 v74, 48, v146
	v_ashrrev_i32_e32 v145, 31, v144
	s_addc_u32 s1, s9, s1
	v_lshlrev_b64 v[148:149], 12, v[146:147]
	v_ashrrev_i32_e32 v107, 31, v106
	v_ashrrev_i32_e32 v91, 31, v90
	v_ashrrev_i32_e32 v75, 31, v74
	v_lshl_add_u64 v[148:149], s[0:1], 0, v[148:149]
	v_lshlrev_b64 v[144:145], 1, v[144:145]
	v_lshlrev_b64 v[106:107], 12, v[106:107]
	v_lshlrev_b64 v[90:91], 12, v[90:91]
	v_lshlrev_b64 v[74:75], 12, v[74:75]
	v_lshl_add_u64 v[148:149], v[148:149], 0, v[144:145]
	v_lshl_add_u64 v[106:107], s[0:1], 0, v[106:107]
	v_lshl_add_u64 v[90:91], s[0:1], 0, v[90:91]
	v_lshl_add_u64 v[74:75], s[0:1], 0, v[74:75]
	s_mov_b64 s[0:1], 0x80000
	v_cvt_pk_bf16_f32 v70, v70, v71
	v_cvt_pk_bf16_f32 v71, v72, v73
	v_cvt_pk_bf16_f32 v72, v66, v67
	v_lshl_add_u64 v[66:67], v[148:149], 0, s[0:1]
	s_mov_b32 s0, 0x80000
	v_cvt_pk_bf16_f32 v60, v60, v61
	v_cvt_pk_bf16_f32 v61, v62, v63
	v_cvt_pk_bf16_f32 v62, v56, v57
	v_add_co_u32_e32 v56, vcc, s0, v148
	v_cvt_pk_bf16_f32 v44, v44, v45
	v_cvt_pk_bf16_f32 v45, v46, v47
	v_cvt_pk_bf16_f32 v46, v40, v41
	v_cvt_pk_bf16_f32 v47, v42, v43
	s_mov_b64 s[0:1], 0x90000
	v_addc_co_u32_e32 v57, vcc, 0, v149, vcc
	global_store_dwordx4 v[66:67], v[44:47], off offset:256
	v_cvt_pk_bf16_f32 v28, v28, v29
	v_cvt_pk_bf16_f32 v29, v30, v31
	v_lshl_add_u64 v[44:45], v[148:149], 0, s[0:1]
	s_mov_b32 s0, 0x90000
	v_add_co_u32_e32 v46, vcc, s0, v148
	v_cvt_pk_bf16_f32 v30, v24, v25
	v_cvt_pk_bf16_f32 v31, v26, v27
	s_mov_b64 s[0:1], 0xa0000
	v_addc_co_u32_e32 v47, vcc, 0, v149, vcc
	global_store_dwordx4 v[44:45], v[28:31], off offset:256
	v_cvt_pk_bf16_f32 v12, v12, v13
	v_cvt_pk_bf16_f32 v13, v14, v15
	v_lshl_add_u64 v[28:29], v[148:149], 0, s[0:1]
	s_mov_b32 s0, 0xa0000
	v_add_co_u32_e32 v30, vcc, s0, v148
	v_cvt_pk_bf16_f32 v14, v8, v9
	v_cvt_pk_bf16_f32 v15, v10, v11
	s_mov_b64 s[0:1], 0xb0000
	v_cvt_pk_bf16_f32 v113, v108, v109
	v_addc_co_u32_e32 v31, vcc, 0, v149, vcc
	global_store_dwordx4 v[28:29], v[12:15], off offset:256
	global_store_dwordx4 v[148:149], v[110:113], off offset:256
	v_cvt_pk_bf16_f32 v97, v92, v93
	v_lshl_add_u64 v[12:13], v[148:149], 0, s[0:1]
	s_mov_b32 s0, 0xb0000
	v_lshl_add_u64 v[110:111], v[106:107], 0, v[144:145]
	v_add_co_u32_e32 v14, vcc, s0, v148
	global_store_dwordx4 v[110:111], v[94:97], off offset:256
	v_cvt_pk_bf16_f32 v81, v76, v77
	v_addc_co_u32_e32 v15, vcc, 0, v149, vcc
	v_lshl_add_u64 v[94:95], v[90:91], 0, v[144:145]
	v_cvt_pk_bf16_f32 v126, v126, v127
	v_cvt_pk_bf16_f32 v127, v128, v129
	v_cvt_pk_bf16_f32 v128, v122, v123
	v_cvt_pk_bf16_f32 v129, v124, v125
	v_cvt_pk_bf16_f32 v106, v118, v119
	v_cvt_pk_bf16_f32 v107, v120, v121
	v_cvt_pk_bf16_f32 v108, v114, v115
	v_cvt_pk_bf16_f32 v109, v116, v117
	v_cvt_pk_bf16_f32 v90, v102, v103
	v_cvt_pk_bf16_f32 v91, v104, v105
	v_cvt_pk_bf16_f32 v92, v98, v99
	v_cvt_pk_bf16_f32 v93, v100, v101
	global_store_dwordx4 v[94:95], v[78:81], off offset:256
	v_cvt_pk_bf16_f32 v76, v82, v83
	v_cvt_pk_bf16_f32 v77, v84, v85
	v_lshl_add_u64 v[78:79], v[74:75], 0, v[144:145]
	v_cvt_pk_bf16_f32 v74, v86, v87
	v_cvt_pk_bf16_f32 v75, v88, v89
	v_cvt_pk_bf16_f32 v73, v68, v69
	v_cvt_pk_bf16_f32 v63, v58, v59
	v_cvt_pk_bf16_f32 v40, v52, v53
	v_cvt_pk_bf16_f32 v41, v54, v55
	v_cvt_pk_bf16_f32 v42, v48, v49
	v_cvt_pk_bf16_f32 v43, v50, v51
	v_cvt_pk_bf16_f32 v24, v36, v37
	v_cvt_pk_bf16_f32 v25, v38, v39
	v_cvt_pk_bf16_f32 v26, v32, v33
	v_cvt_pk_bf16_f32 v27, v34, v35
	v_cvt_pk_bf16_f32 v8, v20, v21
	v_cvt_pk_bf16_f32 v9, v22, v23
	v_cvt_pk_bf16_f32 v10, v16, v17
	v_cvt_pk_bf16_f32 v11, v18, v19
	v_cvt_pk_bf16_f32 v4, v4, v5
	v_cvt_pk_bf16_f32 v5, v6, v7
	v_cvt_pk_bf16_f32 v6, v0, v1
	v_cvt_pk_bf16_f32 v7, v2, v3
	s_andn2_b64 vcc, exec, s[2:3]
	s_mov_b64 s[0:1], -1
	global_store_dwordx4 v[148:149], v[126:129], off
	global_store_dwordx4 v[110:111], v[106:109], off
	global_store_dwordx4 v[94:95], v[90:93], off
	global_store_dwordx4 v[78:79], v[74:77], off
	global_store_dwordx4 v[78:79], v[70:73], off offset:256
	global_store_dwordx4 v[56:57], v[60:63], off
	global_store_dwordx4 v[46:47], v[40:43], off
	global_store_dwordx4 v[30:31], v[24:27], off
	global_store_dwordx4 v[14:15], v[8:11], off
	global_store_dwordx4 v[12:13], v[4:7], off offset:256
	v_writelane_b32 v244, 1, 63
	s_cbranch_vccnz .LBB0_1698
	s_andn2_b64 vcc, exec, s[4:5]
	s_cbranch_vccnz .LBB0_1697
	s_barrier
	s_branch .LBB0_1697
